# strategy 8 MFMA-LDS interleave: the B1-only and At(a=1)-only ds_read groups issued in the late MFMA gaps of the preceding compute interval (132 reads moved)
# baseline (speedup 1.0000x reference)
; #define PG8_STAGE(bufoff, gbase) do { _Pragma("unroll") for (int _i = 0; _i < 2; ++_i) \
;         __builtin_amdgcn_global_load_lds((const unsigned*)((const char*)(gbase) + voff[_i]), (LAS unsigned*)(lds + (bufoff) + ldsw + _i * 8192), 16, 0, 0); } while (0)
; #define PG8_LDA(dst, b, h) do { _Pragma("unroll") for (int m = 0; m < 4; ++m) _Pragma("unroll") for (int k = 0; k < 2; ++k) dst[m][k] = *(const LAS bf16x8*)(lds + PG8_SA(b, h) + aoff + m * 2048 + k * 1024); } while (0)
; #define PG8_LDB(dst, b, h) do { _Pragma("unroll") for (int n = 0; n < 2; ++n) _Pragma("unroll") for (int k = 0; k < 2; ++k) dst[n][k] = *(const LAS bf16x8*)(lds + PG8_SB(b, h) + boff + n * 2048 + k * 1024); } while (0)
; #define PG8_MMA(ai, bj, At, Bt) do { __builtin_amdgcn_s_setprio(1); _Pragma("unroll") for (int m = 0; m < 4; ++m) _Pragma("unroll") for (int n = 0; n < 2; ++n) _Pragma("unroll") for (int k = 0; k < 2; ++k) \
;         acc[ai][bj][m][n] = __builtin_amdgcn_mfma_f32_16x16x32_bf16(Bt[n][k], At[m][k], acc[ai][bj][m][n], 0, 0, 0); __builtin_amdgcn_s_setprio(0); } while (0)
; #define PG8_WAIT_V(n) asm volatile("s_waitcnt vmcnt(" #n ")" ::: "memory")
; #define PG8_WAIT_L(n) asm volatile("s_waitcnt lgkmcnt(" #n ")" ::: "memory")
; #define PG8_BAR __builtin_amdgcn_s_barrier()
; #define PG8_SCHED __builtin_amdgcn_sched_barrier(0)
; template <class Epi>
; DI void gemm_phase(LAS unsigned char* lds, const Gemm g, const StaticOrder& S, const Epi& E) {
;     ...
;             const bool last = (t == nt - 2);
;             const char* a1 = cA + (size_t)(t + 1) * kstep;
;             const char* a2 = last ? nA : cA + (size_t)(t + 2) * kstep; const char* b2 = last ? nB : cB + (size_t)(t + 2) * kstep;
;             const char* a3 = a2 + kstep; const char* b3 = b2 + kstep;
;             PG8_LDB(B0, 0, 0); PG8_SCHED; PG8_LDA(At, 0, 0); PG8_STAGE(PG8_SA(1, 1), a1 + hstep);
;             PG8_WAIT_L(8); PG8_BAR; PG8_WAIT_L(0); PG8_MMA(0, 0, At, B0); PG8_BAR; PG8_SCHED;
;             PG8_LDB(B1, 0, 1); PG8_STAGE(PG8_SB(0, 0), b2);
;             PG8_BAR; PG8_WAIT_L(0); PG8_MMA(0, 1, At, B1); PG8_BAR;
;             PG8_LDA(At, 0, 1); PG8_STAGE(PG8_SA(0, 0), a2);
;             PG8_BAR; PG8_WAIT_L(0); PG8_MMA(1, 0, At, B0); PG8_BAR; PG8_SCHED;
;             PG8_STAGE(PG8_SB(0, 1), b2 + hstep);
;             PG8_WAIT_V(6); PG8_BAR; PG8_MMA(1, 1, At, B1); PG8_BAR;
.LBB0_37:
	ds_read_b128 v[138:141], v135
	ds_read_b128 v[142:145], v135 offset:1024
	ds_read_b128 v[146:149], v135 offset:2048
	ds_read_b128 v[150:153], v135 offset:3072
	ds_read_b128 v[186:189], v137
	ds_read_b128 v[190:193], v137 offset:1024
	ds_read_b128 v[194:197], v137 offset:2048
	ds_read_b128 v[198:201], v137 offset:3072
	ds_read_b128 v[202:205], v137 offset:4096
	ds_read_b128 v[206:209], v137 offset:5120
	ds_read_b128 v[210:213], v137 offset:6144
	ds_read_b128 v[214:217], v137 offset:7168
	s_add_u32 s20, s18, 0xfff80080
	s_addc_u32 s21, s19, -1
	s_add_i32 s39, 0, 0x10000
	s_cmp_eq_u32 s38, 28
	s_cselect_b32 s23, s4, s21
	s_cselect_b32 s22, s5, s20
	s_cselect_b32 s21, s9, s37
	s_cselect_b32 s20, s11, s33
	s_add_i32 m0, s28, 0xc000
	s_nop 0
	global_load_lds_dwordx4 v130, s[18:19]
	s_add_i32 m0, s28, 0xe000
	s_nop 0
	global_load_lds_dwordx4 v132, s[18:19]
	s_waitcnt lgkmcnt(8)
	s_setprio 1
	s_barrier
	s_waitcnt lgkmcnt(0)
	v_mfma_f32_16x16x32_bf16 v[124:127], v[138:141], v[186:189], v[124:127]
	v_mfma_f32_16x16x32_bf16 v[120:123], v[146:149], v[186:189], v[120:123]
	v_mfma_f32_16x16x32_bf16 v[108:111], v[138:141], v[194:197], v[108:111]
	v_mfma_f32_16x16x32_bf16 v[104:107], v[146:149], v[194:197], v[104:107]
	v_mfma_f32_16x16x32_bf16 v[92:95], v[138:141], v[202:205], v[92:95]
	v_mfma_f32_16x16x32_bf16 v[88:91], v[146:149], v[202:205], v[88:91]
	v_mfma_f32_16x16x32_bf16 v[76:79], v[138:141], v[210:213], v[76:79]
	v_mfma_f32_16x16x32_bf16 v[72:75], v[146:149], v[210:213], v[72:75]
	v_mfma_f32_16x16x32_bf16 v[124:127], v[142:145], v[190:193], v[124:127]
	v_mfma_f32_16x16x32_bf16 v[120:123], v[150:153], v[190:193], v[120:123]
	ds_read_b128 v[226:229], v135 offset:16384
	v_mfma_f32_16x16x32_bf16 v[108:111], v[142:145], v[198:201], v[108:111]
	ds_read_b128 v[230:233], v135 offset:17408
	v_mfma_f32_16x16x32_bf16 v[104:107], v[150:153], v[198:201], v[104:107]
	ds_read_b128 v[234:237], v135 offset:18432
	v_mfma_f32_16x16x32_bf16 v[92:95], v[142:145], v[206:209], v[92:95]
	ds_read_b128 v[238:241], v135 offset:19456
	v_mfma_f32_16x16x32_bf16 v[88:91], v[150:153], v[206:209], v[88:91]
	v_mfma_f32_16x16x32_bf16 v[76:79], v[142:145], v[214:217], v[76:79]
	s_setprio 0
	v_mfma_f32_16x16x32_bf16 v[72:75], v[150:153], v[214:217], v[72:75]
	s_barrier
	s_add_i32 s42, 0, 0x14000
	s_add_i32 s39, s39, s27
	s_mov_b32 m0, s39
	s_nop 0
	global_load_lds_dwordx4 v158, s[20:21]
	s_add_i32 m0, s39, 0x2000
	s_nop 0
	global_load_lds_dwordx4 v128, s[20:21]
	s_waitcnt lgkmcnt(0)
	s_setprio 1
	s_barrier
	v_mfma_f32_16x16x32_bf16 v[116:119], v[226:229], v[186:189], v[116:119]
	v_mfma_f32_16x16x32_bf16 v[112:115], v[234:237], v[186:189], v[112:115]
	v_mfma_f32_16x16x32_bf16 v[100:103], v[226:229], v[194:197], v[100:103]
	v_mfma_f32_16x16x32_bf16 v[96:99], v[234:237], v[194:197], v[96:99]
	v_mfma_f32_16x16x32_bf16 v[84:87], v[226:229], v[202:205], v[84:87]
	v_mfma_f32_16x16x32_bf16 v[80:83], v[234:237], v[202:205], v[80:83]
	v_mfma_f32_16x16x32_bf16 v[68:71], v[226:229], v[210:213], v[68:71]
	v_mfma_f32_16x16x32_bf16 v[64:67], v[234:237], v[210:213], v[64:67]
	v_mfma_f32_16x16x32_bf16 v[116:119], v[230:233], v[190:193], v[116:119]
	ds_read_b128 v[186:189], v137 offset:16384
	s_mov_b32 m0, s28
	v_mfma_f32_16x16x32_bf16 v[112:115], v[238:241], v[190:193], v[112:115]
	ds_read_b128 v[190:193], v137 offset:17408
	v_mfma_f32_16x16x32_bf16 v[100:103], v[230:233], v[198:201], v[100:103]
	ds_read_b128 v[194:197], v137 offset:18432
	v_mfma_f32_16x16x32_bf16 v[96:99], v[238:241], v[198:201], v[96:99]
	ds_read_b128 v[198:201], v137 offset:19456
	v_mfma_f32_16x16x32_bf16 v[84:87], v[230:233], v[206:209], v[84:87]
	ds_read_b128 v[202:205], v137 offset:20480
	v_mfma_f32_16x16x32_bf16 v[80:83], v[238:241], v[206:209], v[80:83]
	ds_read_b128 v[206:209], v137 offset:21504
	v_mfma_f32_16x16x32_bf16 v[68:71], v[230:233], v[214:217], v[68:71]
	ds_read_b128 v[210:213], v137 offset:22528
	s_setprio 0
	v_mfma_f32_16x16x32_bf16 v[64:67], v[238:241], v[214:217], v[64:67]
	s_barrier
	ds_read_b128 v[214:217], v137 offset:23552
	global_load_lds_dwordx4 v158, s[22:23]
	s_mov_b64 s[100:101], s[22:23]
	s_mov_b32 m0, s29
	s_nop 0
	global_load_lds_dwordx4 v128, s[22:23]
	s_waitcnt lgkmcnt(0)
	s_setprio 1
	s_barrier
	v_mfma_f32_16x16x32_bf16 v[60:63], v[138:141], v[186:189], v[60:63]
	v_mfma_f32_16x16x32_bf16 v[56:59], v[146:149], v[186:189], v[56:59]
	v_mfma_f32_16x16x32_bf16 v[44:47], v[138:141], v[194:197], v[44:47]
	v_mfma_f32_16x16x32_bf16 v[40:43], v[146:149], v[194:197], v[40:43]
	v_mfma_f32_16x16x32_bf16 v[28:31], v[138:141], v[202:205], v[28:31]
	v_mfma_f32_16x16x32_bf16 v[24:27], v[146:149], v[202:205], v[24:27]
	v_mfma_f32_16x16x32_bf16 v[12:15], v[138:141], v[210:213], v[12:15]
	v_mfma_f32_16x16x32_bf16 v[8:11], v[146:149], v[210:213], v[8:11]
	v_mfma_f32_16x16x32_bf16 v[60:63], v[142:145], v[190:193], v[60:63]
	v_mfma_f32_16x16x32_bf16 v[56:59], v[150:153], v[190:193], v[56:59]
	v_mfma_f32_16x16x32_bf16 v[44:47], v[142:145], v[198:201], v[44:47]
	v_mfma_f32_16x16x32_bf16 v[40:43], v[150:153], v[198:201], v[40:43]
	v_mfma_f32_16x16x32_bf16 v[28:31], v[142:145], v[206:209], v[28:31]
	v_mfma_f32_16x16x32_bf16 v[24:27], v[150:153], v[206:209], v[24:27]
	v_mfma_f32_16x16x32_bf16 v[12:15], v[142:145], v[214:217], v[12:15]
	s_setprio 0
	v_mfma_f32_16x16x32_bf16 v[8:11], v[150:153], v[214:217], v[8:11]
	s_barrier
	s_add_u32 s40, s20, 0x80000
	s_addc_u32 s41, s21, 0
	s_add_i32 s39, s42, s27
	s_mov_b32 m0, s39
	s_nop 0
	global_load_lds_dwordx4 v158, s[40:41]
	s_add_i32 m0, s39, 0x2000
	s_nop 0
	global_load_lds_dwordx4 v128, s[40:41]
	s_waitcnt vmcnt(6)
	s_setprio 1
	s_barrier
; #define PG8_STAGE(bufoff, gbase) do { _Pragma("unroll") for (int _i = 0; _i < 2; ++_i) \
;         __builtin_amdgcn_global_load_lds((const unsigned*)((const char*)(gbase) + voff[_i]), (LAS unsigned*)(lds + (bufoff) + ldsw + _i * 8192), 16, 0, 0); } while (0)
; #define PG8_LDA(dst, b, h) do { _Pragma("unroll") for (int m = 0; m < 4; ++m) _Pragma("unroll") for (int k = 0; k < 2; ++k) dst[m][k] = *(const LAS bf16x8*)(lds + PG8_SA(b, h) + aoff + m * 2048 + k * 1024); } while (0)
; #define PG8_LDB(dst, b, h) do { _Pragma("unroll") for (int n = 0; n < 2; ++n) _Pragma("unroll") for (int k = 0; k < 2; ++k) dst[n][k] = *(const LAS bf16x8*)(lds + PG8_SB(b, h) + boff + n * 2048 + k * 1024); } while (0)
; #define PG8_MMA(ai, bj, At, Bt) do { __builtin_amdgcn_s_setprio(1); _Pragma("unroll") for (int m = 0; m < 4; ++m) _Pragma("unroll") for (int n = 0; n < 2; ++n) _Pragma("unroll") for (int k = 0; k < 2; ++k) \
;         acc[ai][bj][m][n] = __builtin_amdgcn_mfma_f32_16x16x32_bf16(Bt[n][k], At[m][k], acc[ai][bj][m][n], 0, 0, 0); __builtin_amdgcn_s_setprio(0); } while (0)
; #define PG8_WAIT_V(n) asm volatile("s_waitcnt vmcnt(" #n ")" ::: "memory")
; #define PG8_WAIT_L(n) asm volatile("s_waitcnt lgkmcnt(" #n ")" ::: "memory")
; #define PG8_BAR __builtin_amdgcn_s_barrier()
; #define PG8_SCHED __builtin_amdgcn_sched_barrier(0)
; template <class Epi>
; DI void gemm_phase(LAS unsigned char* lds, const Gemm g, const StaticOrder& S, const Epi& E) {
;     ...
;             PG8_WAIT_V(6); PG8_BAR; PG8_MMA(1, 1, At, B1); PG8_BAR;
;             PG8_LDB(B0, 1, 0); PG8_SCHED; PG8_LDA(At, 1, 0); PG8_STAGE(PG8_SA(0, 1), a2 + hstep);
;             PG8_WAIT_L(8); PG8_BAR; PG8_WAIT_L(0); PG8_MMA(0, 0, At, B0); PG8_BAR; PG8_SCHED;
;             PG8_LDB(B1, 1, 1); PG8_STAGE(PG8_SB(1, 0), b3);
;             PG8_BAR; PG8_WAIT_L(0); PG8_MMA(0, 1, At, B1); PG8_BAR;
;             PG8_LDA(At, 1, 1); PG8_STAGE(PG8_SA(1, 0), a3);
;             PG8_BAR; PG8_WAIT_L(0); PG8_MMA(1, 0, At, B0); PG8_BAR; PG8_SCHED;
	v_mfma_f32_16x16x32_bf16 v[52:55], v[226:229], v[186:189], v[52:55]
	v_mfma_f32_16x16x32_bf16 v[48:51], v[234:237], v[186:189], v[48:51]
	v_mfma_f32_16x16x32_bf16 v[36:39], v[226:229], v[194:197], v[36:39]
	v_mfma_f32_16x16x32_bf16 v[32:35], v[234:237], v[194:197], v[32:35]
	v_mfma_f32_16x16x32_bf16 v[20:23], v[226:229], v[202:205], v[20:23]
	v_mfma_f32_16x16x32_bf16 v[16:19], v[234:237], v[202:205], v[16:19]
	v_mfma_f32_16x16x32_bf16 v[4:7], v[226:229], v[210:213], v[4:7]
	v_mfma_f32_16x16x32_bf16 v[0:3], v[234:237], v[210:213], v[0:3]
	v_mfma_f32_16x16x32_bf16 v[52:55], v[230:233], v[190:193], v[52:55]
	s_add_i32 s39, 0, 0x18000
	v_mfma_f32_16x16x32_bf16 v[48:51], v[238:241], v[190:193], v[48:51]
	v_mfma_f32_16x16x32_bf16 v[36:39], v[230:233], v[198:201], v[36:39]
	v_mfma_f32_16x16x32_bf16 v[32:35], v[238:241], v[198:201], v[32:35]
	v_mfma_f32_16x16x32_bf16 v[20:23], v[230:233], v[206:209], v[20:23]
	v_mfma_f32_16x16x32_bf16 v[16:19], v[238:241], v[206:209], v[16:19]
	v_mfma_f32_16x16x32_bf16 v[4:7], v[230:233], v[214:217], v[4:7]
	s_setprio 0
	v_mfma_f32_16x16x32_bf16 v[0:3], v[238:241], v[214:217], v[0:3]
	s_barrier
	ds_read_b128 v[138:141], v135 offset:32768
	ds_read_b128 v[142:145], v135 offset:33792
	ds_read_b128 v[146:149], v135 offset:34816
	ds_read_b128 v[150:153], v135 offset:35840
	ds_read_b128 v[186:189], v137 offset:32768
	ds_read_b128 v[190:193], v137 offset:33792
	ds_read_b128 v[194:197], v137 offset:34816
	ds_read_b128 v[198:201], v137 offset:35840
	ds_read_b128 v[202:205], v137 offset:36864
	ds_read_b128 v[206:209], v137 offset:37888
	ds_read_b128 v[210:213], v137 offset:38912
	ds_read_b128 v[214:217], v137 offset:39936
	s_add_u32 s22, s22, 0x80000
	s_addc_u32 s23, s23, 0
	s_mov_b32 m0, s30
	s_nop 0
	global_load_lds_dwordx4 v158, s[22:23]
	s_mov_b32 m0, s31
	s_nop 0
	global_load_lds_dwordx4 v128, s[22:23]
	s_waitcnt lgkmcnt(8)
	s_setprio 1
	s_barrier
	s_waitcnt lgkmcnt(0)
	v_mfma_f32_16x16x32_bf16 v[124:127], v[138:141], v[186:189], v[124:127]
	v_mfma_f32_16x16x32_bf16 v[120:123], v[146:149], v[186:189], v[120:123]
	v_mfma_f32_16x16x32_bf16 v[108:111], v[138:141], v[194:197], v[108:111]
	v_mfma_f32_16x16x32_bf16 v[104:107], v[146:149], v[194:197], v[104:107]
	v_mfma_f32_16x16x32_bf16 v[92:95], v[138:141], v[202:205], v[92:95]
	v_mfma_f32_16x16x32_bf16 v[88:91], v[146:149], v[202:205], v[88:91]
	v_mfma_f32_16x16x32_bf16 v[76:79], v[138:141], v[210:213], v[76:79]
	v_mfma_f32_16x16x32_bf16 v[72:75], v[146:149], v[210:213], v[72:75]
	v_mfma_f32_16x16x32_bf16 v[124:127], v[142:145], v[190:193], v[124:127]
	v_mfma_f32_16x16x32_bf16 v[120:123], v[150:153], v[190:193], v[120:123]
	ds_read_b128 v[226:229], v135 offset:49152
	v_mfma_f32_16x16x32_bf16 v[108:111], v[142:145], v[198:201], v[108:111]
	ds_read_b128 v[230:233], v135 offset:50176
	v_mfma_f32_16x16x32_bf16 v[104:107], v[150:153], v[198:201], v[104:107]
	ds_read_b128 v[234:237], v135 offset:51200
	v_mfma_f32_16x16x32_bf16 v[92:95], v[142:145], v[206:209], v[92:95]
	ds_read_b128 v[238:241], v135 offset:52224
	v_mfma_f32_16x16x32_bf16 v[88:91], v[150:153], v[206:209], v[88:91]
	v_mfma_f32_16x16x32_bf16 v[76:79], v[142:145], v[214:217], v[76:79]
	s_setprio 0
	v_mfma_f32_16x16x32_bf16 v[72:75], v[150:153], v[214:217], v[72:75]
	s_barrier
	s_add_i32 s22, 0, 0x1c000
	s_add_i32 s23, s39, s27
	s_add_i32 m0, s23, 0xffffff80
	s_nop 0
	global_load_lds_dwordx4 v158, s[20:21] offset:128
	s_add_i32 m0, s23, 0x1f80
	s_nop 0
	global_load_lds_dwordx4 v128, s[20:21] offset:128
	s_waitcnt lgkmcnt(0)
	s_setprio 1
	s_barrier
	v_mfma_f32_16x16x32_bf16 v[116:119], v[226:229], v[186:189], v[116:119]
	v_mfma_f32_16x16x32_bf16 v[112:115], v[234:237], v[186:189], v[112:115]
	v_mfma_f32_16x16x32_bf16 v[100:103], v[226:229], v[194:197], v[100:103]
	v_mfma_f32_16x16x32_bf16 v[96:99], v[234:237], v[194:197], v[96:99]
	v_mfma_f32_16x16x32_bf16 v[84:87], v[226:229], v[202:205], v[84:87]
	v_mfma_f32_16x16x32_bf16 v[80:83], v[234:237], v[202:205], v[80:83]
	v_mfma_f32_16x16x32_bf16 v[68:71], v[226:229], v[210:213], v[68:71]
	v_mfma_f32_16x16x32_bf16 v[64:67], v[234:237], v[210:213], v[64:67]
	v_mfma_f32_16x16x32_bf16 v[116:119], v[230:233], v[190:193], v[116:119]
	ds_read_b128 v[186:189], v137 offset:49152
	s_add_i32 m0, s34, 0xffffff80
	v_mfma_f32_16x16x32_bf16 v[112:115], v[238:241], v[190:193], v[112:115]
	ds_read_b128 v[190:193], v137 offset:50176
	v_mfma_f32_16x16x32_bf16 v[100:103], v[230:233], v[198:201], v[100:103]
	ds_read_b128 v[194:197], v137 offset:51200
	v_mfma_f32_16x16x32_bf16 v[96:99], v[238:241], v[198:201], v[96:99]
	ds_read_b128 v[198:201], v137 offset:52224
	v_mfma_f32_16x16x32_bf16 v[84:87], v[230:233], v[206:209], v[84:87]
	ds_read_b128 v[202:205], v137 offset:53248
	v_mfma_f32_16x16x32_bf16 v[80:83], v[238:241], v[206:209], v[80:83]
	ds_read_b128 v[206:209], v137 offset:54272
	v_mfma_f32_16x16x32_bf16 v[68:71], v[230:233], v[214:217], v[68:71]
	ds_read_b128 v[210:213], v137 offset:55296
	s_setprio 0
	v_mfma_f32_16x16x32_bf16 v[64:67], v[238:241], v[214:217], v[64:67]
	s_barrier
	ds_read_b128 v[214:217], v137 offset:56320
	global_load_lds_dwordx4 v158, s[100:101] offset:128
	s_add_i32 m0, s35, 0xffffff80
	s_nop 0
	global_load_lds_dwordx4 v128, s[100:101] offset:128
	s_waitcnt lgkmcnt(0)
	s_setprio 1
	s_barrier
; #define PG8_STAGE(bufoff, gbase) do { _Pragma("unroll") for (int _i = 0; _i < 2; ++_i) \
;         __builtin_amdgcn_global_load_lds((const unsigned*)((const char*)(gbase) + voff[_i]), (LAS unsigned*)(lds + (bufoff) + ldsw + _i * 8192), 16, 0, 0); } while (0)
; #define PG8_MMA(ai, bj, At, Bt) do { __builtin_amdgcn_s_setprio(1); _Pragma("unroll") for (int m = 0; m < 4; ++m) _Pragma("unroll") for (int n = 0; n < 2; ++n) _Pragma("unroll") for (int k = 0; k < 2; ++k) \
;         acc[ai][bj][m][n] = __builtin_amdgcn_mfma_f32_16x16x32_bf16(Bt[n][k], At[m][k], acc[ai][bj][m][n], 0, 0, 0); __builtin_amdgcn_s_setprio(0); } while (0)
; #define PG8_WAIT_V(n) asm volatile("s_waitcnt vmcnt(" #n ")" ::: "memory")
; #define PG8_WAIT_L(n) asm volatile("s_waitcnt lgkmcnt(" #n ")" ::: "memory")
; #define PG8_BAR __builtin_amdgcn_s_barrier()
; #define PG8_SCHED __builtin_amdgcn_sched_barrier(0)
; template <class Epi>
; DI void gemm_phase(LAS unsigned char* lds, const Gemm g, const StaticOrder& S, const Epi& E) {
;     ...
;             PG8_BAR; PG8_WAIT_L(0); PG8_MMA(1, 0, At, B0); PG8_BAR; PG8_SCHED;
;             PG8_STAGE(PG8_SB(1, 1), b3 + hstep);
;             PG8_WAIT_V(6); PG8_BAR; PG8_MMA(1, 1, At, B1); PG8_BAR;
;         }
;         E(acc, cur, wr, wc, fr, fq);
;     DI void operator()(const f32x4 (&acc)[2][2][4][2], const Unit& u, int wr, int wc, int fr, int fq) const {
;         const int row0 = u.pm * BM + wr * 64 + fr, col0 = u.pn * HALF + wc * 32 + 8 * fq;
; #pragma unroll
;         for (int ai = 0; ai < 2; ++ai)
; #pragma unroll
;             for (int m = 0; m < 4; ++m) { float hv[8];
; #pragma unroll
;                 for (int n = 0; n < 2; ++n)
; #pragma unroll
;                     for (int e = 0; e < 4; ++e) { const float gt = acc[ai][0][m][n][e], up = acc[ai][1][m][n][e];
;                         hv[n * 4 + e] = gt * __builtin_amdgcn_rcpf(1.f + __builtin_amdgcn_exp2f(-1.4426950408889634f * gt)) * up; }
;                 *(u32x4*)(H + (size_t)(row0 + ai * HALF + m * 16) * DFF + col0) = (u32x4){pk(hv[0], hv[1]), pk(hv[2], hv[3]), pk(hv[4], hv[5]), pk(hv[6], hv[7])}; }
	v_mfma_f32_16x16x32_bf16 v[60:63], v[138:141], v[186:189], v[60:63]
	v_mfma_f32_16x16x32_bf16 v[56:59], v[146:149], v[186:189], v[56:59]
	v_mfma_f32_16x16x32_bf16 v[44:47], v[138:141], v[194:197], v[44:47]
	v_mfma_f32_16x16x32_bf16 v[40:43], v[146:149], v[194:197], v[40:43]
	v_mfma_f32_16x16x32_bf16 v[28:31], v[138:141], v[202:205], v[28:31]
	v_mfma_f32_16x16x32_bf16 v[24:27], v[146:149], v[202:205], v[24:27]
	v_mfma_f32_16x16x32_bf16 v[12:15], v[138:141], v[210:213], v[12:15]
	v_mfma_f32_16x16x32_bf16 v[8:11], v[146:149], v[210:213], v[8:11]
	v_mfma_f32_16x16x32_bf16 v[60:63], v[142:145], v[190:193], v[60:63]
	v_mfma_f32_16x16x32_bf16 v[56:59], v[150:153], v[190:193], v[56:59]
	v_mfma_f32_16x16x32_bf16 v[44:47], v[142:145], v[198:201], v[44:47]
	v_mfma_f32_16x16x32_bf16 v[40:43], v[150:153], v[198:201], v[40:43]
	v_mfma_f32_16x16x32_bf16 v[28:31], v[142:145], v[206:209], v[28:31]
	v_mfma_f32_16x16x32_bf16 v[24:27], v[150:153], v[206:209], v[24:27]
	v_mfma_f32_16x16x32_bf16 v[12:15], v[142:145], v[214:217], v[12:15]
	s_setprio 0
	v_mfma_f32_16x16x32_bf16 v[8:11], v[150:153], v[214:217], v[8:11]
	s_barrier
	s_add_u32 s20, s20, 0x80080
	s_addc_u32 s21, s21, 0
	s_add_i32 s22, s22, s27
	s_mov_b32 m0, s22
	s_nop 0
	global_load_lds_dwordx4 v158, s[20:21]
	s_add_i32 m0, s22, 0x2000
	s_nop 0
	global_load_lds_dwordx4 v128, s[20:21]
	s_waitcnt vmcnt(6)
	s_setprio 1
	s_barrier
	v_mfma_f32_16x16x32_bf16 v[52:55], v[226:229], v[186:189], v[52:55]
	v_mfma_f32_16x16x32_bf16 v[48:51], v[234:237], v[186:189], v[48:51]
	v_mfma_f32_16x16x32_bf16 v[36:39], v[226:229], v[194:197], v[36:39]
	v_mfma_f32_16x16x32_bf16 v[32:35], v[234:237], v[194:197], v[32:35]
	v_mfma_f32_16x16x32_bf16 v[20:23], v[226:229], v[202:205], v[20:23]
	v_mfma_f32_16x16x32_bf16 v[16:19], v[234:237], v[202:205], v[16:19]
	v_mfma_f32_16x16x32_bf16 v[4:7], v[226:229], v[210:213], v[4:7]
	v_mfma_f32_16x16x32_bf16 v[0:3], v[234:237], v[210:213], v[0:3]
	v_mfma_f32_16x16x32_bf16 v[52:55], v[230:233], v[190:193], v[52:55]
	s_add_i32 s38, s38, 2
	v_mfma_f32_16x16x32_bf16 v[48:51], v[238:241], v[190:193], v[48:51]
	s_add_u32 s18, s18, 0x100
	v_mfma_f32_16x16x32_bf16 v[36:39], v[230:233], v[198:201], v[36:39]
	s_addc_u32 s19, s19, 0
	v_mfma_f32_16x16x32_bf16 v[32:35], v[238:241], v[198:201], v[32:35]
	s_add_u32 s33, s33, 0x100
	v_mfma_f32_16x16x32_bf16 v[20:23], v[230:233], v[206:209], v[20:23]
	s_addc_u32 s37, s37, 0
	v_mfma_f32_16x16x32_bf16 v[16:19], v[238:241], v[206:209], v[16:19]
	s_cmp_gt_u32 s38, 29
	v_mfma_f32_16x16x32_bf16 v[4:7], v[230:233], v[214:217], v[4:7]
	s_setprio 0
	v_mfma_f32_16x16x32_bf16 v[0:3], v[238:241], v[214:217], v[0:3]
	s_barrier
	s_cbranch_scc0 .LBB0_37
	v_mul_f32_e32 v139, 0xbfb8aa3b, v124
	v_exp_f32_e32 v139, v139
	v_lshl_or_b32 v140, s2, 7, v136
	v_lshl_add_u32 v138, s3, 8, v134
	v_ashrrev_i32_e32 v141, 31, v140
	v_add_f32_e32 v139, 1.0, v139
	v_rcp_f32_e32 v142, v139
	v_mul_f32_e32 v139, 0xbfb8aa3b, v125
	v_exp_f32_e32 v139, v139
	s_movk_i32 s4, 0x2c00
	s_and_b64 vcc, exec, s[6:7]
	s_mov_b64 s[20:21], s[16:17]
	v_add_f32_e32 v139, 1.0, v139
	v_rcp_f32_e32 v143, v139
	v_mul_f32_e32 v139, 0xbfb8aa3b, v126
	v_exp_f32_e32 v139, v139
	s_mov_b64 s[18:19], s[14:15]
	v_pk_mul_f32 v[124:125], v[124:125], v[142:143]
	v_add_f32_e32 v139, 1.0, v139
	v_rcp_f32_e32 v144, v139
	v_mul_f32_e32 v139, 0xbfb8aa3b, v127
	v_exp_f32_e32 v139, v139
	v_pk_mul_f32 v[116:117], v[124:125], v[116:117]
	v_add_f32_e32 v139, 1.0, v139
	v_rcp_f32_e32 v145, v139
	v_mul_f32_e32 v139, 0xbfb8aa3b, v120
	v_exp_f32_e32 v139, v139
	v_cvt_pk_bf16_f32 v116, v116, v117
	v_pk_mul_f32 v[124:125], v[126:127], v[144:145]
	v_add_f32_e32 v139, 1.0, v139
	v_rcp_f32_e32 v146, v139
	v_mul_f32_e32 v139, 0xbfb8aa3b, v121
	v_exp_f32_e32 v139, v139
	v_pk_mul_f32 v[118:119], v[124:125], v[118:119]
	v_add_f32_e32 v139, 1.0, v139
	v_rcp_f32_e32 v147, v139
	v_mul_f32_e32 v139, 0xbfb8aa3b, v122
	v_exp_f32_e32 v139, v139
	v_cvt_pk_bf16_f32 v117, v118, v119
	v_pk_mul_f32 v[118:119], v[120:121], v[146:147]
	v_add_f32_e32 v139, 1.0, v139
	v_rcp_f32_e32 v148, v139
	v_mul_f32_e32 v139, 0xbfb8aa3b, v123
	v_exp_f32_e32 v139, v139
	v_pk_mul_f32 v[112:113], v[118:119], v[112:113]
	v_add_f32_e32 v139, 1.0, v139
	v_rcp_f32_e32 v149, v139
	v_cvt_pk_bf16_f32 v118, v112, v113
	v_pk_mul_f32 v[112:113], v[122:123], v[148:149]
	s_nop 0
	v_pk_mul_f32 v[112:113], v[112:113], v[114:115]
	v_lshlrev_b64 v[114:115], 1, v[140:141]
	v_cvt_pk_bf16_f32 v119, v112, v113
	v_mov_b64_e32 v[112:113], s[54:55]
	v_mad_i64_i32 v[120:121], s[2:3], v138, s4, v[112:113]
	v_lshl_add_u64 v[120:121], v[120:121], 0, v[114:115]
	global_store_dwordx4 v[120:121], v[116:119], off
	v_mul_f32_e32 v120, 0xbfb8aa3b, v104
	v_mul_f32_e32 v121, 0xbfb8aa3b, v105
	v_mul_f32_e32 v116, 0xbfb8aa3b, v108
	v_mul_f32_e32 v117, 0xbfb8aa3b, v109
	v_exp_f32_e32 v116, v116
	v_exp_f32_e32 v117, v117
	v_mul_f32_e32 v118, 0xbfb8aa3b, v110
	v_mul_f32_e32 v119, 0xbfb8aa3b, v111
	v_exp_f32_e32 v118, v118
	v_exp_f32_e32 v119, v119
	v_exp_f32_e32 v120, v120
	v_exp_f32_e32 v121, v121
	v_add_f32_e32 v116, 1.0, v116
	v_add_f32_e32 v117, 1.0, v117
	v_mul_f32_e32 v122, 0xbfb8aa3b, v106
	v_mul_f32_e32 v123, 0xbfb8aa3b, v107
	v_rcp_f32_e32 v116, v116
	v_rcp_f32_e32 v117, v117
	v_add_f32_e32 v118, 1.0, v118
	v_add_f32_e32 v119, 1.0, v119
	v_exp_f32_e32 v122, v122
	v_exp_f32_e32 v123, v123
	v_rcp_f32_e32 v118, v118
	v_rcp_f32_e32 v119, v119
	v_add_f32_e32 v120, 1.0, v120
	v_add_f32_e32 v121, 1.0, v121
	v_rcp_f32_e32 v120, v120
	v_rcp_f32_e32 v121, v121
	v_add_f32_e32 v122, 1.0, v122
	v_add_f32_e32 v123, 1.0, v123
	v_pk_mul_f32 v[108:109], v[108:109], v[116:117]
	v_rcp_f32_e32 v122, v122
;     DI void operator()(const f32x4 (&acc)[2][2][4][2], const Unit& u, int wr, int wc, int fr, int fq) const {
;     ...
;         for (int ai = 0; ai < 2; ++ai)
; #pragma unroll
;             for (int m = 0; m < 4; ++m) { float hv[8];
; #pragma unroll
;                 for (int n = 0; n < 2; ++n)
; #pragma unroll
;                     for (int e = 0; e < 4; ++e) { const float gt = acc[ai][0][m][n][e], up = acc[ai][1][m][n][e];
;                         hv[n * 4 + e] = gt * __builtin_amdgcn_rcpf(1.f + __builtin_amdgcn_exp2f(-1.4426950408889634f * gt)) * up; }
;                 *(u32x4*)(H + (size_t)(row0 + ai * HALF + m * 16) * DFF + col0) = (u32x4){pk(hv[0], hv[1]), pk(hv[2], hv[3]), pk(hv[4], hv[5]), pk(hv[6], hv[7])}; }
	v_rcp_f32_e32 v123, v123
	v_pk_mul_f32 v[100:101], v[108:109], v[100:101]
	v_pk_mul_f32 v[108:109], v[110:111], v[118:119]
	v_cvt_pk_bf16_f32 v100, v100, v101
	v_pk_mul_f32 v[102:103], v[108:109], v[102:103]
	s_nop 0
	v_cvt_pk_bf16_f32 v101, v102, v103
	v_pk_mul_f32 v[102:103], v[104:105], v[120:121]
	s_nop 0
	v_pk_mul_f32 v[96:97], v[102:103], v[96:97]
	s_nop 0
	v_cvt_pk_bf16_f32 v102, v96, v97
	v_pk_mul_f32 v[96:97], v[106:107], v[122:123]
	s_nop 0
	v_pk_mul_f32 v[96:97], v[96:97], v[98:99]
	v_mul_f32_e32 v98, 0xbfb8aa3b, v94
	v_cvt_pk_bf16_f32 v103, v96, v97
	v_or_b32_e32 v96, 16, v138
	v_mad_i64_i32 v[96:97], s[2:3], v96, s4, v[112:113]
	v_lshl_add_u64 v[96:97], v[96:97], 0, v[114:115]
	global_store_dwordx4 v[96:97], v[100:103], off
	v_mul_f32_e32 v96, 0xbfb8aa3b, v92
	v_mul_f32_e32 v97, 0xbfb8aa3b, v93
	v_exp_f32_e32 v96, v96
	v_exp_f32_e32 v97, v97
	v_mul_f32_e32 v99, 0xbfb8aa3b, v95
	v_exp_f32_e32 v98, v98
	v_exp_f32_e32 v99, v99
	v_mul_f32_e32 v100, 0xbfb8aa3b, v88
	v_mul_f32_e32 v101, 0xbfb8aa3b, v89
	v_exp_f32_e32 v100, v100
	v_exp_f32_e32 v101, v101
	v_add_f32_e32 v96, 1.0, v96
	v_add_f32_e32 v97, 1.0, v97
	v_mul_f32_e32 v102, 0xbfb8aa3b, v90
	v_mul_f32_e32 v103, 0xbfb8aa3b, v91
	v_rcp_f32_e32 v96, v96
	v_rcp_f32_e32 v97, v97
	v_add_f32_e32 v98, 1.0, v98
	v_add_f32_e32 v99, 1.0, v99
	v_exp_f32_e32 v102, v102
	v_exp_f32_e32 v103, v103
	v_rcp_f32_e32 v98, v98
	v_rcp_f32_e32 v99, v99
	v_add_f32_e32 v100, 1.0, v100
	v_add_f32_e32 v101, 1.0, v101
	v_rcp_f32_e32 v100, v100
	v_rcp_f32_e32 v101, v101
	v_add_f32_e32 v102, 1.0, v102
	v_add_f32_e32 v103, 1.0, v103
	v_pk_mul_f32 v[92:93], v[92:93], v[96:97]
	v_rcp_f32_e32 v102, v102
	v_rcp_f32_e32 v103, v103
	v_pk_mul_f32 v[84:85], v[92:93], v[84:85]
	v_pk_mul_f32 v[92:93], v[94:95], v[98:99]
	v_cvt_pk_bf16_f32 v84, v84, v85
	v_pk_mul_f32 v[86:87], v[92:93], v[86:87]
	s_nop 0
	v_cvt_pk_bf16_f32 v85, v86, v87
	v_pk_mul_f32 v[86:87], v[88:89], v[100:101]
	s_nop 0
	v_pk_mul_f32 v[80:81], v[86:87], v[80:81]
	s_nop 0
	v_cvt_pk_bf16_f32 v86, v80, v81
	v_pk_mul_f32 v[80:81], v[90:91], v[102:103]
	s_nop 0
	v_pk_mul_f32 v[80:81], v[80:81], v[82:83]
	v_mul_f32_e32 v82, 0xbfb8aa3b, v78
	v_cvt_pk_bf16_f32 v87, v80, v81
	v_or_b32_e32 v80, 32, v138
	v_mad_i64_i32 v[80:81], s[2:3], v80, s4, v[112:113]
	v_lshl_add_u64 v[80:81], v[80:81], 0, v[114:115]
	global_store_dwordx4 v[80:81], v[84:87], off
	v_mul_f32_e32 v80, 0xbfb8aa3b, v76
	v_mul_f32_e32 v81, 0xbfb8aa3b, v77
	v_exp_f32_e32 v80, v80
	v_exp_f32_e32 v81, v81
	v_mul_f32_e32 v83, 0xbfb8aa3b, v79
	v_exp_f32_e32 v82, v82
	v_exp_f32_e32 v83, v83
	v_mul_f32_e32 v84, 0xbfb8aa3b, v72
	v_mul_f32_e32 v85, 0xbfb8aa3b, v73
	v_exp_f32_e32 v84, v84
	v_exp_f32_e32 v85, v85
	v_add_f32_e32 v80, 1.0, v80
	v_add_f32_e32 v81, 1.0, v81
	v_mul_f32_e32 v86, 0xbfb8aa3b, v74
	v_mul_f32_e32 v87, 0xbfb8aa3b, v75
	v_rcp_f32_e32 v80, v80
	v_rcp_f32_e32 v81, v81
	v_add_f32_e32 v82, 1.0, v82
	v_add_f32_e32 v83, 1.0, v83
	v_exp_f32_e32 v86, v86
	v_exp_f32_e32 v87, v87
	v_rcp_f32_e32 v82, v82
	v_rcp_f32_e32 v83, v83
	v_add_f32_e32 v84, 1.0, v84
	v_add_f32_e32 v85, 1.0, v85
	v_rcp_f32_e32 v84, v84
	v_rcp_f32_e32 v85, v85
	v_add_f32_e32 v86, 1.0, v86
	v_add_f32_e32 v87, 1.0, v87
	v_pk_mul_f32 v[76:77], v[76:77], v[80:81]
	v_rcp_f32_e32 v86, v86
	v_rcp_f32_e32 v87, v87
	v_pk_mul_f32 v[68:69], v[76:77], v[68:69]
	v_pk_mul_f32 v[76:77], v[78:79], v[82:83]
	v_cvt_pk_bf16_f32 v68, v68, v69
	v_pk_mul_f32 v[70:71], v[76:77], v[70:71]
	s_nop 0
	v_cvt_pk_bf16_f32 v69, v70, v71
	v_pk_mul_f32 v[70:71], v[72:73], v[84:85]
	v_add_u32_e32 v72, 0x80, v138
	v_pk_mul_f32 v[64:65], v[70:71], v[64:65]
	s_nop 0
	v_cvt_pk_bf16_f32 v70, v64, v65
	v_pk_mul_f32 v[64:65], v[74:75], v[86:87]
	s_nop 0
	v_pk_mul_f32 v[64:65], v[64:65], v[66:67]
	v_mul_f32_e32 v66, 0xbfb8aa3b, v62
	v_cvt_pk_bf16_f32 v71, v64, v65
	v_or_b32_e32 v64, 48, v138
	v_mad_i64_i32 v[64:65], s[2:3], v64, s4, v[112:113]
	v_lshl_add_u64 v[64:65], v[64:65], 0, v[114:115]
	global_store_dwordx4 v[64:65], v[68:71], off
	v_mul_f32_e32 v64, 0xbfb8aa3b, v60
	v_mul_f32_e32 v65, 0xbfb8aa3b, v61
	v_exp_f32_e32 v64, v64
	v_exp_f32_e32 v65, v65
	v_mul_f32_e32 v67, 0xbfb8aa3b, v63
	v_exp_f32_e32 v66, v66
	v_exp_f32_e32 v67, v67
	v_mul_f32_e32 v68, 0xbfb8aa3b, v56
	v_mul_f32_e32 v69, 0xbfb8aa3b, v57
	v_exp_f32_e32 v68, v68
	v_exp_f32_e32 v69, v69
	v_add_f32_e32 v64, 1.0, v64
	v_add_f32_e32 v65, 1.0, v65
	v_mul_f32_e32 v70, 0xbfb8aa3b, v58
	v_mul_f32_e32 v71, 0xbfb8aa3b, v59
	v_rcp_f32_e32 v64, v64
	v_rcp_f32_e32 v65, v65
	v_add_f32_e32 v66, 1.0, v66
	v_add_f32_e32 v67, 1.0, v67
	v_exp_f32_e32 v70, v70
	v_exp_f32_e32 v71, v71
	v_rcp_f32_e32 v66, v66
	v_rcp_f32_e32 v67, v67
	v_add_f32_e32 v68, 1.0, v68
	v_add_f32_e32 v69, 1.0, v69
	v_rcp_f32_e32 v68, v68
	v_rcp_f32_e32 v69, v69
	v_add_f32_e32 v70, 1.0, v70
	v_add_f32_e32 v71, 1.0, v71
	v_pk_mul_f32 v[60:61], v[60:61], v[64:65]
	v_rcp_f32_e32 v70, v70
	v_rcp_f32_e32 v71, v71
	v_pk_mul_f32 v[52:53], v[60:61], v[52:53]
	v_pk_mul_f32 v[60:61], v[62:63], v[66:67]
	v_cvt_pk_bf16_f32 v52, v52, v53
	v_pk_mul_f32 v[54:55], v[60:61], v[54:55]
	s_nop 0
	v_cvt_pk_bf16_f32 v53, v54, v55
	v_pk_mul_f32 v[54:55], v[56:57], v[68:69]
	s_nop 0
	v_pk_mul_f32 v[48:49], v[54:55], v[48:49]
; #define PG8_WAIT_V(n) asm volatile("s_waitcnt vmcnt(" #n ")" ::: "memory")
; #define PG8_BAR __builtin_amdgcn_s_barrier()
; template <class Epi>
; DI void gemm_phase(LAS unsigned char* lds, const Gemm g, const StaticOrder& S, const Epi& E) {
;     ...
;     PG8_WAIT_V(0);
;     if (wr == 0) PG8_BAR;
;     PG8_BAR;
;     DI void operator()(const f32x4 (&acc)[2][2][4][2], const Unit& u, int wr, int wc, int fr, int fq) const {
;     ...
;         for (int ai = 0; ai < 2; ++ai)
; #pragma unroll
;             for (int m = 0; m < 4; ++m) { float hv[8];
; #pragma unroll
;                 for (int n = 0; n < 2; ++n)
; #pragma unroll
;                     for (int e = 0; e < 4; ++e) { const float gt = acc[ai][0][m][n][e], up = acc[ai][1][m][n][e];
;                         hv[n * 4 + e] = gt * __builtin_amdgcn_rcpf(1.f + __builtin_amdgcn_exp2f(-1.4426950408889634f * gt)) * up; }
;                 *(u32x4*)(H + (size_t)(row0 + ai * HALF + m * 16) * DFF + col0) = (u32x4){pk(hv[0], hv[1]), pk(hv[2], hv[3]), pk(hv[4], hv[5]), pk(hv[6], hv[7])}; }
	s_nop 0
	v_cvt_pk_bf16_f32 v54, v48, v49
	v_pk_mul_f32 v[48:49], v[58:59], v[70:71]
	s_nop 0
	v_pk_mul_f32 v[48:49], v[48:49], v[50:51]
	v_mul_f32_e32 v50, 0xbfb8aa3b, v46
	v_cvt_pk_bf16_f32 v55, v48, v49
	v_mad_i64_i32 v[48:49], s[2:3], v72, s4, v[112:113]
	v_lshl_add_u64 v[48:49], v[48:49], 0, v[114:115]
	global_store_dwordx4 v[48:49], v[52:55], off
	v_mul_f32_e32 v48, 0xbfb8aa3b, v44
	v_mul_f32_e32 v49, 0xbfb8aa3b, v45
	v_exp_f32_e32 v48, v48
	v_exp_f32_e32 v49, v49
	v_mul_f32_e32 v51, 0xbfb8aa3b, v47
	v_exp_f32_e32 v50, v50
	v_exp_f32_e32 v51, v51
	v_mul_f32_e32 v52, 0xbfb8aa3b, v40
	v_mul_f32_e32 v53, 0xbfb8aa3b, v41
	v_exp_f32_e32 v52, v52
	v_exp_f32_e32 v53, v53
	v_add_f32_e32 v48, 1.0, v48
	v_add_f32_e32 v49, 1.0, v49
	v_mul_f32_e32 v54, 0xbfb8aa3b, v42
	v_mul_f32_e32 v55, 0xbfb8aa3b, v43
	v_rcp_f32_e32 v48, v48
	v_rcp_f32_e32 v49, v49
	v_add_f32_e32 v50, 1.0, v50
	v_add_f32_e32 v51, 1.0, v51
	v_exp_f32_e32 v54, v54
	v_exp_f32_e32 v55, v55
	v_rcp_f32_e32 v50, v50
	v_rcp_f32_e32 v51, v51
	v_add_f32_e32 v52, 1.0, v52
	v_add_f32_e32 v53, 1.0, v53
	v_rcp_f32_e32 v52, v52
	v_rcp_f32_e32 v53, v53
	v_add_f32_e32 v54, 1.0, v54
	v_add_f32_e32 v55, 1.0, v55
	v_pk_mul_f32 v[44:45], v[44:45], v[48:49]
	v_rcp_f32_e32 v54, v54
	v_rcp_f32_e32 v55, v55
	v_pk_mul_f32 v[36:37], v[44:45], v[36:37]
	v_pk_mul_f32 v[44:45], v[46:47], v[50:51]
	v_cvt_pk_bf16_f32 v36, v36, v37
	v_pk_mul_f32 v[38:39], v[44:45], v[38:39]
	s_nop 0
	v_cvt_pk_bf16_f32 v37, v38, v39
	v_pk_mul_f32 v[38:39], v[40:41], v[52:53]
	s_nop 0
	v_pk_mul_f32 v[32:33], v[38:39], v[32:33]
	s_nop 0
	v_cvt_pk_bf16_f32 v38, v32, v33
	v_pk_mul_f32 v[32:33], v[42:43], v[54:55]
	s_nop 0
	v_pk_mul_f32 v[32:33], v[32:33], v[34:35]
	v_mul_f32_e32 v34, 0xbfb8aa3b, v30
	v_cvt_pk_bf16_f32 v39, v32, v33
	v_add_u32_e32 v32, 0x90, v138
	v_mad_i64_i32 v[32:33], s[2:3], v32, s4, v[112:113]
	v_lshl_add_u64 v[32:33], v[32:33], 0, v[114:115]
	global_store_dwordx4 v[32:33], v[36:39], off
	v_mul_f32_e32 v32, 0xbfb8aa3b, v28
	v_mul_f32_e32 v33, 0xbfb8aa3b, v29
	v_exp_f32_e32 v32, v32
	v_exp_f32_e32 v33, v33
	v_mul_f32_e32 v35, 0xbfb8aa3b, v31
	v_exp_f32_e32 v34, v34
	v_exp_f32_e32 v35, v35
	v_mul_f32_e32 v36, 0xbfb8aa3b, v24
	v_mul_f32_e32 v37, 0xbfb8aa3b, v25
	v_exp_f32_e32 v36, v36
	v_exp_f32_e32 v37, v37
	v_add_f32_e32 v32, 1.0, v32
	v_add_f32_e32 v33, 1.0, v33
	v_mul_f32_e32 v38, 0xbfb8aa3b, v26
	v_mul_f32_e32 v39, 0xbfb8aa3b, v27
	v_rcp_f32_e32 v32, v32
	v_rcp_f32_e32 v33, v33
	v_add_f32_e32 v34, 1.0, v34
	v_add_f32_e32 v35, 1.0, v35
	v_exp_f32_e32 v38, v38
	v_exp_f32_e32 v39, v39
	v_rcp_f32_e32 v34, v34
	v_rcp_f32_e32 v35, v35
	v_add_f32_e32 v36, 1.0, v36
	v_add_f32_e32 v37, 1.0, v37
	v_rcp_f32_e32 v36, v36
	v_rcp_f32_e32 v37, v37
	v_add_f32_e32 v38, 1.0, v38
	v_add_f32_e32 v39, 1.0, v39
	v_pk_mul_f32 v[28:29], v[28:29], v[32:33]
	v_rcp_f32_e32 v38, v38
	v_rcp_f32_e32 v39, v39
	v_pk_mul_f32 v[20:21], v[28:29], v[20:21]
	v_pk_mul_f32 v[28:29], v[30:31], v[34:35]
	v_cvt_pk_bf16_f32 v20, v20, v21
	v_pk_mul_f32 v[22:23], v[28:29], v[22:23]
	s_nop 0
	v_cvt_pk_bf16_f32 v21, v22, v23
	v_pk_mul_f32 v[22:23], v[24:25], v[36:37]
	s_nop 0
	v_pk_mul_f32 v[16:17], v[22:23], v[16:17]
	s_nop 0
	v_cvt_pk_bf16_f32 v22, v16, v17
	v_pk_mul_f32 v[16:17], v[26:27], v[38:39]
	s_nop 0
	v_pk_mul_f32 v[16:17], v[16:17], v[18:19]
	v_mul_f32_e32 v18, 0xbfb8aa3b, v14
	v_cvt_pk_bf16_f32 v23, v16, v17
	v_add_u32_e32 v16, 0xa0, v138
	v_mad_i64_i32 v[16:17], s[2:3], v16, s4, v[112:113]
	v_lshl_add_u64 v[16:17], v[16:17], 0, v[114:115]
	global_store_dwordx4 v[16:17], v[20:23], off
	v_mul_f32_e32 v16, 0xbfb8aa3b, v12
	v_mul_f32_e32 v17, 0xbfb8aa3b, v13
	v_exp_f32_e32 v16, v16
	v_exp_f32_e32 v17, v17
	v_mul_f32_e32 v19, 0xbfb8aa3b, v15
	v_exp_f32_e32 v18, v18
	v_exp_f32_e32 v19, v19
	v_mul_f32_e32 v20, 0xbfb8aa3b, v8
	v_mul_f32_e32 v21, 0xbfb8aa3b, v9
	v_exp_f32_e32 v20, v20
	v_exp_f32_e32 v21, v21
	v_add_f32_e32 v16, 1.0, v16
	v_add_f32_e32 v17, 1.0, v17
	v_mul_f32_e32 v22, 0xbfb8aa3b, v10
	v_mul_f32_e32 v23, 0xbfb8aa3b, v11
	v_rcp_f32_e32 v16, v16
	v_rcp_f32_e32 v17, v17
	v_add_f32_e32 v18, 1.0, v18
	v_add_f32_e32 v19, 1.0, v19
	v_exp_f32_e32 v22, v22
	v_exp_f32_e32 v23, v23
	v_rcp_f32_e32 v18, v18
	v_rcp_f32_e32 v19, v19
	v_add_f32_e32 v20, 1.0, v20
	v_add_f32_e32 v21, 1.0, v21
	v_rcp_f32_e32 v20, v20
	v_rcp_f32_e32 v21, v21
	v_add_f32_e32 v22, 1.0, v22
	v_add_f32_e32 v23, 1.0, v23
	v_pk_mul_f32 v[12:13], v[12:13], v[16:17]
	v_rcp_f32_e32 v22, v22
	v_rcp_f32_e32 v23, v23
	v_pk_mul_f32 v[4:5], v[12:13], v[4:5]
	v_pk_mul_f32 v[12:13], v[14:15], v[18:19]
	v_cvt_pk_bf16_f32 v4, v4, v5
	v_pk_mul_f32 v[6:7], v[12:13], v[6:7]
	s_nop 0
	v_cvt_pk_bf16_f32 v5, v6, v7
	v_pk_mul_f32 v[6:7], v[8:9], v[20:21]
	s_nop 0
	v_pk_mul_f32 v[0:1], v[6:7], v[0:1]
	s_nop 0
	v_cvt_pk_bf16_f32 v6, v0, v1
	v_pk_mul_f32 v[0:1], v[10:11], v[22:23]
	s_nop 0
	v_pk_mul_f32 v[0:1], v[0:1], v[2:3]
	s_nop 0
	v_cvt_pk_bf16_f32 v7, v0, v1
	v_add_u32_e32 v0, 0xb0, v138
	v_mad_i64_i32 v[0:1], s[2:3], v0, s4, v[112:113]
	v_lshl_add_u64 v[0:1], v[0:1], 0, v[114:115]
	s_mov_b32 s2, s8
	s_mov_b32 s3, s10
	global_store_dwordx4 v[0:1], v[4:7], off
	s_cbranch_vccz .LBB0_34
	s_waitcnt vmcnt(0)
	s_cmpk_gt_u32 s24, 0xff
	s_cbranch_scc1 .LBB0_41
	s_barrier

; #define PG8_STAGE(bufoff, gbase) do { _Pragma("unroll") for (int _i = 0; _i < 2; ++_i) \
;         __builtin_amdgcn_global_load_lds((const unsigned*)((const char*)(gbase) + voff[_i]), (LAS unsigned*)(lds + (bufoff) + ldsw + _i * 8192), 16, 0, 0); } while (0)
; #define PG8_LDA(dst, b, h) do { _Pragma("unroll") for (int m = 0; m < 4; ++m) _Pragma("unroll") for (int k = 0; k < 2; ++k) dst[m][k] = *(const LAS bf16x8*)(lds + PG8_SA(b, h) + aoff + m * 2048 + k * 1024); } while (0)
; #define PG8_LDB(dst, b, h) do { _Pragma("unroll") for (int n = 0; n < 2; ++n) _Pragma("unroll") for (int k = 0; k < 2; ++k) dst[n][k] = *(const LAS bf16x8*)(lds + PG8_SB(b, h) + boff + n * 2048 + k * 1024); } while (0)
; #define PG8_MMA(ai, bj, At, Bt) do { __builtin_amdgcn_s_setprio(1); _Pragma("unroll") for (int m = 0; m < 4; ++m) _Pragma("unroll") for (int n = 0; n < 2; ++n) _Pragma("unroll") for (int k = 0; k < 2; ++k) \
;         acc[ai][bj][m][n] = __builtin_amdgcn_mfma_f32_16x16x32_bf16(Bt[n][k], At[m][k], acc[ai][bj][m][n], 0, 0, 0); __builtin_amdgcn_s_setprio(0); } while (0)
; #define PG8_WAIT_V(n) asm volatile("s_waitcnt vmcnt(" #n ")" ::: "memory")
; #define PG8_WAIT_L(n) asm volatile("s_waitcnt lgkmcnt(" #n ")" ::: "memory")
; #define PG8_BAR __builtin_amdgcn_s_barrier()
; #define PG8_SCHED __builtin_amdgcn_sched_barrier(0)
; template <class Epi>
; DI void gemm_phase(LAS unsigned char* lds, const Gemm g, const StaticOrder& S, const Epi& E) {
;     ...
;             const bool last = (t == nt - 2);
;             const char* a1 = cA + (size_t)(t + 1) * kstep;
;             const char* a2 = last ? nA : cA + (size_t)(t + 2) * kstep; const char* b2 = last ? nB : cB + (size_t)(t + 2) * kstep;
;             const char* a3 = a2 + kstep; const char* b3 = b2 + kstep;
;             PG8_LDB(B0, 0, 0); PG8_SCHED; PG8_LDA(At, 0, 0); PG8_STAGE(PG8_SA(1, 1), a1 + hstep);
;             PG8_WAIT_L(8); PG8_BAR; PG8_WAIT_L(0); PG8_MMA(0, 0, At, B0); PG8_BAR; PG8_SCHED;
;             PG8_LDB(B1, 0, 1); PG8_STAGE(PG8_SB(0, 0), b2);
;             PG8_BAR; PG8_WAIT_L(0); PG8_MMA(0, 1, At, B1); PG8_BAR;
;             PG8_LDA(At, 0, 1); PG8_STAGE(PG8_SA(0, 0), a2);
;             PG8_BAR; PG8_WAIT_L(0); PG8_MMA(1, 0, At, B0); PG8_BAR; PG8_SCHED;
;             PG8_STAGE(PG8_SB(0, 1), b2 + hstep);
;             PG8_WAIT_V(6); PG8_BAR; PG8_MMA(1, 1, At, B1); PG8_BAR;
.LBB0_77:
	ds_read_b128 v[128:131], v226
	ds_read_b128 v[132:135], v226 offset:1024
	ds_read_b128 v[136:139], v226 offset:2048
	ds_read_b128 v[140:143], v226 offset:3072
	ds_read_b128 v[144:147], v228
	ds_read_b128 v[148:151], v228 offset:1024
	ds_read_b128 v[152:155], v228 offset:2048
	ds_read_b128 v[194:197], v228 offset:3072
	ds_read_b128 v[198:201], v228 offset:4096
	ds_read_b128 v[202:205], v228 offset:5120
	ds_read_b128 v[206:209], v228 offset:6144
	ds_read_b128 v[210:213], v228 offset:7168
	s_add_u32 s22, s20, 0x100
	s_addc_u32 s23, s21, 0
	s_add_i32 s43, 0, 0x10000
	s_cmp_eq_u32 s33, 32
	s_cselect_b32 s27, s9, s23
	s_cselect_b32 s26, s8, s22
	s_cselect_b32 s25, s11, s5
	s_cselect_b32 s24, s10, s4
	s_add_i32 m0, s34, 0xc000
	s_nop 0
	global_load_lds_dwordx4 v190, s[20:21]
	s_add_i32 m0, s34, 0xe000
	s_nop 0
	global_load_lds_dwordx4 v192, s[20:21]
	s_waitcnt lgkmcnt(8)
	s_setprio 1
	s_barrier
	s_waitcnt lgkmcnt(0)
	v_mfma_f32_16x16x32_bf16 v[124:127], v[128:131], v[144:147], v[124:127]
	v_mfma_f32_16x16x32_bf16 v[120:123], v[136:139], v[144:147], v[120:123]
	v_mfma_f32_16x16x32_bf16 v[116:119], v[128:131], v[152:155], v[116:119]
	v_mfma_f32_16x16x32_bf16 v[112:115], v[136:139], v[152:155], v[112:115]
	v_mfma_f32_16x16x32_bf16 v[108:111], v[128:131], v[198:201], v[108:111]
	v_mfma_f32_16x16x32_bf16 v[104:107], v[136:139], v[198:201], v[104:107]
	v_mfma_f32_16x16x32_bf16 v[100:103], v[128:131], v[206:209], v[100:103]
	v_mfma_f32_16x16x32_bf16 v[96:99], v[136:139], v[206:209], v[96:99]
	v_mfma_f32_16x16x32_bf16 v[124:127], v[132:135], v[148:151], v[124:127]
	v_mfma_f32_16x16x32_bf16 v[120:123], v[140:143], v[148:151], v[120:123]
	ds_read_b128 v[214:217], v226 offset:16384
	v_mfma_f32_16x16x32_bf16 v[116:119], v[132:135], v[194:197], v[116:119]
	ds_read_b128 v[230:233], v226 offset:17408
	v_mfma_f32_16x16x32_bf16 v[112:115], v[140:143], v[194:197], v[112:115]
	ds_read_b128 v[234:237], v226 offset:18432
	v_mfma_f32_16x16x32_bf16 v[108:111], v[132:135], v[202:205], v[108:111]
	ds_read_b128 v[238:241], v226 offset:19456
	v_mfma_f32_16x16x32_bf16 v[104:107], v[140:143], v[202:205], v[104:107]
	v_mfma_f32_16x16x32_bf16 v[100:103], v[132:135], v[210:213], v[100:103]
	s_setprio 0
	v_mfma_f32_16x16x32_bf16 v[96:99], v[140:143], v[210:213], v[96:99]
	s_barrier
	s_add_i32 s44, 0, 0x14000
	s_add_i32 s20, s43, s31
	s_mov_b32 m0, s20
	s_nop 0
	global_load_lds_dwordx4 v188, s[24:25]
	s_add_i32 m0, s20, 0x2000
	s_nop 0
	global_load_lds_dwordx4 v186, s[24:25]
	s_waitcnt lgkmcnt(0)
	s_setprio 1
	s_barrier
	v_mfma_f32_16x16x32_bf16 v[60:63], v[214:217], v[144:147], v[60:63]
	v_mfma_f32_16x16x32_bf16 v[56:59], v[234:237], v[144:147], v[56:59]
	v_mfma_f32_16x16x32_bf16 v[52:55], v[214:217], v[152:155], v[52:55]
	v_mfma_f32_16x16x32_bf16 v[48:51], v[234:237], v[152:155], v[48:51]
	v_mfma_f32_16x16x32_bf16 v[44:47], v[214:217], v[198:201], v[44:47]
	v_mfma_f32_16x16x32_bf16 v[40:43], v[234:237], v[198:201], v[40:43]
	v_mfma_f32_16x16x32_bf16 v[36:39], v[214:217], v[206:209], v[36:39]
	v_mfma_f32_16x16x32_bf16 v[32:35], v[234:237], v[206:209], v[32:35]
	v_mfma_f32_16x16x32_bf16 v[60:63], v[230:233], v[148:151], v[60:63]
	ds_read_b128 v[144:147], v228 offset:16384
	s_mov_b32 m0, s34
	v_mfma_f32_16x16x32_bf16 v[56:59], v[238:241], v[148:151], v[56:59]
	ds_read_b128 v[148:151], v228 offset:17408
	v_mfma_f32_16x16x32_bf16 v[52:55], v[230:233], v[194:197], v[52:55]
	ds_read_b128 v[152:155], v228 offset:18432
	v_mfma_f32_16x16x32_bf16 v[48:51], v[238:241], v[194:197], v[48:51]
	ds_read_b128 v[194:197], v228 offset:19456
	v_mfma_f32_16x16x32_bf16 v[44:47], v[230:233], v[202:205], v[44:47]
	ds_read_b128 v[198:201], v228 offset:20480
	v_mfma_f32_16x16x32_bf16 v[40:43], v[238:241], v[202:205], v[40:43]
	ds_read_b128 v[202:205], v228 offset:21504
	v_mfma_f32_16x16x32_bf16 v[36:39], v[230:233], v[210:213], v[36:39]
	ds_read_b128 v[206:209], v228 offset:22528
	s_setprio 0
	v_mfma_f32_16x16x32_bf16 v[32:35], v[238:241], v[210:213], v[32:35]
	s_barrier
	ds_read_b128 v[210:213], v228 offset:23552
	global_load_lds_dwordx4 v188, s[26:27]
	s_mov_b64 s[100:101], s[26:27]
	s_mov_b32 m0, s35
	s_nop 0
	global_load_lds_dwordx4 v186, s[26:27]
	s_waitcnt lgkmcnt(0)
	s_setprio 1
	s_barrier
	v_mfma_f32_16x16x32_bf16 v[92:95], v[128:131], v[144:147], v[92:95]
	v_mfma_f32_16x16x32_bf16 v[88:91], v[136:139], v[144:147], v[88:91]
	v_mfma_f32_16x16x32_bf16 v[84:87], v[128:131], v[152:155], v[84:87]
	v_mfma_f32_16x16x32_bf16 v[80:83], v[136:139], v[152:155], v[80:83]
	v_mfma_f32_16x16x32_bf16 v[76:79], v[128:131], v[198:201], v[76:79]
	v_mfma_f32_16x16x32_bf16 v[72:75], v[136:139], v[198:201], v[72:75]
	v_mfma_f32_16x16x32_bf16 v[68:71], v[128:131], v[206:209], v[68:71]
	v_mfma_f32_16x16x32_bf16 v[64:67], v[136:139], v[206:209], v[64:67]
	v_mfma_f32_16x16x32_bf16 v[92:95], v[132:135], v[148:151], v[92:95]
	v_mfma_f32_16x16x32_bf16 v[88:91], v[140:143], v[148:151], v[88:91]
	v_mfma_f32_16x16x32_bf16 v[84:87], v[132:135], v[194:197], v[84:87]
	v_mfma_f32_16x16x32_bf16 v[80:83], v[140:143], v[194:197], v[80:83]
	v_mfma_f32_16x16x32_bf16 v[76:79], v[132:135], v[202:205], v[76:79]
	v_mfma_f32_16x16x32_bf16 v[72:75], v[140:143], v[202:205], v[72:75]
	v_mfma_f32_16x16x32_bf16 v[68:71], v[132:135], v[210:213], v[68:71]
	s_setprio 0
	v_mfma_f32_16x16x32_bf16 v[64:67], v[140:143], v[210:213], v[64:67]
	s_barrier
	s_add_u32 s20, s24, 0x90000
	s_addc_u32 s21, s25, 0
	s_add_i32 s43, s44, s31
	s_mov_b32 m0, s43
	s_nop 0
	global_load_lds_dwordx4 v188, s[20:21]
	s_add_i32 m0, s43, 0x2000
	s_nop 0
	global_load_lds_dwordx4 v186, s[20:21]
	s_waitcnt vmcnt(6)
	s_setprio 1
	s_barrier
; #define PG8_STAGE(bufoff, gbase) do { _Pragma("unroll") for (int _i = 0; _i < 2; ++_i) \
;         __builtin_amdgcn_global_load_lds((const unsigned*)((const char*)(gbase) + voff[_i]), (LAS unsigned*)(lds + (bufoff) + ldsw + _i * 8192), 16, 0, 0); } while (0)
; #define PG8_LDA(dst, b, h) do { _Pragma("unroll") for (int m = 0; m < 4; ++m) _Pragma("unroll") for (int k = 0; k < 2; ++k) dst[m][k] = *(const LAS bf16x8*)(lds + PG8_SA(b, h) + aoff + m * 2048 + k * 1024); } while (0)
; #define PG8_LDB(dst, b, h) do { _Pragma("unroll") for (int n = 0; n < 2; ++n) _Pragma("unroll") for (int k = 0; k < 2; ++k) dst[n][k] = *(const LAS bf16x8*)(lds + PG8_SB(b, h) + boff + n * 2048 + k * 1024); } while (0)
; #define PG8_MMA(ai, bj, At, Bt) do { __builtin_amdgcn_s_setprio(1); _Pragma("unroll") for (int m = 0; m < 4; ++m) _Pragma("unroll") for (int n = 0; n < 2; ++n) _Pragma("unroll") for (int k = 0; k < 2; ++k) \
;         acc[ai][bj][m][n] = __builtin_amdgcn_mfma_f32_16x16x32_bf16(Bt[n][k], At[m][k], acc[ai][bj][m][n], 0, 0, 0); __builtin_amdgcn_s_setprio(0); } while (0)
; #define PG8_WAIT_V(n) asm volatile("s_waitcnt vmcnt(" #n ")" ::: "memory")
; #define PG8_WAIT_L(n) asm volatile("s_waitcnt lgkmcnt(" #n ")" ::: "memory")
; #define PG8_BAR __builtin_amdgcn_s_barrier()
; #define PG8_SCHED __builtin_amdgcn_sched_barrier(0)
; template <class Epi>
; DI void gemm_phase(LAS unsigned char* lds, const Gemm g, const StaticOrder& S, const Epi& E) {
;     ...
;             PG8_WAIT_V(6); PG8_BAR; PG8_MMA(1, 1, At, B1); PG8_BAR;
;             PG8_LDB(B0, 1, 0); PG8_SCHED; PG8_LDA(At, 1, 0); PG8_STAGE(PG8_SA(0, 1), a2 + hstep);
;             PG8_WAIT_L(8); PG8_BAR; PG8_WAIT_L(0); PG8_MMA(0, 0, At, B0); PG8_BAR; PG8_SCHED;
;             PG8_LDB(B1, 1, 1); PG8_STAGE(PG8_SB(1, 0), b3);
;             PG8_BAR; PG8_WAIT_L(0); PG8_MMA(0, 1, At, B1); PG8_BAR;
;             PG8_LDA(At, 1, 1); PG8_STAGE(PG8_SA(1, 0), a3);
;             PG8_BAR; PG8_WAIT_L(0); PG8_MMA(1, 0, At, B0); PG8_BAR; PG8_SCHED;
	v_mfma_f32_16x16x32_bf16 v[28:31], v[214:217], v[144:147], v[28:31]
	v_mfma_f32_16x16x32_bf16 v[24:27], v[234:237], v[144:147], v[24:27]
	v_mfma_f32_16x16x32_bf16 v[20:23], v[214:217], v[152:155], v[20:23]
	v_mfma_f32_16x16x32_bf16 v[16:19], v[234:237], v[152:155], v[16:19]
	v_mfma_f32_16x16x32_bf16 v[12:15], v[214:217], v[198:201], v[12:15]
	v_mfma_f32_16x16x32_bf16 v[8:11], v[234:237], v[198:201], v[8:11]
	v_mfma_f32_16x16x32_bf16 v[4:7], v[214:217], v[206:209], v[4:7]
	v_mfma_f32_16x16x32_bf16 v[0:3], v[234:237], v[206:209], v[0:3]
	v_mfma_f32_16x16x32_bf16 v[28:31], v[230:233], v[148:151], v[28:31]
	s_add_i32 s43, 0, 0x18000
	v_mfma_f32_16x16x32_bf16 v[24:27], v[238:241], v[148:151], v[24:27]
	v_mfma_f32_16x16x32_bf16 v[20:23], v[230:233], v[194:197], v[20:23]
	v_mfma_f32_16x16x32_bf16 v[16:19], v[238:241], v[194:197], v[16:19]
	v_mfma_f32_16x16x32_bf16 v[12:15], v[230:233], v[202:205], v[12:15]
	v_mfma_f32_16x16x32_bf16 v[8:11], v[238:241], v[202:205], v[8:11]
	v_mfma_f32_16x16x32_bf16 v[4:7], v[230:233], v[210:213], v[4:7]
	s_setprio 0
	v_mfma_f32_16x16x32_bf16 v[0:3], v[238:241], v[210:213], v[0:3]
	s_barrier
	ds_read_b128 v[128:131], v226 offset:32768
	ds_read_b128 v[132:135], v226 offset:33792
	ds_read_b128 v[136:139], v226 offset:34816
	ds_read_b128 v[140:143], v226 offset:35840
	ds_read_b128 v[144:147], v228 offset:32768
	ds_read_b128 v[148:151], v228 offset:33792
	ds_read_b128 v[152:155], v228 offset:34816
	ds_read_b128 v[194:197], v228 offset:35840
	ds_read_b128 v[198:201], v228 offset:36864
	ds_read_b128 v[202:205], v228 offset:37888
	ds_read_b128 v[206:209], v228 offset:38912
	ds_read_b128 v[210:213], v228 offset:39936
	s_add_u32 s20, s26, 0x90000
	s_addc_u32 s21, s27, 0
	s_mov_b32 m0, s36
	s_nop 0
	global_load_lds_dwordx4 v188, s[20:21]
	s_mov_b32 m0, s37
	s_nop 0
	global_load_lds_dwordx4 v186, s[20:21]
	s_waitcnt lgkmcnt(8)
	s_setprio 1
	s_barrier
	s_waitcnt lgkmcnt(0)
	v_mfma_f32_16x16x32_bf16 v[124:127], v[128:131], v[144:147], v[124:127]
	v_mfma_f32_16x16x32_bf16 v[120:123], v[136:139], v[144:147], v[120:123]
	v_mfma_f32_16x16x32_bf16 v[116:119], v[128:131], v[152:155], v[116:119]
	v_mfma_f32_16x16x32_bf16 v[112:115], v[136:139], v[152:155], v[112:115]
	v_mfma_f32_16x16x32_bf16 v[108:111], v[128:131], v[198:201], v[108:111]
	v_mfma_f32_16x16x32_bf16 v[104:107], v[136:139], v[198:201], v[104:107]
	v_mfma_f32_16x16x32_bf16 v[100:103], v[128:131], v[206:209], v[100:103]
	v_mfma_f32_16x16x32_bf16 v[96:99], v[136:139], v[206:209], v[96:99]
	v_mfma_f32_16x16x32_bf16 v[124:127], v[132:135], v[148:151], v[124:127]
	v_mfma_f32_16x16x32_bf16 v[120:123], v[140:143], v[148:151], v[120:123]
	ds_read_b128 v[214:217], v226 offset:49152
	v_mfma_f32_16x16x32_bf16 v[116:119], v[132:135], v[194:197], v[116:119]
	ds_read_b128 v[230:233], v226 offset:50176
	v_mfma_f32_16x16x32_bf16 v[112:115], v[140:143], v[194:197], v[112:115]
	ds_read_b128 v[234:237], v226 offset:51200
	v_mfma_f32_16x16x32_bf16 v[108:111], v[132:135], v[202:205], v[108:111]
	ds_read_b128 v[238:241], v226 offset:52224
	v_mfma_f32_16x16x32_bf16 v[104:107], v[140:143], v[202:205], v[104:107]
	v_mfma_f32_16x16x32_bf16 v[100:103], v[132:135], v[210:213], v[100:103]
	s_setprio 0
	v_mfma_f32_16x16x32_bf16 v[96:99], v[140:143], v[210:213], v[96:99]
	s_barrier
	s_add_i32 s26, 0, 0x1c000
	s_add_i32 s20, s43, s31
	s_add_i32 m0, s20, 0xffffff80
	s_nop 0
	global_load_lds_dwordx4 v188, s[24:25] offset:128
	s_add_i32 m0, s20, 0x1f80
	s_nop 0
	global_load_lds_dwordx4 v186, s[24:25] offset:128
	s_waitcnt lgkmcnt(0)
	s_setprio 1
	s_barrier
	v_mfma_f32_16x16x32_bf16 v[60:63], v[214:217], v[144:147], v[60:63]
	v_mfma_f32_16x16x32_bf16 v[56:59], v[234:237], v[144:147], v[56:59]
	v_mfma_f32_16x16x32_bf16 v[52:55], v[214:217], v[152:155], v[52:55]
	v_mfma_f32_16x16x32_bf16 v[48:51], v[234:237], v[152:155], v[48:51]
	v_mfma_f32_16x16x32_bf16 v[44:47], v[214:217], v[198:201], v[44:47]
	v_mfma_f32_16x16x32_bf16 v[40:43], v[234:237], v[198:201], v[40:43]
	v_mfma_f32_16x16x32_bf16 v[36:39], v[214:217], v[206:209], v[36:39]
	v_mfma_f32_16x16x32_bf16 v[32:35], v[234:237], v[206:209], v[32:35]
	v_mfma_f32_16x16x32_bf16 v[60:63], v[230:233], v[148:151], v[60:63]
	ds_read_b128 v[144:147], v228 offset:49152
	s_add_i32 m0, s38, 0xffffff80
	v_mfma_f32_16x16x32_bf16 v[56:59], v[238:241], v[148:151], v[56:59]
	ds_read_b128 v[148:151], v228 offset:50176
	v_mfma_f32_16x16x32_bf16 v[52:55], v[230:233], v[194:197], v[52:55]
	ds_read_b128 v[152:155], v228 offset:51200
	v_mfma_f32_16x16x32_bf16 v[48:51], v[238:241], v[194:197], v[48:51]
	ds_read_b128 v[194:197], v228 offset:52224
	v_mfma_f32_16x16x32_bf16 v[44:47], v[230:233], v[202:205], v[44:47]
	ds_read_b128 v[198:201], v228 offset:53248
	v_mfma_f32_16x16x32_bf16 v[40:43], v[238:241], v[202:205], v[40:43]
	ds_read_b128 v[202:205], v228 offset:54272
	v_mfma_f32_16x16x32_bf16 v[36:39], v[230:233], v[210:213], v[36:39]
	ds_read_b128 v[206:209], v228 offset:55296
	s_setprio 0
	v_mfma_f32_16x16x32_bf16 v[32:35], v[238:241], v[210:213], v[32:35]
	s_barrier
	ds_read_b128 v[210:213], v228 offset:56320
	global_load_lds_dwordx4 v188, s[100:101] offset:128
	s_add_i32 m0, s39, 0xffffff80
	s_nop 0
	global_load_lds_dwordx4 v186, s[100:101] offset:128
	s_waitcnt lgkmcnt(0)
	s_setprio 1
	s_barrier
; template <class Epi>
; DI void gemm_phase(LAS unsigned char* lds, const Gemm g, const StaticOrder& S, const Epi& E) {
;     ...
;             PG8_BAR; PG8_WAIT_L(0); PG8_MMA(1, 0, At, B0); PG8_BAR; PG8_SCHED;
;             PG8_STAGE(PG8_SB(1, 1), b3 + hstep);
;             PG8_WAIT_V(6); PG8_BAR; PG8_MMA(1, 1, At, B1); PG8_BAR;
;         }
;         E(acc, cur, wr, wc, fr, fq);
;     template <bool LN, int BJ, int LO, int HI> DI void batch(const f32x4 (&acc)[2][2][4][2], unsigned row0, unsigned col0, const f32x4 (&gv)[2], const f32x4 (&bv)[2]) const {
;         f32x4 r[HI - LO]; float mean[(HI - LO) / 2], rstd[(HI - LO) / 2];
; #pragma unroll
;         for (int i = LO; i < HI; ++i) { const int ai = i >> 3, m = (i >> 1) & 3, n = i & 1; const unsigned row = row0 + ai * HALF + m * 16;
;             if (n == 0) { mean[(i - LO) >> 1] = 0.f; rstd[(i - LO) >> 1] = 1.f;
;                 if (LN) { const float2 st = *(const float2*)(stats + row * 2u); mean[(i - LO) >> 1] = st.x; rstd[(i - LO) >> 1] = st.y; } }
;             r[i - LO] = *(const f32x4*)(src + (row * (unsigned)DM + col0 + BJ * HALF + n * 16)); }
; #pragma unroll
;         for (int i = LO; i < HI; ++i) { const int ai = i >> 3, m = (i >> 1) & 3, n = i & 1; const unsigned row = row0 + ai * HALF + m * 16;
;             *(f32x4*)(Y + (row * (unsigned)DM + col0 + BJ * HALF + n * 16)) = acc[ai][BJ][m][n] + ((r[i - LO] - mean[(i - LO) >> 1]) * rstd[(i - LO) >> 1]) * gv[n] + bv[n]; }
;         __builtin_amdgcn_sched_barrier(0);
;     }
;     template <bool LN, int BJ> DI void load_gb(unsigned col0, f32x4 (&gv)[2], f32x4 (&bv)[2]) const {
; #pragma unroll
;         for (int n = 0; n < 2; ++n) {
;             if (LN) { gv[n] = *(const f32x4*)(gam + col0 + BJ * HALF + n * 16) * ALPHA; bv[n] = *(const f32x4*)(bet + col0 + BJ * HALF + n * 16) * ALPHA; }
;             else { gv[n] = (f32x4){ALPHA, ALPHA, ALPHA, ALPHA}; bv[n] = (f32x4){0.f, 0.f, 0.f, 0.f}; }
;         }
;     }
;     template <bool LN> DI void run(const f32x4 (&acc)[2][2][4][2], const Unit& u, int wr, int wc, int fr, int fq) const {
;         const unsigned row0 = u.pm * BM + wr * 64 + fr, col0 = u.pn * BM + wc * 32 + 4 * fq;
;         f32x4 gv[2], bv[2];
;         load_gb<LN, 0>(col0, gv, bv);
;         batch<LN, 0, 0, 4>(acc, row0, col0, gv, bv);
;         batch<LN, 0, 4, 8>(acc, row0, col0, gv, bv);
;         batch<LN, 0, 8, 12>(acc, row0, col0, gv, bv);
	v_mfma_f32_16x16x32_bf16 v[92:95], v[128:131], v[144:147], v[92:95]
	v_mfma_f32_16x16x32_bf16 v[88:91], v[136:139], v[144:147], v[88:91]
	v_mfma_f32_16x16x32_bf16 v[84:87], v[128:131], v[152:155], v[84:87]
	v_mfma_f32_16x16x32_bf16 v[80:83], v[136:139], v[152:155], v[80:83]
	v_mfma_f32_16x16x32_bf16 v[76:79], v[128:131], v[198:201], v[76:79]
	v_mfma_f32_16x16x32_bf16 v[72:75], v[136:139], v[198:201], v[72:75]
	v_mfma_f32_16x16x32_bf16 v[68:71], v[128:131], v[206:209], v[68:71]
	v_mfma_f32_16x16x32_bf16 v[64:67], v[136:139], v[206:209], v[64:67]
	v_mfma_f32_16x16x32_bf16 v[92:95], v[132:135], v[148:151], v[92:95]
	v_mfma_f32_16x16x32_bf16 v[88:91], v[140:143], v[148:151], v[88:91]
	v_mfma_f32_16x16x32_bf16 v[84:87], v[132:135], v[194:197], v[84:87]
	v_mfma_f32_16x16x32_bf16 v[80:83], v[140:143], v[194:197], v[80:83]
	v_mfma_f32_16x16x32_bf16 v[76:79], v[132:135], v[202:205], v[76:79]
	v_mfma_f32_16x16x32_bf16 v[72:75], v[140:143], v[202:205], v[72:75]
	v_mfma_f32_16x16x32_bf16 v[68:71], v[132:135], v[210:213], v[68:71]
	s_setprio 0
	v_mfma_f32_16x16x32_bf16 v[64:67], v[140:143], v[210:213], v[64:67]
	s_barrier
	s_add_u32 s20, s24, 0x90080
	s_addc_u32 s21, s25, 0
	s_add_i32 s24, s26, s31
	s_mov_b32 m0, s24
	s_nop 0
	global_load_lds_dwordx4 v188, s[20:21]
	s_add_i32 m0, s24, 0x2000
	s_nop 0
	global_load_lds_dwordx4 v186, s[20:21]
	s_waitcnt vmcnt(6)
	s_setprio 1
	s_barrier
	v_mfma_f32_16x16x32_bf16 v[28:31], v[214:217], v[144:147], v[28:31]
	v_mfma_f32_16x16x32_bf16 v[24:27], v[234:237], v[144:147], v[24:27]
	v_mfma_f32_16x16x32_bf16 v[20:23], v[214:217], v[152:155], v[20:23]
	v_mfma_f32_16x16x32_bf16 v[16:19], v[234:237], v[152:155], v[16:19]
	v_mfma_f32_16x16x32_bf16 v[12:15], v[214:217], v[198:201], v[12:15]
	v_mfma_f32_16x16x32_bf16 v[8:11], v[234:237], v[198:201], v[8:11]
	v_mfma_f32_16x16x32_bf16 v[4:7], v[214:217], v[206:209], v[4:7]
	v_mfma_f32_16x16x32_bf16 v[0:3], v[234:237], v[206:209], v[0:3]
	v_mfma_f32_16x16x32_bf16 v[28:31], v[230:233], v[148:151], v[28:31]
	s_add_i32 s33, s33, 2
	v_mfma_f32_16x16x32_bf16 v[24:27], v[238:241], v[148:151], v[24:27]
	s_add_u32 s4, s4, 0x100
	v_mfma_f32_16x16x32_bf16 v[20:23], v[230:233], v[194:197], v[20:23]
	s_addc_u32 s5, s5, 0
	v_mfma_f32_16x16x32_bf16 v[16:19], v[238:241], v[194:197], v[16:19]
	s_cmp_gt_u32 s33, 33
	v_mfma_f32_16x16x32_bf16 v[12:15], v[230:233], v[202:205], v[12:15]
	s_mov_b64 s[20:21], s[22:23]
	v_mfma_f32_16x16x32_bf16 v[8:11], v[238:241], v[202:205], v[8:11]
	v_mfma_f32_16x16x32_bf16 v[4:7], v[230:233], v[210:213], v[4:7]
	s_setprio 0
	v_mfma_f32_16x16x32_bf16 v[0:3], v[238:241], v[210:213], v[0:3]
	s_barrier
	s_cbranch_scc0 .LBB0_77
	v_lshl_add_u32 v206, s3, 8, v225
	v_lshl_or_b32 v158, s2, 8, v227
	v_lshlrev_b32_e32 v232, 11, v206
	s_andn2_b64 vcc, exec, s[14:15]
	v_or_b32_e32 v231, 16, v158
	v_add_u32_e32 v194, v232, v158
	v_or_b32_e32 v230, 0x80, v158
	v_or_b32_e32 v229, 0x90, v158
	s_cbranch_vccnz .LBB0_80
	v_lshlrev_b64 v[132:133], 2, v[158:159]
	v_lshl_add_u64 v[140:141], s[16:17], 0, v[132:133]
	global_load_dwordx4 v[128:131], v[140:141], off
	v_lshl_add_u64 v[142:143], s[18:19], 0, v[132:133]
	v_readlane_b32 s2, v253, 8
	v_mov_b32_e32 v195, v159
	v_lshlrev_b32_e32 v136, 1, v206
	v_mov_b32_e32 v137, v159
	v_readlane_b32 s3, v253, 9
	v_lshlrev_b64 v[212:213], 2, v[194:195]
	v_add_u32_e32 v146, v232, v231
	v_lshl_add_u64 v[144:145], v[136:137], 2, s[2:3]
	v_lshl_add_u64 v[136:137], s[88:89], 0, v[212:213]
	v_mov_b32_e32 v147, v159
	v_lshl_add_u64 v[146:147], v[146:147], 2, s[88:89]
	v_or_b32_e32 v195, 16, v206
	v_mov_b32_e32 v201, v159
	v_mov_b32_e32 v209, v159
	v_lshl_add_u64 v[212:213], s[90:91], 0, v[212:213]
	s_waitcnt vmcnt(0)
	v_pk_mul_f32 v[152:153], v[130:131], s[78:79] op_sel_hi:[1,0]
	v_pk_mul_f32 v[154:155], v[128:129], s[78:79] op_sel_hi:[1,0]
	global_load_dwordx4 v[132:135], v[142:143], off
	global_load_dwordx4 v[128:131], v[140:141], off offset:64
	global_load_dwordx2 v[204:205], v[144:145], off
	global_load_dwordx4 v[196:199], v[146:147], off
	v_lshlrev_b32_e32 v146, 1, v195
	global_load_dwordx4 v[136:139], v[136:137], off
	v_lshlrev_b32_e32 v195, 11, v195
	v_mov_b32_e32 v147, v159
	v_add_u32_e32 v200, v195, v158
	v_lshl_add_u64 v[146:147], v[146:147], 2, s[2:3]
	v_lshl_add_u64 v[200:201], v[200:201], 2, s[88:89]
	global_load_dwordx2 v[214:215], v[146:147], off
	v_add_u32_e32 v208, v195, v231
	global_load_dwordx4 v[200:203], v[200:201], off
	v_lshl_add_u64 v[208:209], v[208:209], 2, s[88:89]
	global_load_dwordx4 v[208:211], v[208:209], off
	s_waitcnt vmcnt(0)
	v_pk_mul_f32 v[148:149], v[130:131], s[78:79] op_sel_hi:[1,0]
	v_pk_mul_f32 v[150:151], v[128:129], s[78:79] op_sel_hi:[1,0]
	global_load_dwordx4 v[128:131], v[142:143], off offset:64
	v_sub_f32_e32 v137, v137, v204
	v_sub_f32_e32 v136, v136, v204
	v_sub_f32_e32 v139, v139, v204
	v_sub_f32_e32 v138, v138, v204
	v_pk_mul_f32 v[138:139], v[204:205], v[138:139] op_sel:[1,0]
	v_pk_mul_f32 v[136:137], v[204:205], v[136:137] op_sel:[1,0]
	v_pk_fma_f32 v[138:139], v[152:153], v[138:139], v[126:127]
	v_pk_fma_f32 v[136:137], v[154:155], v[136:137], v[124:125]
	v_pk_fma_f32 v[138:139], v[134:135], s[78:79], v[138:139] op_sel_hi:[1,0,1]
	v_pk_fma_f32 v[136:137], v[132:133], s[78:79], v[136:137] op_sel_hi:[1,0,1]
	global_store_dwordx4 v[212:213], v[136:139], off
	s_nop 1
	v_sub_f32_e32 v137, v197, v204
	v_sub_f32_e32 v136, v196, v204
	v_sub_f32_e32 v139, v199, v204
	v_sub_f32_e32 v138, v198, v204
	v_pk_mul_f32 v[138:139], v[204:205], v[138:139] op_sel:[1,0]
	v_pk_mul_f32 v[136:137], v[204:205], v[136:137] op_sel:[1,0]
	v_pk_fma_f32 v[138:139], v[148:149], v[138:139], v[122:123]
	v_pk_fma_f32 v[136:137], v[150:151], v[136:137], v[120:121]
	v_or_b32_e32 v196, 16, v194
	v_mov_b32_e32 v197, v159
	v_lshl_add_u64 v[196:197], v[196:197], 2, s[90:91]
	s_waitcnt vmcnt(0)
;     template <bool LN, int BJ, int LO, int HI> DI void batch(const f32x4 (&acc)[2][2][4][2], unsigned row0, unsigned col0, const f32x4 (&gv)[2], const f32x4 (&bv)[2]) const {
;         f32x4 r[HI - LO]; float mean[(HI - LO) / 2], rstd[(HI - LO) / 2];
; #pragma unroll
;         for (int i = LO; i < HI; ++i) { const int ai = i >> 3, m = (i >> 1) & 3, n = i & 1; const unsigned row = row0 + ai * HALF + m * 16;
;             if (n == 0) { mean[(i - LO) >> 1] = 0.f; rstd[(i - LO) >> 1] = 1.f;
;                 if (LN) { const float2 st = *(const float2*)(stats + row * 2u); mean[(i - LO) >> 1] = st.x; rstd[(i - LO) >> 1] = st.y; } }
;             r[i - LO] = *(const f32x4*)(src + (row * (unsigned)DM + col0 + BJ * HALF + n * 16)); }
; #pragma unroll
;         for (int i = LO; i < HI; ++i) { const int ai = i >> 3, m = (i >> 1) & 3, n = i & 1; const unsigned row = row0 + ai * HALF + m * 16;
;             *(f32x4*)(Y + (row * (unsigned)DM + col0 + BJ * HALF + n * 16)) = acc[ai][BJ][m][n] + ((r[i - LO] - mean[(i - LO) >> 1]) * rstd[(i - LO) >> 1]) * gv[n] + bv[n]; }
	v_pk_fma_f32 v[138:139], v[130:131], s[78:79], v[138:139] op_sel_hi:[1,0,1]
	v_pk_fma_f32 v[136:137], v[128:129], s[78:79], v[136:137] op_sel_hi:[1,0,1]
	global_store_dwordx4 v[196:197], v[136:139], off
	v_add_u32_e32 v196, 0x8000, v194
	v_mov_b32_e32 v197, v159
	v_sub_f32_e32 v137, v201, v214
	v_sub_f32_e32 v136, v200, v214
	v_sub_f32_e32 v139, v203, v214
	v_sub_f32_e32 v138, v202, v214
	v_pk_mul_f32 v[138:139], v[214:215], v[138:139] op_sel:[1,0]
	v_pk_mul_f32 v[136:137], v[214:215], v[136:137] op_sel:[1,0]
	v_pk_fma_f32 v[138:139], v[152:153], v[138:139], v[118:119]
	v_pk_fma_f32 v[136:137], v[154:155], v[136:137], v[116:117]
	v_pk_fma_f32 v[138:139], v[134:135], s[78:79], v[138:139] op_sel_hi:[1,0,1]
	v_pk_fma_f32 v[136:137], v[132:133], s[78:79], v[136:137] op_sel_hi:[1,0,1]
	v_lshl_add_u64 v[196:197], v[196:197], 2, s[90:91]
	global_store_dwordx4 v[196:197], v[136:139], off
	v_add_u32_e32 v196, 0x8010, v194
	v_mov_b32_e32 v197, v159
	v_sub_f32_e32 v137, v209, v214
	v_sub_f32_e32 v136, v208, v214
	v_sub_f32_e32 v139, v211, v214
	v_sub_f32_e32 v138, v210, v214
	v_pk_mul_f32 v[138:139], v[214:215], v[138:139] op_sel:[1,0]
	v_pk_mul_f32 v[136:137], v[214:215], v[136:137] op_sel:[1,0]
	v_pk_fma_f32 v[138:139], v[148:149], v[138:139], v[114:115]
	v_pk_fma_f32 v[136:137], v[150:151], v[136:137], v[112:113]
	v_pk_fma_f32 v[138:139], v[130:131], s[78:79], v[138:139] op_sel_hi:[1,0,1]
	v_pk_fma_f32 v[136:137], v[128:129], s[78:79], v[136:137] op_sel_hi:[1,0,1]
	v_lshl_add_u64 v[196:197], v[196:197], 2, s[90:91]
	global_store_dwordx4 v[196:197], v[136:139], off
	s_nop 1
	v_or_b32_e32 v138, 32, v206
	v_lshlrev_b32_e32 v136, 1, v138
	v_mov_b32_e32 v137, v159
	v_lshlrev_b32_e32 v236, 11, v138
	v_lshl_add_u64 v[200:201], v[136:137], 2, s[2:3]
	v_add_u32_e32 v136, v236, v158
	v_lshl_add_u64 v[136:137], v[136:137], 2, s[88:89]
	global_load_dwordx2 v[204:205], v[200:201], off
	v_add_u32_e32 v196, v236, v231
	global_load_dwordx4 v[136:139], v[136:137], off
	v_mov_b32_e32 v197, v159
	v_lshl_add_u64 v[196:197], v[196:197], 2, s[88:89]
	global_load_dwordx4 v[196:199], v[196:197], off
	v_or_b32_e32 v207, 48, v206
	v_lshlrev_b32_e32 v235, 11, v207
	v_lshlrev_b32_e32 v202, 1, v207
	v_mov_b32_e32 v203, v159
	v_add_u32_e32 v208, v235, v158
	v_mov_b32_e32 v209, v159
	v_lshl_add_u64 v[202:203], v[202:203], 2, s[2:3]
	v_lshl_add_u64 v[208:209], v[208:209], 2, s[88:89]
	global_load_dwordx2 v[216:217], v[202:203], off
	v_add_u32_e32 v212, v235, v231
	global_load_dwordx4 v[208:211], v[208:209], off
	v_mov_b32_e32 v213, v159
	v_lshl_add_u64 v[212:213], v[212:213], 2, s[88:89]
	global_load_dwordx4 v[212:215], v[212:213], off
	v_add_u32_e32 v218, 0x10000, v194
	v_mov_b32_e32 v219, v159
	v_lshl_add_u64 v[218:219], v[218:219], 2, s[90:91]
	s_waitcnt vmcnt(0)
	v_sub_f32_e32 v137, v137, v204
	v_sub_f32_e32 v136, v136, v204
	v_sub_f32_e32 v139, v139, v204
	v_sub_f32_e32 v138, v138, v204
	v_pk_mul_f32 v[138:139], v[204:205], v[138:139] op_sel:[1,0]
	v_pk_mul_f32 v[136:137], v[204:205], v[136:137] op_sel:[1,0]
	v_pk_fma_f32 v[138:139], v[152:153], v[138:139], v[110:111]
	v_pk_fma_f32 v[136:137], v[154:155], v[136:137], v[108:109]
	v_pk_fma_f32 v[138:139], v[134:135], s[78:79], v[138:139] op_sel_hi:[1,0,1]
	v_pk_fma_f32 v[136:137], v[132:133], s[78:79], v[136:137] op_sel_hi:[1,0,1]
	global_store_dwordx4 v[218:219], v[136:139], off
	s_nop 1
	v_sub_f32_e32 v137, v197, v204
	v_sub_f32_e32 v136, v196, v204
	v_sub_f32_e32 v139, v199, v204
	v_sub_f32_e32 v138, v198, v204
	v_pk_mul_f32 v[138:139], v[204:205], v[138:139] op_sel:[1,0]
	v_pk_mul_f32 v[136:137], v[204:205], v[136:137] op_sel:[1,0]
	v_pk_fma_f32 v[138:139], v[148:149], v[138:139], v[106:107]
	v_pk_fma_f32 v[136:137], v[150:151], v[136:137], v[104:105]
	v_add_u32_e32 v196, 0x10010, v194
	v_mov_b32_e32 v197, v159
	v_pk_fma_f32 v[138:139], v[130:131], s[78:79], v[138:139] op_sel_hi:[1,0,1]
	v_pk_fma_f32 v[136:137], v[128:129], s[78:79], v[136:137] op_sel_hi:[1,0,1]
	v_lshl_add_u64 v[196:197], v[196:197], 2, s[90:91]
	global_store_dwordx4 v[196:197], v[136:139], off
	v_add_u32_e32 v196, 0x18000, v194
	v_mov_b32_e32 v197, v159
	v_sub_f32_e32 v137, v209, v216
	v_sub_f32_e32 v136, v208, v216
	v_sub_f32_e32 v139, v211, v216
	v_sub_f32_e32 v138, v210, v216
	v_pk_mul_f32 v[138:139], v[216:217], v[138:139] op_sel:[1,0]
	v_pk_mul_f32 v[136:137], v[216:217], v[136:137] op_sel:[1,0]
	v_pk_fma_f32 v[138:139], v[152:153], v[138:139], v[102:103]
	v_pk_fma_f32 v[136:137], v[154:155], v[136:137], v[100:101]
	v_pk_fma_f32 v[138:139], v[134:135], s[78:79], v[138:139] op_sel_hi:[1,0,1]
	v_pk_fma_f32 v[136:137], v[132:133], s[78:79], v[136:137] op_sel_hi:[1,0,1]
	v_lshl_add_u64 v[196:197], v[196:197], 2, s[90:91]
	global_store_dwordx4 v[196:197], v[136:139], off
	v_add_u32_e32 v196, 0x18010, v194
	v_mov_b32_e32 v197, v159
	v_sub_f32_e32 v137, v213, v216
	v_sub_f32_e32 v136, v212, v216
	v_sub_f32_e32 v139, v215, v216
	v_sub_f32_e32 v138, v214, v216
	v_pk_mul_f32 v[138:139], v[216:217], v[138:139] op_sel:[1,0]
	v_pk_mul_f32 v[136:137], v[216:217], v[136:137] op_sel:[1,0]
	v_pk_fma_f32 v[138:139], v[148:149], v[138:139], v[98:99]
	v_pk_fma_f32 v[136:137], v[150:151], v[136:137], v[96:97]
	v_pk_fma_f32 v[138:139], v[130:131], s[78:79], v[138:139] op_sel_hi:[1,0,1]
	v_pk_fma_f32 v[136:137], v[128:129], s[78:79], v[136:137] op_sel_hi:[1,0,1]
	v_lshl_add_u64 v[196:197], v[196:197], 2, s[90:91]
	global_store_dwordx4 v[196:197], v[136:139], off
	s_nop 1
	v_add_u32_e32 v138, 0x80, v206
	v_lshlrev_b32_e32 v136, 1, v138
	v_mov_b32_e32 v137, v159
	v_lshlrev_b32_e32 v233, 11, v138
	v_lshl_add_u64 v[196:197], v[136:137], 2, s[2:3]
	v_add_u32_e32 v136, v233, v158
	v_lshl_add_u64 v[136:137], v[136:137], 2, s[88:89]
	global_load_dwordx2 v[204:205], v[196:197], off
	v_add_u32_e32 v198, v233, v231
	global_load_dwordx4 v[136:139], v[136:137], off
	v_mov_b32_e32 v199, v159
	v_add_u32_e32 v207, 0x90, v206
	v_lshl_add_u64 v[198:199], v[198:199], 2, s[88:89]
	v_lshlrev_b32_e32 v234, 11, v207
	global_load_dwordx4 v[208:211], v[198:199], off
	v_add_u32_e32 v212, v234, v158
	v_mov_b32_e32 v213, v159
	v_lshl_add_u64 v[212:213], v[212:213], 2, s[88:89]
	global_load_dwordx4 v[212:215], v[212:213], off
	v_lshlrev_b32_e32 v198, 1, v207
	v_mov_b32_e32 v199, v159
	v_lshl_add_u64 v[198:199], v[198:199], 2, s[2:3]
	global_load_dwordx2 v[220:221], v[198:199], off
	v_add_u32_e32 v216, v234, v231
	v_mov_b32_e32 v217, v159
	v_lshl_add_u64 v[216:217], v[216:217], 2, s[88:89]
	global_load_dwordx4 v[216:219], v[216:217], off
	v_add_u32_e32 v238, 0x40000, v194
	v_mov_b32_e32 v239, v159
	v_lshl_add_u64 v[238:239], v[238:239], 2, s[90:91]
	s_waitcnt vmcnt(0)
;     template <bool LN, int BJ, int LO, int HI> DI void batch(const f32x4 (&acc)[2][2][4][2], unsigned row0, unsigned col0, const f32x4 (&gv)[2], const f32x4 (&bv)[2]) const {
;         f32x4 r[HI - LO]; float mean[(HI - LO) / 2], rstd[(HI - LO) / 2];
; #pragma unroll
;         for (int i = LO; i < HI; ++i) { const int ai = i >> 3, m = (i >> 1) & 3, n = i & 1; const unsigned row = row0 + ai * HALF + m * 16;
;             if (n == 0) { mean[(i - LO) >> 1] = 0.f; rstd[(i - LO) >> 1] = 1.f;
;                 if (LN) { const float2 st = *(const float2*)(stats + row * 2u); mean[(i - LO) >> 1] = st.x; rstd[(i - LO) >> 1] = st.y; } }
;             r[i - LO] = *(const f32x4*)(src + (row * (unsigned)DM + col0 + BJ * HALF + n * 16)); }
; #pragma unroll
;         for (int i = LO; i < HI; ++i) { const int ai = i >> 3, m = (i >> 1) & 3, n = i & 1; const unsigned row = row0 + ai * HALF + m * 16;
;             *(f32x4*)(Y + (row * (unsigned)DM + col0 + BJ * HALF + n * 16)) = acc[ai][BJ][m][n] + ((r[i - LO] - mean[(i - LO) >> 1]) * rstd[(i - LO) >> 1]) * gv[n] + bv[n]; }
	v_sub_f32_e32 v137, v137, v204
	v_sub_f32_e32 v136, v136, v204
	v_sub_f32_e32 v139, v139, v204
	v_sub_f32_e32 v138, v138, v204
	v_pk_mul_f32 v[138:139], v[204:205], v[138:139] op_sel:[1,0]
	v_pk_mul_f32 v[136:137], v[204:205], v[136:137] op_sel:[1,0]
	v_pk_fma_f32 v[138:139], v[152:153], v[138:139], v[94:95]
	v_pk_fma_f32 v[136:137], v[154:155], v[136:137], v[92:93]
	v_pk_fma_f32 v[138:139], v[134:135], s[78:79], v[138:139] op_sel_hi:[1,0,1]
	v_pk_fma_f32 v[136:137], v[132:133], s[78:79], v[136:137] op_sel_hi:[1,0,1]
	global_store_dwordx4 v[238:239], v[136:139], off
	s_nop 1
	v_sub_f32_e32 v137, v209, v204
	v_sub_f32_e32 v136, v208, v204
	v_sub_f32_e32 v139, v211, v204
	v_sub_f32_e32 v138, v210, v204
	v_pk_mul_f32 v[138:139], v[204:205], v[138:139] op_sel:[1,0]
	v_pk_mul_f32 v[136:137], v[204:205], v[136:137] op_sel:[1,0]
	v_pk_fma_f32 v[138:139], v[148:149], v[138:139], v[90:91]
	v_pk_fma_f32 v[136:137], v[150:151], v[136:137], v[88:89]
	v_add_u32_e32 v204, 0x40010, v194
	v_mov_b32_e32 v205, v159
	v_pk_fma_f32 v[138:139], v[130:131], s[78:79], v[138:139] op_sel_hi:[1,0,1]
	v_pk_fma_f32 v[136:137], v[128:129], s[78:79], v[136:137] op_sel_hi:[1,0,1]
	v_lshl_add_u64 v[204:205], v[204:205], 2, s[90:91]
	global_store_dwordx4 v[204:205], v[136:139], off
	v_add_u32_e32 v204, 0x48000, v194
	v_mov_b32_e32 v205, v159
	v_sub_f32_e32 v137, v213, v220
	v_sub_f32_e32 v136, v212, v220
	v_sub_f32_e32 v139, v215, v220
	v_sub_f32_e32 v138, v214, v220
	v_pk_mul_f32 v[138:139], v[220:221], v[138:139] op_sel:[1,0]
	v_pk_mul_f32 v[136:137], v[220:221], v[136:137] op_sel:[1,0]
	v_pk_fma_f32 v[138:139], v[152:153], v[138:139], v[86:87]
	v_pk_fma_f32 v[136:137], v[154:155], v[136:137], v[84:85]
	v_pk_fma_f32 v[138:139], v[134:135], s[78:79], v[138:139] op_sel_hi:[1,0,1]
	v_pk_fma_f32 v[136:137], v[132:133], s[78:79], v[136:137] op_sel_hi:[1,0,1]
	v_lshl_add_u64 v[204:205], v[204:205], 2, s[90:91]
	global_store_dwordx4 v[204:205], v[136:139], off
	v_add_u32_e32 v204, 0x48010, v194
	v_mov_b32_e32 v205, v159
	v_sub_f32_e32 v137, v217, v220
	v_sub_f32_e32 v136, v216, v220
	v_sub_f32_e32 v139, v219, v220
	v_sub_f32_e32 v138, v218, v220
	v_pk_mul_f32 v[138:139], v[220:221], v[138:139] op_sel:[1,0]
	v_pk_mul_f32 v[136:137], v[220:221], v[136:137] op_sel:[1,0]
	v_pk_fma_f32 v[138:139], v[148:149], v[138:139], v[82:83]
	v_pk_fma_f32 v[136:137], v[150:151], v[136:137], v[80:81]
	v_pk_fma_f32 v[138:139], v[130:131], s[78:79], v[138:139] op_sel_hi:[1,0,1]
	v_pk_fma_f32 v[136:137], v[128:129], s[78:79], v[136:137] op_sel_hi:[1,0,1]
	v_lshl_add_u64 v[204:205], v[204:205], 2, s[90:91]
	global_store_dwordx4 v[204:205], v[136:139], off
	s_nop 1
	v_add_u32_e32 v138, 0xa0, v206
	v_lshlrev_b32_e32 v136, 1, v138
	v_mov_b32_e32 v137, v159
	v_lshlrev_b32_e32 v237, 11, v138
	v_lshl_add_u64 v[204:205], v[136:137], 2, s[2:3]
	v_add_u32_e32 v136, v237, v158
	v_lshl_add_u64 v[136:137], v[136:137], 2, s[88:89]
	global_load_dwordx2 v[220:221], v[204:205], off
	v_add_u32_e32 v208, v237, v231
	global_load_dwordx4 v[136:139], v[136:137], off
	v_mov_b32_e32 v209, v159
	v_lshl_add_u64 v[208:209], v[208:209], 2, s[88:89]
	global_load_dwordx4 v[212:215], v[208:209], off
	v_add_u32_e32 v208, 0xb0, v206
	v_lshlrev_b32_e32 v206, 1, v208
	v_mov_b32_e32 v207, v159
	v_lshlrev_b32_e32 v238, 11, v208
	v_lshl_add_u64 v[210:211], v[206:207], 2, s[2:3]
	v_add_u32_e32 v206, v238, v158
	v_lshl_add_u64 v[206:207], v[206:207], 2, s[88:89]
	global_load_dwordx2 v[240:241], v[210:211], off
	v_add_u32_e32 v216, v238, v231
	global_load_dwordx4 v[206:209], v[206:207], off
	v_mov_b32_e32 v217, v159
	v_lshl_add_u64 v[216:217], v[216:217], 2, s[88:89]
	global_load_dwordx4 v[216:219], v[216:217], off
	v_add_u32_e32 v242, 0x50000, v194
	v_mov_b32_e32 v243, v159
	v_lshl_add_u64 v[242:243], v[242:243], 2, s[90:91]
	s_waitcnt vmcnt(0)
	v_sub_f32_e32 v137, v137, v220
	v_sub_f32_e32 v136, v136, v220
	v_sub_f32_e32 v139, v139, v220
	v_sub_f32_e32 v138, v138, v220
	v_pk_mul_f32 v[138:139], v[220:221], v[138:139] op_sel:[1,0]
	v_pk_mul_f32 v[136:137], v[220:221], v[136:137] op_sel:[1,0]
	v_pk_fma_f32 v[138:139], v[152:153], v[138:139], v[78:79]
	v_pk_fma_f32 v[136:137], v[154:155], v[136:137], v[76:77]
	v_pk_fma_f32 v[138:139], v[134:135], s[78:79], v[138:139] op_sel_hi:[1,0,1]
	v_pk_fma_f32 v[136:137], v[132:133], s[78:79], v[136:137] op_sel_hi:[1,0,1]
	global_store_dwordx4 v[242:243], v[136:139], off
	s_nop 1
	v_sub_f32_e32 v137, v213, v220
	v_sub_f32_e32 v136, v212, v220
	v_sub_f32_e32 v139, v215, v220
	v_sub_f32_e32 v138, v214, v220
	v_pk_mul_f32 v[138:139], v[220:221], v[138:139] op_sel:[1,0]
	v_pk_mul_f32 v[136:137], v[220:221], v[136:137] op_sel:[1,0]
	v_pk_fma_f32 v[138:139], v[148:149], v[138:139], v[74:75]
	v_pk_fma_f32 v[136:137], v[150:151], v[136:137], v[72:73]
	v_add_u32_e32 v212, 0x50010, v194
	v_mov_b32_e32 v213, v159
	v_pk_fma_f32 v[138:139], v[130:131], s[78:79], v[138:139] op_sel_hi:[1,0,1]
	v_pk_fma_f32 v[136:137], v[128:129], s[78:79], v[136:137] op_sel_hi:[1,0,1]
	v_lshl_add_u64 v[212:213], v[212:213], 2, s[90:91]
	global_store_dwordx4 v[212:213], v[136:139], off
	s_nop 1
	v_sub_f32_e32 v137, v207, v240
	v_sub_f32_e32 v136, v206, v240
	v_sub_f32_e32 v139, v209, v240
	v_sub_f32_e32 v138, v208, v240
	v_pk_mul_f32 v[136:137], v[240:241], v[136:137] op_sel:[1,0]
	v_pk_mul_f32 v[138:139], v[240:241], v[138:139] op_sel:[1,0]
	v_pk_fma_f32 v[136:137], v[154:155], v[136:137], v[68:69]
	v_pk_fma_f32 v[138:139], v[152:153], v[138:139], v[70:71]
	v_pk_fma_f32 v[132:133], v[132:133], s[78:79], v[136:137] op_sel_hi:[1,0,1]
	v_add_u32_e32 v136, 0x58000, v194
	v_mov_b32_e32 v137, v159
	v_pk_fma_f32 v[134:135], v[134:135], s[78:79], v[138:139] op_sel_hi:[1,0,1]
	v_lshl_add_u64 v[136:137], v[136:137], 2, s[90:91]
	global_store_dwordx4 v[136:137], v[132:135], off
	s_nop 1
	v_sub_f32_e32 v133, v217, v240
	v_sub_f32_e32 v132, v216, v240
	v_sub_f32_e32 v135, v219, v240
	v_sub_f32_e32 v134, v218, v240
	v_pk_mul_f32 v[132:133], v[240:241], v[132:133] op_sel:[1,0]
	v_pk_mul_f32 v[134:135], v[240:241], v[134:135] op_sel:[1,0]
	v_pk_fma_f32 v[132:133], v[150:151], v[132:133], v[64:65]
	v_pk_fma_f32 v[134:135], v[148:149], v[134:135], v[66:67]
	v_pk_fma_f32 v[128:129], v[128:129], s[78:79], v[132:133] op_sel_hi:[1,0,1]
	v_add_u32_e32 v132, 0x58010, v194
	v_mov_b32_e32 v133, v159
	v_pk_fma_f32 v[130:131], v[130:131], s[78:79], v[134:135] op_sel_hi:[1,0,1]
	v_lshl_add_u64 v[132:133], v[132:133], 2, s[90:91]
	global_store_dwordx4 v[132:133], v[128:131], off
	global_load_dwordx4 v[128:131], v[140:141], off offset:512
	v_add_u32_e32 v136, v232, v230
	v_mov_b32_e32 v137, v159
	v_lshl_add_u64 v[136:137], v[136:137], 2, s[88:89]
	s_waitcnt vmcnt(0)
;     template <bool LN, int BJ, int LO, int HI> DI void batch(const f32x4 (&acc)[2][2][4][2], unsigned row0, unsigned col0, const f32x4 (&gv)[2], const f32x4 (&bv)[2]) const {
;         f32x4 r[HI - LO]; float mean[(HI - LO) / 2], rstd[(HI - LO) / 2];
; #pragma unroll
;         for (int i = LO; i < HI; ++i) { const int ai = i >> 3, m = (i >> 1) & 3, n = i & 1; const unsigned row = row0 + ai * HALF + m * 16;
;             if (n == 0) { mean[(i - LO) >> 1] = 0.f; rstd[(i - LO) >> 1] = 1.f;
;                 if (LN) { const float2 st = *(const float2*)(stats + row * 2u); mean[(i - LO) >> 1] = st.x; rstd[(i - LO) >> 1] = st.y; } }
;             r[i - LO] = *(const f32x4*)(src + (row * (unsigned)DM + col0 + BJ * HALF + n * 16)); }
; #pragma unroll
;         for (int i = LO; i < HI; ++i) { const int ai = i >> 3, m = (i >> 1) & 3, n = i & 1; const unsigned row = row0 + ai * HALF + m * 16;
;             *(f32x4*)(Y + (row * (unsigned)DM + col0 + BJ * HALF + n * 16)) = acc[ai][BJ][m][n] + ((r[i - LO] - mean[(i - LO) >> 1]) * rstd[(i - LO) >> 1]) * gv[n] + bv[n]; }
;     template <bool LN, int BJ> DI void load_gb(unsigned col0, f32x4 (&gv)[2], f32x4 (&bv)[2]) const {
; #pragma unroll
;         for (int n = 0; n < 2; ++n) {
;             if (LN) { gv[n] = *(const f32x4*)(gam + col0 + BJ * HALF + n * 16) * ALPHA; bv[n] = *(const f32x4*)(bet + col0 + BJ * HALF + n * 16) * ALPHA; }
;             else { gv[n] = (f32x4){ALPHA, ALPHA, ALPHA, ALPHA}; bv[n] = (f32x4){0.f, 0.f, 0.f, 0.f}; }
;         }
;     }
;     template <bool LN> DI void run(const f32x4 (&acc)[2][2][4][2], const Unit& u, int wr, int wc, int fr, int fq) const {
;         const unsigned row0 = u.pm * BM + wr * 64 + fr, col0 = u.pn * BM + wc * 32 + 4 * fq;
;         f32x4 gv[2], bv[2];
;         load_gb<LN, 0>(col0, gv, bv);
;         batch<LN, 0, 0, 4>(acc, row0, col0, gv, bv);
;         batch<LN, 0, 4, 8>(acc, row0, col0, gv, bv);
;         batch<LN, 0, 8, 12>(acc, row0, col0, gv, bv);
;         batch<LN, 0, 12, 16>(acc, row0, col0, gv, bv);
;         load_gb<LN, 1>(col0, gv, bv);
	v_pk_mul_f32 v[212:213], v[130:131], s[78:79] op_sel_hi:[1,0]
	v_pk_mul_f32 v[214:215], v[128:129], s[78:79] op_sel_hi:[1,0]
	global_load_dwordx4 v[132:135], v[142:143], off offset:512
	global_load_dwordx4 v[128:131], v[140:141], off offset:576
	s_waitcnt vmcnt(0)
	v_pk_mul_f32 v[206:207], v[130:131], s[78:79] op_sel_hi:[1,0]
	v_pk_mul_f32 v[208:209], v[128:129], s[78:79] op_sel_hi:[1,0]
	global_load_dwordx4 v[128:131], v[142:143], off offset:576
	global_load_dwordx2 v[220:221], v[144:145], off
	global_load_dwordx4 v[240:243], v[136:137], off
	v_add_u32_e32 v136, v232, v229
	v_mov_b32_e32 v137, v159
	v_lshl_add_u64 v[136:137], v[136:137], 2, s[88:89]
	global_load_dwordx4 v[244:247], v[136:137], off
	global_load_dwordx2 v[218:219], v[146:147], off
	v_add_u32_e32 v136, v195, v230
	v_mov_b32_e32 v137, v159
	v_lshl_add_u64 v[136:137], v[136:137], 2, s[88:89]
	global_load_dwordx4 v[248:251], v[136:137], off
	v_add_u32_e32 v136, v195, v229
	v_mov_b32_e32 v137, v159
	v_lshl_add_u64 v[136:137], v[136:137], 2, s[88:89]
	global_load_dwordx4 v[152:155], v[136:137], off
	global_load_dwordx2 v[216:217], v[200:201], off
	v_add_u32_e32 v136, v236, v230
	v_mov_b32_e32 v137, v159
	v_lshl_add_u64 v[136:137], v[136:137], 2, s[88:89]
	global_load_dwordx4 v[148:151], v[136:137], off
	v_add_u32_e32 v136, v236, v229
	v_mov_b32_e32 v137, v159
	v_lshl_add_u64 v[136:137], v[136:137], 2, s[88:89]
	global_load_dwordx4 v[144:147], v[136:137], off
	global_load_dwordx2 v[200:201], v[202:203], off
	v_add_u32_e32 v136, v235, v230
	v_mov_b32_e32 v137, v159
	v_lshl_add_u64 v[136:137], v[136:137], 2, s[88:89]
	global_load_dwordx4 v[140:143], v[136:137], off
	v_add_u32_e32 v136, v235, v229
	v_mov_b32_e32 v137, v159
	v_lshl_add_u64 v[136:137], v[136:137], 2, s[88:89]
	global_load_dwordx4 v[136:139], v[136:137], off
	v_add_u32_e32 v202, 0x80, v194
	v_mov_b32_e32 v203, v159
	v_lshl_add_u64 v[202:203], v[202:203], 2, s[90:91]
	s_waitcnt vmcnt(0)
	v_sub_f32_e32 v241, v241, v220
	v_sub_f32_e32 v240, v240, v220
	v_sub_f32_e32 v243, v243, v220
	v_sub_f32_e32 v242, v242, v220
	v_pk_mul_f32 v[242:243], v[220:221], v[242:243] op_sel:[1,0]
	v_pk_mul_f32 v[240:241], v[220:221], v[240:241] op_sel:[1,0]
	v_pk_fma_f32 v[242:243], v[212:213], v[242:243], v[62:63]
	v_pk_fma_f32 v[240:241], v[214:215], v[240:241], v[60:61]
	v_pk_fma_f32 v[242:243], v[134:135], s[78:79], v[242:243] op_sel_hi:[1,0,1]
	v_pk_fma_f32 v[240:241], v[132:133], s[78:79], v[240:241] op_sel_hi:[1,0,1]
	global_store_dwordx4 v[202:203], v[240:243], off
	v_sub_f32_e32 v203, v245, v220
	v_sub_f32_e32 v202, v244, v220
	v_sub_f32_e32 v241, v247, v220
	v_sub_f32_e32 v240, v246, v220
	v_pk_mul_f32 v[202:203], v[220:221], v[202:203] op_sel:[1,0]
	v_pk_mul_f32 v[240:241], v[220:221], v[240:241] op_sel:[1,0]
	v_pk_fma_f32 v[202:203], v[208:209], v[202:203], v[56:57]
	v_pk_fma_f32 v[220:221], v[206:207], v[240:241], v[58:59]
	v_pk_fma_f32 v[240:241], v[128:129], s[78:79], v[202:203] op_sel_hi:[1,0,1]
	v_add_u32_e32 v202, 0x90, v194
	v_mov_b32_e32 v203, v159
	v_pk_fma_f32 v[242:243], v[130:131], s[78:79], v[220:221] op_sel_hi:[1,0,1]
	v_lshl_add_u64 v[202:203], v[202:203], 2, s[90:91]
	global_store_dwordx4 v[202:203], v[240:243], off
	v_sub_f32_e32 v203, v249, v218
	v_sub_f32_e32 v202, v248, v218
	v_sub_f32_e32 v221, v251, v218
	v_sub_f32_e32 v220, v250, v218
	v_pk_mul_f32 v[202:203], v[218:219], v[202:203] op_sel:[1,0]
	v_pk_mul_f32 v[220:221], v[218:219], v[220:221] op_sel:[1,0]
	v_pk_fma_f32 v[202:203], v[214:215], v[202:203], v[52:53]
	v_pk_fma_f32 v[220:221], v[212:213], v[220:221], v[54:55]
	v_pk_fma_f32 v[240:241], v[132:133], s[78:79], v[202:203] op_sel_hi:[1,0,1]
	v_add_u32_e32 v202, 0x8080, v194
	v_mov_b32_e32 v203, v159
	v_sub_f32_e32 v153, v153, v218
	v_sub_f32_e32 v152, v152, v218
	v_sub_f32_e32 v155, v155, v218
	v_sub_f32_e32 v154, v154, v218
	v_pk_fma_f32 v[242:243], v[134:135], s[78:79], v[220:221] op_sel_hi:[1,0,1]
	v_lshl_add_u64 v[202:203], v[202:203], 2, s[90:91]
	v_pk_mul_f32 v[154:155], v[218:219], v[154:155] op_sel:[1,0]
	v_pk_mul_f32 v[152:153], v[218:219], v[152:153] op_sel:[1,0]
	global_store_dwordx4 v[202:203], v[240:243], off
	v_pk_fma_f32 v[152:153], v[208:209], v[152:153], v[48:49]
	v_pk_fma_f32 v[154:155], v[206:207], v[154:155], v[50:51]
	v_add_u32_e32 v202, 0x8090, v194
	v_mov_b32_e32 v203, v159
	v_sub_f32_e32 v149, v149, v216
	v_sub_f32_e32 v148, v148, v216
	v_sub_f32_e32 v151, v151, v216
	v_sub_f32_e32 v150, v150, v216
	v_pk_fma_f32 v[154:155], v[130:131], s[78:79], v[154:155] op_sel_hi:[1,0,1]
	v_pk_fma_f32 v[152:153], v[128:129], s[78:79], v[152:153] op_sel_hi:[1,0,1]
	v_lshl_add_u64 v[202:203], v[202:203], 2, s[90:91]
	v_pk_mul_f32 v[150:151], v[216:217], v[150:151] op_sel:[1,0]
	v_pk_mul_f32 v[148:149], v[216:217], v[148:149] op_sel:[1,0]
	global_store_dwordx4 v[202:203], v[152:155], off
	v_pk_fma_f32 v[148:149], v[214:215], v[148:149], v[44:45]
	v_pk_fma_f32 v[150:151], v[212:213], v[150:151], v[46:47]
	v_add_u32_e32 v152, 0x10080, v194
	v_mov_b32_e32 v153, v159
	v_sub_f32_e32 v145, v145, v216
	v_sub_f32_e32 v144, v144, v216
	v_sub_f32_e32 v147, v147, v216
	v_sub_f32_e32 v146, v146, v216
	v_pk_fma_f32 v[150:151], v[134:135], s[78:79], v[150:151] op_sel_hi:[1,0,1]
	v_pk_fma_f32 v[148:149], v[132:133], s[78:79], v[148:149] op_sel_hi:[1,0,1]
	v_lshl_add_u64 v[152:153], v[152:153], 2, s[90:91]
	v_pk_mul_f32 v[146:147], v[216:217], v[146:147] op_sel:[1,0]
	v_pk_mul_f32 v[144:145], v[216:217], v[144:145] op_sel:[1,0]
	global_store_dwordx4 v[152:153], v[148:151], off
	v_pk_fma_f32 v[144:145], v[208:209], v[144:145], v[40:41]
	v_pk_fma_f32 v[146:147], v[206:207], v[146:147], v[42:43]
;     template <bool LN, int BJ, int LO, int HI> DI void batch(const f32x4 (&acc)[2][2][4][2], unsigned row0, unsigned col0, const f32x4 (&gv)[2], const f32x4 (&bv)[2]) const {
;         f32x4 r[HI - LO]; float mean[(HI - LO) / 2], rstd[(HI - LO) / 2];
; #pragma unroll
;         for (int i = LO; i < HI; ++i) { const int ai = i >> 3, m = (i >> 1) & 3, n = i & 1; const unsigned row = row0 + ai * HALF + m * 16;
;             if (n == 0) { mean[(i - LO) >> 1] = 0.f; rstd[(i - LO) >> 1] = 1.f;
;                 if (LN) { const float2 st = *(const float2*)(stats + row * 2u); mean[(i - LO) >> 1] = st.x; rstd[(i - LO) >> 1] = st.y; } }
;             r[i - LO] = *(const f32x4*)(src + (row * (unsigned)DM + col0 + BJ * HALF + n * 16)); }
; #pragma unroll
;         for (int i = LO; i < HI; ++i) { const int ai = i >> 3, m = (i >> 1) & 3, n = i & 1; const unsigned row = row0 + ai * HALF + m * 16;
;             *(f32x4*)(Y + (row * (unsigned)DM + col0 + BJ * HALF + n * 16)) = acc[ai][BJ][m][n] + ((r[i - LO] - mean[(i - LO) >> 1]) * rstd[(i - LO) >> 1]) * gv[n] + bv[n]; }
	v_add_u32_e32 v148, 0x10090, v194
	v_mov_b32_e32 v149, v159
	v_sub_f32_e32 v141, v141, v200
	v_sub_f32_e32 v140, v140, v200
	v_sub_f32_e32 v143, v143, v200
	v_sub_f32_e32 v142, v142, v200
	v_pk_fma_f32 v[146:147], v[130:131], s[78:79], v[146:147] op_sel_hi:[1,0,1]
	v_pk_fma_f32 v[144:145], v[128:129], s[78:79], v[144:145] op_sel_hi:[1,0,1]
	v_lshl_add_u64 v[148:149], v[148:149], 2, s[90:91]
	v_pk_mul_f32 v[142:143], v[200:201], v[142:143] op_sel:[1,0]
	v_pk_mul_f32 v[140:141], v[200:201], v[140:141] op_sel:[1,0]
	global_store_dwordx4 v[148:149], v[144:147], off
	v_pk_fma_f32 v[140:141], v[214:215], v[140:141], v[36:37]
	v_pk_fma_f32 v[142:143], v[212:213], v[142:143], v[38:39]
	v_add_u32_e32 v144, 0x18080, v194
	v_mov_b32_e32 v145, v159
	v_sub_f32_e32 v137, v137, v200
	v_sub_f32_e32 v136, v136, v200
	v_sub_f32_e32 v139, v139, v200
	v_sub_f32_e32 v138, v138, v200
	v_pk_fma_f32 v[142:143], v[134:135], s[78:79], v[142:143] op_sel_hi:[1,0,1]
	v_pk_fma_f32 v[140:141], v[132:133], s[78:79], v[140:141] op_sel_hi:[1,0,1]
	v_lshl_add_u64 v[144:145], v[144:145], 2, s[90:91]
	v_pk_mul_f32 v[138:139], v[200:201], v[138:139] op_sel:[1,0]
	v_pk_mul_f32 v[136:137], v[200:201], v[136:137] op_sel:[1,0]
	global_store_dwordx4 v[144:145], v[140:143], off
	v_pk_fma_f32 v[136:137], v[208:209], v[136:137], v[32:33]
	v_pk_fma_f32 v[138:139], v[206:207], v[138:139], v[34:35]
	v_add_u32_e32 v140, 0x18090, v194
	v_mov_b32_e32 v141, v159
	v_pk_fma_f32 v[138:139], v[130:131], s[78:79], v[138:139] op_sel_hi:[1,0,1]
	v_pk_fma_f32 v[136:137], v[128:129], s[78:79], v[136:137] op_sel_hi:[1,0,1]
	v_lshl_add_u64 v[140:141], v[140:141], 2, s[90:91]
	global_store_dwordx4 v[140:141], v[136:139], off
	s_nop 1
	v_add_u32_e32 v136, v233, v230
	v_mov_b32_e32 v137, v159
	v_lshl_add_u64 v[136:137], v[136:137], 2, s[88:89]
	global_load_dwordx2 v[220:221], v[196:197], off
	global_load_dwordx4 v[216:219], v[136:137], off
	v_add_u32_e32 v136, v233, v229
	v_mov_b32_e32 v137, v159
	v_lshl_add_u64 v[136:137], v[136:137], 2, s[88:89]
	global_load_dwordx4 v[240:243], v[136:137], off
	global_load_dwordx2 v[200:201], v[198:199], off
	v_add_u32_e32 v136, v234, v230
	v_mov_b32_e32 v137, v159
	v_lshl_add_u64 v[136:137], v[136:137], 2, s[88:89]
	global_load_dwordx4 v[244:247], v[136:137], off
	v_add_u32_e32 v136, v234, v229
	v_mov_b32_e32 v137, v159
	v_lshl_add_u64 v[136:137], v[136:137], 2, s[88:89]
	global_load_dwordx4 v[152:155], v[136:137], off
	global_load_dwordx2 v[198:199], v[204:205], off
	v_add_u32_e32 v136, v237, v230
	v_mov_b32_e32 v137, v159
	v_lshl_add_u64 v[136:137], v[136:137], 2, s[88:89]
	global_load_dwordx4 v[148:151], v[136:137], off
	v_add_u32_e32 v136, v237, v229
	v_mov_b32_e32 v137, v159
	v_lshl_add_u64 v[136:137], v[136:137], 2, s[88:89]
	global_load_dwordx4 v[144:147], v[136:137], off
	global_load_dwordx2 v[196:197], v[210:211], off
	v_add_u32_e32 v136, v238, v230
	v_mov_b32_e32 v137, v159
	v_lshl_add_u64 v[136:137], v[136:137], 2, s[88:89]
	global_load_dwordx4 v[140:143], v[136:137], off
	v_add_u32_e32 v136, v238, v229
	v_mov_b32_e32 v137, v159
	v_lshl_add_u64 v[136:137], v[136:137], 2, s[88:89]
	global_load_dwordx4 v[136:139], v[136:137], off
	v_add_u32_e32 v210, 0x40080, v194
	v_mov_b32_e32 v211, v159
	v_lshl_add_u64 v[210:211], v[210:211], 2, s[90:91]
	s_waitcnt vmcnt(0)
;     template <bool LN, int BJ, int LO, int HI> DI void batch(const f32x4 (&acc)[2][2][4][2], unsigned row0, unsigned col0, const f32x4 (&gv)[2], const f32x4 (&bv)[2]) const {
;         f32x4 r[HI - LO]; float mean[(HI - LO) / 2], rstd[(HI - LO) / 2];
; #pragma unroll
;         for (int i = LO; i < HI; ++i) { const int ai = i >> 3, m = (i >> 1) & 3, n = i & 1; const unsigned row = row0 + ai * HALF + m * 16;
;             if (n == 0) { mean[(i - LO) >> 1] = 0.f; rstd[(i - LO) >> 1] = 1.f;
;                 if (LN) { const float2 st = *(const float2*)(stats + row * 2u); mean[(i - LO) >> 1] = st.x; rstd[(i - LO) >> 1] = st.y; } }
;             r[i - LO] = *(const f32x4*)(src + (row * (unsigned)DM + col0 + BJ * HALF + n * 16)); }
; #pragma unroll
;         for (int i = LO; i < HI; ++i) { const int ai = i >> 3, m = (i >> 1) & 3, n = i & 1; const unsigned row = row0 + ai * HALF + m * 16;
;             *(f32x4*)(Y + (row * (unsigned)DM + col0 + BJ * HALF + n * 16)) = acc[ai][BJ][m][n] + ((r[i - LO] - mean[(i - LO) >> 1]) * rstd[(i - LO) >> 1]) * gv[n] + bv[n]; }
	v_sub_f32_e32 v203, v217, v220
	v_sub_f32_e32 v202, v216, v220
	v_sub_f32_e32 v205, v219, v220
	v_sub_f32_e32 v204, v218, v220
	v_pk_mul_f32 v[204:205], v[220:221], v[204:205] op_sel:[1,0]
	v_pk_mul_f32 v[202:203], v[220:221], v[202:203] op_sel:[1,0]
	v_pk_fma_f32 v[204:205], v[212:213], v[204:205], v[30:31]
	v_pk_fma_f32 v[202:203], v[214:215], v[202:203], v[28:29]
	v_pk_fma_f32 v[204:205], v[134:135], s[78:79], v[204:205] op_sel_hi:[1,0,1]
	v_pk_fma_f32 v[202:203], v[132:133], s[78:79], v[202:203] op_sel_hi:[1,0,1]
	global_store_dwordx4 v[210:211], v[202:205], off
	v_add_u32_e32 v210, 0x40090, v194
	v_mov_b32_e32 v211, v159
	v_sub_f32_e32 v203, v241, v220
	v_sub_f32_e32 v202, v240, v220
	v_sub_f32_e32 v205, v243, v220
	v_sub_f32_e32 v204, v242, v220
	v_pk_mul_f32 v[204:205], v[220:221], v[204:205] op_sel:[1,0]
	v_pk_mul_f32 v[202:203], v[220:221], v[202:203] op_sel:[1,0]
	v_pk_fma_f32 v[204:205], v[206:207], v[204:205], v[26:27]
	v_pk_fma_f32 v[202:203], v[208:209], v[202:203], v[24:25]
	v_pk_fma_f32 v[204:205], v[130:131], s[78:79], v[204:205] op_sel_hi:[1,0,1]
	v_pk_fma_f32 v[202:203], v[128:129], s[78:79], v[202:203] op_sel_hi:[1,0,1]
	v_lshl_add_u64 v[210:211], v[210:211], 2, s[90:91]
	global_store_dwordx4 v[210:211], v[202:205], off
	v_sub_f32_e32 v149, v149, v198
	v_sub_f32_e32 v148, v148, v198
	v_sub_f32_e32 v203, v245, v200
	v_sub_f32_e32 v202, v244, v200
	v_sub_f32_e32 v141, v141, v196
	v_sub_f32_e32 v140, v140, v196
	v_sub_f32_e32 v205, v247, v200
	v_sub_f32_e32 v204, v246, v200
	v_pk_mul_f32 v[202:203], v[200:201], v[202:203] op_sel:[1,0]
	v_sub_f32_e32 v151, v151, v198
	v_sub_f32_e32 v150, v150, v198
	v_pk_mul_f32 v[148:149], v[198:199], v[148:149] op_sel:[1,0]
	v_sub_f32_e32 v143, v143, v196
	v_sub_f32_e32 v142, v142, v196
	v_pk_mul_f32 v[140:141], v[196:197], v[140:141] op_sel:[1,0]
	v_pk_mul_f32 v[204:205], v[200:201], v[204:205] op_sel:[1,0]
	v_pk_fma_f32 v[202:203], v[214:215], v[202:203], v[20:21]
	v_sub_f32_e32 v153, v153, v200
	v_sub_f32_e32 v152, v152, v200
	v_sub_f32_e32 v155, v155, v200
	v_sub_f32_e32 v154, v154, v200
	v_pk_mul_f32 v[150:151], v[198:199], v[150:151] op_sel:[1,0]
	v_pk_fma_f32 v[148:149], v[214:215], v[148:149], v[12:13]
	v_pk_mul_f32 v[142:143], v[196:197], v[142:143] op_sel:[1,0]
	v_pk_fma_f32 v[140:141], v[214:215], v[140:141], v[4:5]
	v_pk_fma_f32 v[204:205], v[212:213], v[204:205], v[22:23]
	v_pk_fma_f32 v[202:203], v[132:133], s[78:79], v[202:203] op_sel_hi:[1,0,1]
	v_pk_mul_f32 v[154:155], v[200:201], v[154:155] op_sel:[1,0]
	v_pk_mul_f32 v[152:153], v[200:201], v[152:153] op_sel:[1,0]
	v_pk_fma_f32 v[150:151], v[212:213], v[150:151], v[14:15]
	v_pk_fma_f32 v[148:149], v[132:133], s[78:79], v[148:149] op_sel_hi:[1,0,1]
	v_pk_fma_f32 v[142:143], v[212:213], v[142:143], v[6:7]
	v_pk_fma_f32 v[132:133], v[132:133], s[78:79], v[140:141] op_sel_hi:[1,0,1]
	v_add_u32_e32 v140, 0x58080, v194
	v_mov_b32_e32 v141, v159
	v_pk_fma_f32 v[204:205], v[134:135], s[78:79], v[204:205] op_sel_hi:[1,0,1]
	v_pk_fma_f32 v[152:153], v[208:209], v[152:153], v[16:17]
	v_pk_fma_f32 v[154:155], v[206:207], v[154:155], v[18:19]
	v_add_u32_e32 v200, 0x48090, v194
	v_mov_b32_e32 v201, v159
	v_pk_fma_f32 v[150:151], v[134:135], s[78:79], v[150:151] op_sel_hi:[1,0,1]
	v_pk_fma_f32 v[134:135], v[134:135], s[78:79], v[142:143] op_sel_hi:[1,0,1]
	v_lshl_add_u64 v[140:141], v[140:141], 2, s[90:91]
	v_pk_fma_f32 v[154:155], v[130:131], s[78:79], v[154:155] op_sel_hi:[1,0,1]
	v_pk_fma_f32 v[152:153], v[128:129], s[78:79], v[152:153] op_sel_hi:[1,0,1]
	v_lshl_add_u64 v[200:201], v[200:201], 2, s[90:91]
	v_sub_f32_e32 v145, v145, v198
	v_sub_f32_e32 v144, v144, v198
	global_store_dwordx4 v[140:141], v[132:135], off
	global_store_dwordx4 v[200:201], v[152:155], off
	v_sub_f32_e32 v147, v147, v198
	v_sub_f32_e32 v133, v137, v196
	v_sub_f32_e32 v132, v136, v196
	v_add_u32_e32 v152, 0x50080, v194
	v_mov_b32_e32 v153, v159
	v_sub_f32_e32 v146, v146, v198
	v_pk_mul_f32 v[144:145], v[198:199], v[144:145] op_sel:[1,0]
	v_sub_f32_e32 v135, v139, v196
	v_sub_f32_e32 v134, v138, v196
	v_pk_mul_f32 v[132:133], v[196:197], v[132:133] op_sel:[1,0]
	v_lshl_add_u64 v[152:153], v[152:153], 2, s[90:91]
	v_pk_mul_f32 v[146:147], v[198:199], v[146:147] op_sel:[1,0]
	v_pk_fma_f32 v[144:145], v[208:209], v[144:145], v[8:9]
	v_pk_mul_f32 v[134:135], v[196:197], v[134:135] op_sel:[1,0]
	v_pk_fma_f32 v[132:133], v[208:209], v[132:133], v[0:1]
	v_add_u32_e32 v210, 0x48080, v194
	v_mov_b32_e32 v211, v159
	global_store_dwordx4 v[152:153], v[148:151], off
	v_pk_fma_f32 v[146:147], v[206:207], v[146:147], v[10:11]
	v_pk_fma_f32 v[144:145], v[128:129], s[78:79], v[144:145] op_sel_hi:[1,0,1]
	v_add_u32_e32 v148, 0x50090, v194
	v_mov_b32_e32 v149, v159
	v_pk_fma_f32 v[134:135], v[206:207], v[134:135], v[2:3]
	v_pk_fma_f32 v[128:129], v[128:129], s[78:79], v[132:133] op_sel_hi:[1,0,1]
	v_add_u32_e32 v132, 0x58090, v194
	v_mov_b32_e32 v133, v159
	v_lshl_add_u64 v[210:211], v[210:211], 2, s[90:91]
	v_pk_fma_f32 v[146:147], v[130:131], s[78:79], v[146:147] op_sel_hi:[1,0,1]
	v_lshl_add_u64 v[148:149], v[148:149], 2, s[90:91]
	v_pk_fma_f32 v[130:131], v[130:131], s[78:79], v[134:135] op_sel_hi:[1,0,1]
	v_lshl_add_u64 v[132:133], v[132:133], 2, s[90:91]
	global_store_dwordx4 v[210:211], v[202:205], off
	global_store_dwordx4 v[148:149], v[144:147], off
	global_store_dwordx4 v[132:133], v[128:131], off
	s_mov_b64 s[20:21], 0
	s_branch .LBB0_81

; #define PG8_STAGE(bufoff, gbase) do { _Pragma("unroll") for (int _i = 0; _i < 2; ++_i) \
;         __builtin_amdgcn_global_load_lds((const unsigned*)((const char*)(gbase) + voff[_i]), (LAS unsigned*)(lds + (bufoff) + ldsw + _i * 8192), 16, 0, 0); } while (0)
; #define PG8_LDA(dst, b, h) do { _Pragma("unroll") for (int m = 0; m < 4; ++m) _Pragma("unroll") for (int k = 0; k < 2; ++k) dst[m][k] = *(const LAS bf16x8*)(lds + PG8_SA(b, h) + aoff + m * 2048 + k * 1024); } while (0)
; #define PG8_LDB(dst, b, h) do { _Pragma("unroll") for (int n = 0; n < 2; ++n) _Pragma("unroll") for (int k = 0; k < 2; ++k) dst[n][k] = *(const LAS bf16x8*)(lds + PG8_SB(b, h) + boff + n * 2048 + k * 1024); } while (0)
; #define PG8_MMA(ai, bj, At, Bt) do { __builtin_amdgcn_s_setprio(1); _Pragma("unroll") for (int m = 0; m < 4; ++m) _Pragma("unroll") for (int n = 0; n < 2; ++n) _Pragma("unroll") for (int k = 0; k < 2; ++k) \
;         acc[ai][bj][m][n] = __builtin_amdgcn_mfma_f32_16x16x32_bf16(Bt[n][k], At[m][k], acc[ai][bj][m][n], 0, 0, 0); __builtin_amdgcn_s_setprio(0); } while (0)
; #define PG8_WAIT_V(n) asm volatile("s_waitcnt vmcnt(" #n ")" ::: "memory")
; #define PG8_WAIT_L(n) asm volatile("s_waitcnt lgkmcnt(" #n ")" ::: "memory")
; #define PG8_BAR __builtin_amdgcn_s_barrier()
; #define PG8_SCHED __builtin_amdgcn_sched_barrier(0)
; template <class Epi>
; DI void gemm_phase(LAS unsigned char* lds, const Gemm g, const StaticOrder& S, const Epi& E) {
;     ...
;             const bool last = (t == nt - 2);
;             const char* a1 = cA + (size_t)(t + 1) * kstep;
;             const char* a2 = last ? nA : cA + (size_t)(t + 2) * kstep; const char* b2 = last ? nB : cB + (size_t)(t + 2) * kstep;
;             const char* a3 = a2 + kstep; const char* b3 = b2 + kstep;
;             PG8_LDB(B0, 0, 0); PG8_SCHED; PG8_LDA(At, 0, 0); PG8_STAGE(PG8_SA(1, 1), a1 + hstep);
;             PG8_WAIT_L(8); PG8_BAR; PG8_WAIT_L(0); PG8_MMA(0, 0, At, B0); PG8_BAR; PG8_SCHED;
;             PG8_LDB(B1, 0, 1); PG8_STAGE(PG8_SB(0, 0), b2);
;             PG8_BAR; PG8_WAIT_L(0); PG8_MMA(0, 1, At, B1); PG8_BAR;
;             PG8_LDA(At, 0, 1); PG8_STAGE(PG8_SA(0, 0), a2);
;             PG8_BAR; PG8_WAIT_L(0); PG8_MMA(1, 0, At, B0); PG8_BAR; PG8_SCHED;
;             PG8_STAGE(PG8_SB(0, 1), b2 + hstep);
;             PG8_WAIT_V(6); PG8_BAR; PG8_MMA(1, 1, At, B1); PG8_BAR;
.LBB0_134:
	ds_read_b128 v[96:99], v199
	ds_read_b128 v[100:103], v199 offset:1024
	ds_read_b128 v[136:139], v199 offset:2048
	ds_read_b128 v[148:151], v199 offset:3072
	ds_read_b128 v[152:155], v201
	ds_read_b128 v[186:189], v201 offset:1024
	ds_read_b128 v[190:193], v201 offset:2048
	ds_read_b128 v[194:197], v201 offset:3072
	ds_read_b128 v[202:205], v201 offset:4096
	ds_read_b128 v[206:209], v201 offset:5120
	ds_read_b128 v[210:213], v201 offset:6144
	ds_read_b128 v[214:217], v201 offset:7168
	s_add_u32 s18, s16, 0x100
	s_addc_u32 s19, s17, 0
	s_add_i32 s39, 0, 0x10000
	s_cmpk_eq_i32 s33, 0x54
	s_cselect_b32 s23, s9, s19
	s_cselect_b32 s22, s8, s18
	s_cselect_b32 s21, s11, s5
	s_cselect_b32 s20, s10, s4
	s_add_i32 m0, s28, 0xc000
	s_nop 0
	global_load_lds_dwordx4 v144, s[16:17]
	s_add_i32 m0, s28, 0xe000
	s_nop 0
	global_load_lds_dwordx4 v146, s[16:17]
	s_waitcnt lgkmcnt(8)
	s_setprio 1
	s_barrier
	s_waitcnt lgkmcnt(0)
	v_mfma_f32_16x16x32_bf16 v[132:135], v[96:99], v[152:155], v[132:135]
	v_mfma_f32_16x16x32_bf16 v[128:131], v[136:139], v[152:155], v[128:131]
	v_mfma_f32_16x16x32_bf16 v[124:127], v[96:99], v[190:193], v[124:127]
	v_mfma_f32_16x16x32_bf16 v[120:123], v[136:139], v[190:193], v[120:123]
	v_mfma_f32_16x16x32_bf16 v[116:119], v[96:99], v[202:205], v[116:119]
	v_mfma_f32_16x16x32_bf16 v[112:115], v[136:139], v[202:205], v[112:115]
	v_mfma_f32_16x16x32_bf16 v[108:111], v[96:99], v[210:213], v[108:111]
	v_mfma_f32_16x16x32_bf16 v[104:107], v[136:139], v[210:213], v[104:107]
	v_mfma_f32_16x16x32_bf16 v[132:135], v[100:103], v[186:189], v[132:135]
	v_mfma_f32_16x16x32_bf16 v[128:131], v[148:151], v[186:189], v[128:131]
	ds_read_b128 v[226:229], v199 offset:16384
	v_mfma_f32_16x16x32_bf16 v[124:127], v[100:103], v[194:197], v[124:127]
	ds_read_b128 v[230:233], v199 offset:17408
	v_mfma_f32_16x16x32_bf16 v[120:123], v[148:151], v[194:197], v[120:123]
	ds_read_b128 v[234:237], v199 offset:18432
	v_mfma_f32_16x16x32_bf16 v[116:119], v[100:103], v[206:209], v[116:119]
	ds_read_b128 v[238:241], v199 offset:19456
	v_mfma_f32_16x16x32_bf16 v[112:115], v[148:151], v[206:209], v[112:115]
	v_mfma_f32_16x16x32_bf16 v[108:111], v[100:103], v[214:217], v[108:111]
	s_setprio 0
	v_mfma_f32_16x16x32_bf16 v[104:107], v[148:151], v[214:217], v[104:107]
	s_barrier
	s_add_i32 s40, 0, 0x14000
	s_add_i32 s16, s39, s27
	s_mov_b32 m0, s16
	s_nop 0
	global_load_lds_dwordx4 v142, s[20:21]
	s_add_i32 m0, s16, 0x2000
	s_nop 0
	global_load_lds_dwordx4 v140, s[20:21]
	s_waitcnt lgkmcnt(0)
	s_setprio 1
	s_barrier
	v_mfma_f32_16x16x32_bf16 v[60:63], v[226:229], v[152:155], v[60:63]
	v_mfma_f32_16x16x32_bf16 v[56:59], v[234:237], v[152:155], v[56:59]
	v_mfma_f32_16x16x32_bf16 v[52:55], v[226:229], v[190:193], v[52:55]
	v_mfma_f32_16x16x32_bf16 v[48:51], v[234:237], v[190:193], v[48:51]
	v_mfma_f32_16x16x32_bf16 v[44:47], v[226:229], v[202:205], v[44:47]
	v_mfma_f32_16x16x32_bf16 v[40:43], v[234:237], v[202:205], v[40:43]
	v_mfma_f32_16x16x32_bf16 v[36:39], v[226:229], v[210:213], v[36:39]
	v_mfma_f32_16x16x32_bf16 v[32:35], v[234:237], v[210:213], v[32:35]
	v_mfma_f32_16x16x32_bf16 v[60:63], v[230:233], v[186:189], v[60:63]
	ds_read_b128 v[152:155], v201 offset:16384
	s_mov_b32 m0, s28
	v_mfma_f32_16x16x32_bf16 v[56:59], v[238:241], v[186:189], v[56:59]
	ds_read_b128 v[186:189], v201 offset:17408
	v_mfma_f32_16x16x32_bf16 v[52:55], v[230:233], v[194:197], v[52:55]
	ds_read_b128 v[190:193], v201 offset:18432
	v_mfma_f32_16x16x32_bf16 v[48:51], v[238:241], v[194:197], v[48:51]
	ds_read_b128 v[194:197], v201 offset:19456
	v_mfma_f32_16x16x32_bf16 v[44:47], v[230:233], v[206:209], v[44:47]
	ds_read_b128 v[202:205], v201 offset:20480
	v_mfma_f32_16x16x32_bf16 v[40:43], v[238:241], v[206:209], v[40:43]
	ds_read_b128 v[206:209], v201 offset:21504
	v_mfma_f32_16x16x32_bf16 v[36:39], v[230:233], v[214:217], v[36:39]
	ds_read_b128 v[210:213], v201 offset:22528
	s_setprio 0
	v_mfma_f32_16x16x32_bf16 v[32:35], v[238:241], v[214:217], v[32:35]
	s_barrier
	ds_read_b128 v[214:217], v201 offset:23552
	global_load_lds_dwordx4 v142, s[22:23]
	s_mov_b64 s[100:101], s[22:23]
	s_mov_b32 m0, s29
	s_nop 0
	global_load_lds_dwordx4 v140, s[22:23]
	s_waitcnt lgkmcnt(0)
	s_setprio 1
	s_barrier
	v_mfma_f32_16x16x32_bf16 v[92:95], v[96:99], v[152:155], v[92:95]
	v_mfma_f32_16x16x32_bf16 v[88:91], v[136:139], v[152:155], v[88:91]
	v_mfma_f32_16x16x32_bf16 v[84:87], v[96:99], v[190:193], v[84:87]
	v_mfma_f32_16x16x32_bf16 v[80:83], v[136:139], v[190:193], v[80:83]
	v_mfma_f32_16x16x32_bf16 v[76:79], v[96:99], v[202:205], v[76:79]
	v_mfma_f32_16x16x32_bf16 v[72:75], v[136:139], v[202:205], v[72:75]
	v_mfma_f32_16x16x32_bf16 v[68:71], v[96:99], v[210:213], v[68:71]
	v_mfma_f32_16x16x32_bf16 v[64:67], v[136:139], v[210:213], v[64:67]
	v_mfma_f32_16x16x32_bf16 v[92:95], v[100:103], v[186:189], v[92:95]
	v_mfma_f32_16x16x32_bf16 v[88:91], v[148:151], v[186:189], v[88:91]
	v_mfma_f32_16x16x32_bf16 v[84:87], v[100:103], v[194:197], v[84:87]
	v_mfma_f32_16x16x32_bf16 v[80:83], v[148:151], v[194:197], v[80:83]
	v_mfma_f32_16x16x32_bf16 v[76:79], v[100:103], v[206:209], v[76:79]
	v_mfma_f32_16x16x32_bf16 v[72:75], v[148:151], v[206:209], v[72:75]
	v_mfma_f32_16x16x32_bf16 v[68:71], v[100:103], v[214:217], v[68:71]
	s_setprio 0
	v_mfma_f32_16x16x32_bf16 v[64:67], v[148:151], v[214:217], v[64:67]
	s_barrier
	s_add_u32 s16, s20, 0x160000
	s_addc_u32 s17, s21, 0
	s_add_i32 s39, s40, s27
	s_mov_b32 m0, s39
	s_nop 0
	global_load_lds_dwordx4 v142, s[16:17]
	s_add_i32 m0, s39, 0x2000
	s_nop 0
	global_load_lds_dwordx4 v140, s[16:17]
	s_waitcnt vmcnt(6)
	s_setprio 1
	s_barrier
; #define PG8_STAGE(bufoff, gbase) do { _Pragma("unroll") for (int _i = 0; _i < 2; ++_i) \
;         __builtin_amdgcn_global_load_lds((const unsigned*)((const char*)(gbase) + voff[_i]), (LAS unsigned*)(lds + (bufoff) + ldsw + _i * 8192), 16, 0, 0); } while (0)
; #define PG8_LDA(dst, b, h) do { _Pragma("unroll") for (int m = 0; m < 4; ++m) _Pragma("unroll") for (int k = 0; k < 2; ++k) dst[m][k] = *(const LAS bf16x8*)(lds + PG8_SA(b, h) + aoff + m * 2048 + k * 1024); } while (0)
; #define PG8_LDB(dst, b, h) do { _Pragma("unroll") for (int n = 0; n < 2; ++n) _Pragma("unroll") for (int k = 0; k < 2; ++k) dst[n][k] = *(const LAS bf16x8*)(lds + PG8_SB(b, h) + boff + n * 2048 + k * 1024); } while (0)
; #define PG8_MMA(ai, bj, At, Bt) do { __builtin_amdgcn_s_setprio(1); _Pragma("unroll") for (int m = 0; m < 4; ++m) _Pragma("unroll") for (int n = 0; n < 2; ++n) _Pragma("unroll") for (int k = 0; k < 2; ++k) \
;         acc[ai][bj][m][n] = __builtin_amdgcn_mfma_f32_16x16x32_bf16(Bt[n][k], At[m][k], acc[ai][bj][m][n], 0, 0, 0); __builtin_amdgcn_s_setprio(0); } while (0)
; #define PG8_WAIT_V(n) asm volatile("s_waitcnt vmcnt(" #n ")" ::: "memory")
; #define PG8_WAIT_L(n) asm volatile("s_waitcnt lgkmcnt(" #n ")" ::: "memory")
; #define PG8_BAR __builtin_amdgcn_s_barrier()
; #define PG8_SCHED __builtin_amdgcn_sched_barrier(0)
; template <class Epi>
; DI void gemm_phase(LAS unsigned char* lds, const Gemm g, const StaticOrder& S, const Epi& E) {
;     ...
;             PG8_WAIT_V(6); PG8_BAR; PG8_MMA(1, 1, At, B1); PG8_BAR;
;             PG8_LDB(B0, 1, 0); PG8_SCHED; PG8_LDA(At, 1, 0); PG8_STAGE(PG8_SA(0, 1), a2 + hstep);
;             PG8_WAIT_L(8); PG8_BAR; PG8_WAIT_L(0); PG8_MMA(0, 0, At, B0); PG8_BAR; PG8_SCHED;
;             PG8_LDB(B1, 1, 1); PG8_STAGE(PG8_SB(1, 0), b3);
;             PG8_BAR; PG8_WAIT_L(0); PG8_MMA(0, 1, At, B1); PG8_BAR;
;             PG8_LDA(At, 1, 1); PG8_STAGE(PG8_SA(1, 0), a3);
;             PG8_BAR; PG8_WAIT_L(0); PG8_MMA(1, 0, At, B0); PG8_BAR; PG8_SCHED;
	v_mfma_f32_16x16x32_bf16 v[28:31], v[226:229], v[152:155], v[28:31]
	v_mfma_f32_16x16x32_bf16 v[24:27], v[234:237], v[152:155], v[24:27]
	v_mfma_f32_16x16x32_bf16 v[20:23], v[226:229], v[190:193], v[20:23]
	v_mfma_f32_16x16x32_bf16 v[16:19], v[234:237], v[190:193], v[16:19]
	v_mfma_f32_16x16x32_bf16 v[12:15], v[226:229], v[202:205], v[12:15]
	v_mfma_f32_16x16x32_bf16 v[8:11], v[234:237], v[202:205], v[8:11]
	v_mfma_f32_16x16x32_bf16 v[4:7], v[226:229], v[210:213], v[4:7]
	v_mfma_f32_16x16x32_bf16 v[0:3], v[234:237], v[210:213], v[0:3]
	v_mfma_f32_16x16x32_bf16 v[28:31], v[230:233], v[186:189], v[28:31]
	s_add_i32 s39, 0, 0x18000
	v_mfma_f32_16x16x32_bf16 v[24:27], v[238:241], v[186:189], v[24:27]
	v_mfma_f32_16x16x32_bf16 v[20:23], v[230:233], v[194:197], v[20:23]
	v_mfma_f32_16x16x32_bf16 v[16:19], v[238:241], v[194:197], v[16:19]
	v_mfma_f32_16x16x32_bf16 v[12:15], v[230:233], v[206:209], v[12:15]
	v_mfma_f32_16x16x32_bf16 v[8:11], v[238:241], v[206:209], v[8:11]
	v_mfma_f32_16x16x32_bf16 v[4:7], v[230:233], v[214:217], v[4:7]
	s_setprio 0
	v_mfma_f32_16x16x32_bf16 v[0:3], v[238:241], v[214:217], v[0:3]
	s_barrier
	ds_read_b128 v[96:99], v199 offset:32768
	ds_read_b128 v[100:103], v199 offset:33792
	ds_read_b128 v[136:139], v199 offset:34816
	ds_read_b128 v[148:151], v199 offset:35840
	ds_read_b128 v[152:155], v201 offset:32768
	ds_read_b128 v[186:189], v201 offset:33792
	ds_read_b128 v[190:193], v201 offset:34816
	ds_read_b128 v[194:197], v201 offset:35840
	ds_read_b128 v[202:205], v201 offset:36864
	ds_read_b128 v[206:209], v201 offset:37888
	ds_read_b128 v[210:213], v201 offset:38912
	ds_read_b128 v[214:217], v201 offset:39936
	s_add_u32 s16, s22, 0x160000
	s_addc_u32 s17, s23, 0
	s_mov_b32 m0, s30
	s_nop 0
	global_load_lds_dwordx4 v142, s[16:17]
	s_mov_b32 m0, s31
	s_nop 0
	global_load_lds_dwordx4 v140, s[16:17]
	s_waitcnt lgkmcnt(8)
	s_setprio 1
	s_barrier
	s_waitcnt lgkmcnt(0)
	v_mfma_f32_16x16x32_bf16 v[132:135], v[96:99], v[152:155], v[132:135]
	v_mfma_f32_16x16x32_bf16 v[128:131], v[136:139], v[152:155], v[128:131]
	v_mfma_f32_16x16x32_bf16 v[124:127], v[96:99], v[190:193], v[124:127]
	v_mfma_f32_16x16x32_bf16 v[120:123], v[136:139], v[190:193], v[120:123]
	v_mfma_f32_16x16x32_bf16 v[116:119], v[96:99], v[202:205], v[116:119]
	v_mfma_f32_16x16x32_bf16 v[112:115], v[136:139], v[202:205], v[112:115]
	v_mfma_f32_16x16x32_bf16 v[108:111], v[96:99], v[210:213], v[108:111]
	v_mfma_f32_16x16x32_bf16 v[104:107], v[136:139], v[210:213], v[104:107]
	v_mfma_f32_16x16x32_bf16 v[132:135], v[100:103], v[186:189], v[132:135]
	v_mfma_f32_16x16x32_bf16 v[128:131], v[148:151], v[186:189], v[128:131]
	ds_read_b128 v[226:229], v199 offset:49152
	v_mfma_f32_16x16x32_bf16 v[124:127], v[100:103], v[194:197], v[124:127]
	ds_read_b128 v[230:233], v199 offset:50176
	v_mfma_f32_16x16x32_bf16 v[120:123], v[148:151], v[194:197], v[120:123]
	ds_read_b128 v[234:237], v199 offset:51200
	v_mfma_f32_16x16x32_bf16 v[116:119], v[100:103], v[206:209], v[116:119]
	ds_read_b128 v[238:241], v199 offset:52224
	v_mfma_f32_16x16x32_bf16 v[112:115], v[148:151], v[206:209], v[112:115]
	v_mfma_f32_16x16x32_bf16 v[108:111], v[100:103], v[214:217], v[108:111]
	s_setprio 0
	v_mfma_f32_16x16x32_bf16 v[104:107], v[148:151], v[214:217], v[104:107]
	s_barrier
	s_add_i32 s22, 0, 0x1c000
	s_add_i32 s16, s39, s27
	s_add_i32 m0, s16, 0xffffff80
	s_nop 0
	global_load_lds_dwordx4 v142, s[20:21] offset:128
	s_add_i32 m0, s16, 0x1f80
	s_nop 0
	global_load_lds_dwordx4 v140, s[20:21] offset:128
	s_waitcnt lgkmcnt(0)
	s_setprio 1
	s_barrier
	v_mfma_f32_16x16x32_bf16 v[60:63], v[226:229], v[152:155], v[60:63]
	v_mfma_f32_16x16x32_bf16 v[56:59], v[234:237], v[152:155], v[56:59]
	v_mfma_f32_16x16x32_bf16 v[52:55], v[226:229], v[190:193], v[52:55]
	v_mfma_f32_16x16x32_bf16 v[48:51], v[234:237], v[190:193], v[48:51]
	v_mfma_f32_16x16x32_bf16 v[44:47], v[226:229], v[202:205], v[44:47]
	v_mfma_f32_16x16x32_bf16 v[40:43], v[234:237], v[202:205], v[40:43]
	v_mfma_f32_16x16x32_bf16 v[36:39], v[226:229], v[210:213], v[36:39]
	v_mfma_f32_16x16x32_bf16 v[32:35], v[234:237], v[210:213], v[32:35]
	v_mfma_f32_16x16x32_bf16 v[60:63], v[230:233], v[186:189], v[60:63]
	ds_read_b128 v[152:155], v201 offset:49152
	s_add_i32 m0, s34, 0xffffff80
	v_mfma_f32_16x16x32_bf16 v[56:59], v[238:241], v[186:189], v[56:59]
	ds_read_b128 v[186:189], v201 offset:50176
	v_mfma_f32_16x16x32_bf16 v[52:55], v[230:233], v[194:197], v[52:55]
	ds_read_b128 v[190:193], v201 offset:51200
	v_mfma_f32_16x16x32_bf16 v[48:51], v[238:241], v[194:197], v[48:51]
	ds_read_b128 v[194:197], v201 offset:52224
	v_mfma_f32_16x16x32_bf16 v[44:47], v[230:233], v[206:209], v[44:47]
	ds_read_b128 v[202:205], v201 offset:53248
	v_mfma_f32_16x16x32_bf16 v[40:43], v[238:241], v[206:209], v[40:43]
	ds_read_b128 v[206:209], v201 offset:54272
	v_mfma_f32_16x16x32_bf16 v[36:39], v[230:233], v[214:217], v[36:39]
	ds_read_b128 v[210:213], v201 offset:55296
	s_setprio 0
	v_mfma_f32_16x16x32_bf16 v[32:35], v[238:241], v[214:217], v[32:35]
	s_barrier
	ds_read_b128 v[214:217], v201 offset:56320
	global_load_lds_dwordx4 v142, s[100:101] offset:128
	s_add_i32 m0, s35, 0xffffff80
	s_nop 0
	global_load_lds_dwordx4 v140, s[100:101] offset:128
	s_waitcnt lgkmcnt(0)
	s_setprio 1
	s_barrier
; #define PG8_WAIT_V(n) asm volatile("s_waitcnt vmcnt(" #n ")" ::: "memory")
; #define PG8_WAIT_L(n) asm volatile("s_waitcnt lgkmcnt(" #n ")" ::: "memory")
; template <class Epi>
; DI void gemm_phase(LAS unsigned char* lds, const Gemm g, const StaticOrder& S, const Epi& E) {
;     ...
;             PG8_BAR; PG8_WAIT_L(0); PG8_MMA(1, 0, At, B0); PG8_BAR; PG8_SCHED;
;             PG8_STAGE(PG8_SB(1, 1), b3 + hstep);
;             PG8_WAIT_V(6); PG8_BAR; PG8_MMA(1, 1, At, B1); PG8_BAR;
;     template <bool LN, int BJ, int LO, int HI> DI void batch(const f32x4 (&acc)[2][2][4][2], unsigned row0, unsigned col0, const f32x4 (&gv)[2], const f32x4 (&bv)[2]) const {
;         f32x4 r[HI - LO]; float mean[(HI - LO) / 2], rstd[(HI - LO) / 2];
; #pragma unroll
;         for (int i = LO; i < HI; ++i) { const int ai = i >> 3, m = (i >> 1) & 3, n = i & 1; const unsigned row = row0 + ai * HALF + m * 16;
;             if (n == 0) { mean[(i - LO) >> 1] = 0.f; rstd[(i - LO) >> 1] = 1.f;
;                 if (LN) { const float2 st = *(const float2*)(stats + row * 2u); mean[(i - LO) >> 1] = st.x; rstd[(i - LO) >> 1] = st.y; } }
;             r[i - LO] = *(const f32x4*)(src + (row * (unsigned)DM + col0 + BJ * HALF + n * 16)); }
; #pragma unroll
;         for (int i = LO; i < HI; ++i) { const int ai = i >> 3, m = (i >> 1) & 3, n = i & 1; const unsigned row = row0 + ai * HALF + m * 16;
;             *(f32x4*)(Y + (row * (unsigned)DM + col0 + BJ * HALF + n * 16)) = acc[ai][BJ][m][n] + ((r[i - LO] - mean[(i - LO) >> 1]) * rstd[(i - LO) >> 1]) * gv[n] + bv[n]; }
;         __builtin_amdgcn_sched_barrier(0);
;     }
;     template <bool LN, int BJ> DI void load_gb(unsigned col0, f32x4 (&gv)[2], f32x4 (&bv)[2]) const {
; #pragma unroll
;         for (int n = 0; n < 2; ++n) {
;             if (LN) { gv[n] = *(const f32x4*)(gam + col0 + BJ * HALF + n * 16) * ALPHA; bv[n] = *(const f32x4*)(bet + col0 + BJ * HALF + n * 16) * ALPHA; }
;             else { gv[n] = (f32x4){ALPHA, ALPHA, ALPHA, ALPHA}; bv[n] = (f32x4){0.f, 0.f, 0.f, 0.f}; }
;         }
;     }
;     template <bool LN> DI void run(const f32x4 (&acc)[2][2][4][2], const Unit& u, int wr, int wc, int fr, int fq) const {
;         const unsigned row0 = u.pm * BM + wr * 64 + fr, col0 = u.pn * BM + wc * 32 + 4 * fq;
;         f32x4 gv[2], bv[2];
;         load_gb<LN, 0>(col0, gv, bv);
;         batch<LN, 0, 0, 4>(acc, row0, col0, gv, bv);
	v_mfma_f32_16x16x32_bf16 v[92:95], v[96:99], v[152:155], v[92:95]
	v_mfma_f32_16x16x32_bf16 v[88:91], v[136:139], v[152:155], v[88:91]
	v_mfma_f32_16x16x32_bf16 v[84:87], v[96:99], v[190:193], v[84:87]
	v_mfma_f32_16x16x32_bf16 v[80:83], v[136:139], v[190:193], v[80:83]
	v_mfma_f32_16x16x32_bf16 v[76:79], v[96:99], v[202:205], v[76:79]
	v_mfma_f32_16x16x32_bf16 v[72:75], v[136:139], v[202:205], v[72:75]
	v_mfma_f32_16x16x32_bf16 v[68:71], v[96:99], v[210:213], v[68:71]
	v_mfma_f32_16x16x32_bf16 v[64:67], v[136:139], v[210:213], v[64:67]
	v_mfma_f32_16x16x32_bf16 v[92:95], v[100:103], v[186:189], v[92:95]
	v_mfma_f32_16x16x32_bf16 v[88:91], v[148:151], v[186:189], v[88:91]
	v_mfma_f32_16x16x32_bf16 v[84:87], v[100:103], v[194:197], v[84:87]
	v_mfma_f32_16x16x32_bf16 v[80:83], v[148:151], v[194:197], v[80:83]
	v_mfma_f32_16x16x32_bf16 v[76:79], v[100:103], v[206:209], v[76:79]
	v_mfma_f32_16x16x32_bf16 v[72:75], v[148:151], v[206:209], v[72:75]
	v_mfma_f32_16x16x32_bf16 v[68:71], v[100:103], v[214:217], v[68:71]
	s_setprio 0
	v_mfma_f32_16x16x32_bf16 v[64:67], v[148:151], v[214:217], v[64:67]
	s_barrier
	s_add_u32 s16, s20, 0x160080
	s_addc_u32 s17, s21, 0
	s_add_i32 s20, s22, s27
	s_mov_b32 m0, s20
	s_nop 0
	global_load_lds_dwordx4 v142, s[16:17]
	s_add_i32 m0, s20, 0x2000
	s_nop 0
	global_load_lds_dwordx4 v140, s[16:17]
	s_waitcnt vmcnt(6)
	s_setprio 1
	s_barrier
	v_mfma_f32_16x16x32_bf16 v[28:31], v[226:229], v[152:155], v[28:31]
	v_mfma_f32_16x16x32_bf16 v[24:27], v[234:237], v[152:155], v[24:27]
	v_mfma_f32_16x16x32_bf16 v[20:23], v[226:229], v[190:193], v[20:23]
	v_mfma_f32_16x16x32_bf16 v[16:19], v[234:237], v[190:193], v[16:19]
	v_mfma_f32_16x16x32_bf16 v[12:15], v[226:229], v[202:205], v[12:15]
	v_mfma_f32_16x16x32_bf16 v[8:11], v[234:237], v[202:205], v[8:11]
	v_mfma_f32_16x16x32_bf16 v[4:7], v[226:229], v[210:213], v[4:7]
	v_mfma_f32_16x16x32_bf16 v[0:3], v[234:237], v[210:213], v[0:3]
	v_mfma_f32_16x16x32_bf16 v[28:31], v[230:233], v[186:189], v[28:31]
	s_add_i32 s33, s33, 2
	v_mfma_f32_16x16x32_bf16 v[24:27], v[238:241], v[186:189], v[24:27]
	s_add_u32 s4, s4, 0x100
	v_mfma_f32_16x16x32_bf16 v[20:23], v[230:233], v[194:197], v[20:23]
	s_addc_u32 s5, s5, 0
	v_mfma_f32_16x16x32_bf16 v[16:19], v[238:241], v[194:197], v[16:19]
	s_cmpk_gt_u32 s33, 0x55
	v_mfma_f32_16x16x32_bf16 v[12:15], v[230:233], v[206:209], v[12:15]
	s_mov_b64 s[16:17], s[18:19]
	v_mfma_f32_16x16x32_bf16 v[8:11], v[238:241], v[206:209], v[8:11]
	v_mfma_f32_16x16x32_bf16 v[4:7], v[230:233], v[214:217], v[4:7]
	s_setprio 0
	v_mfma_f32_16x16x32_bf16 v[0:3], v[238:241], v[214:217], v[0:3]
	s_barrier
	s_cbranch_scc0 .LBB0_134
	v_lshl_or_b32 v158, s2, 8, v200
	v_lshlrev_b64 v[100:101], 2, v[158:159]
	v_lshl_add_u64 v[150:151], s[12:13], 0, v[100:101]
	global_load_dwordx4 v[96:99], v[150:151], off
	v_lshl_add_u64 v[152:153], s[14:15], 0, v[100:101]
	v_lshl_add_u32 v203, s3, 8, v198
	v_lshlrev_b32_e32 v202, 11, v203
	v_add_u32_e32 v148, v202, v158
	v_mov_b32_e32 v149, v159
	v_lshlrev_b32_e32 v136, 1, v203
	v_mov_b32_e32 v137, v159
	v_lshlrev_b64 v[220:221], 2, v[148:149]
	v_lshl_add_u64 v[154:155], v[136:137], 2, s[96:97]
	v_lshl_add_u64 v[136:137], s[90:91], 0, v[220:221]
	v_or_b32_e32 v204, 16, v158
	v_or_b32_e32 v138, 16, v203
	v_lshlrev_b32_e32 v149, 11, v138
	s_waitcnt vmcnt(0)
	v_pk_mul_f32 v[192:193], v[98:99], s[78:79] op_sel_hi:[1,0]
	v_pk_mul_f32 v[194:195], v[96:97], s[78:79] op_sel_hi:[1,0]
	global_load_dwordx4 v[100:103], v[152:153], off
	global_load_dwordx4 v[96:99], v[150:151], off offset:64
	global_load_dwordx2 v[218:219], v[154:155], off
	global_load_dwordx4 v[206:209], v[136:137], off
	v_add_u32_e32 v136, v202, v204
	v_mov_b32_e32 v137, v159
	v_lshl_add_u64 v[136:137], v[136:137], 2, s[90:91]
	global_load_dwordx4 v[210:213], v[136:137], off
	v_lshlrev_b32_e32 v136, 1, v138
	v_mov_b32_e32 v137, v159
	v_lshl_add_u64 v[186:187], v[136:137], 2, s[96:97]
	v_add_u32_e32 v136, v149, v158
	v_lshl_add_u64 v[136:137], v[136:137], 2, s[90:91]
	global_load_dwordx2 v[196:197], v[186:187], off
	global_load_dwordx4 v[214:217], v[136:137], off
	v_add_u32_e32 v136, v149, v204
	v_mov_b32_e32 v137, v159
	v_lshl_add_u64 v[136:137], v[136:137], 2, s[90:91]
	global_load_dwordx4 v[136:139], v[136:137], off
	s_waitcnt vmcnt(0)
	v_pk_mul_f32 v[188:189], v[98:99], s[78:79] op_sel_hi:[1,0]
	v_pk_mul_f32 v[190:191], v[96:97], s[78:79] op_sel_hi:[1,0]
	global_load_dwordx4 v[96:99], v[152:153], off offset:64
	v_sub_f32_e32 v207, v207, v218
	v_sub_f32_e32 v206, v206, v218
	v_sub_f32_e32 v209, v209, v218
	v_sub_f32_e32 v208, v208, v218
	v_pk_mul_f32 v[208:209], v[218:219], v[208:209] op_sel:[1,0]
	v_pk_mul_f32 v[206:207], v[218:219], v[206:207] op_sel:[1,0]
	v_pk_fma_f32 v[134:135], v[192:193], v[208:209], v[134:135]
	v_pk_fma_f32 v[132:133], v[194:195], v[206:207], v[132:133]
	v_pk_fma_f32 v[134:135], v[102:103], s[78:79], v[134:135] op_sel_hi:[1,0,1]
	v_pk_fma_f32 v[132:133], v[100:101], s[78:79], v[132:133] op_sel_hi:[1,0,1]
	v_lshl_add_u64 v[206:207], s[88:89], 0, v[220:221]
	global_store_dwordx4 v[206:207], v[132:135], off
	s_nop 1
	v_sub_f32_e32 v133, v211, v218
	v_sub_f32_e32 v132, v210, v218
	v_sub_f32_e32 v135, v213, v218
	v_sub_f32_e32 v134, v212, v218
	v_pk_mul_f32 v[134:135], v[218:219], v[134:135] op_sel:[1,0]
	v_pk_mul_f32 v[132:133], v[218:219], v[132:133] op_sel:[1,0]
	v_pk_fma_f32 v[130:131], v[188:189], v[134:135], v[130:131]
	v_pk_fma_f32 v[128:129], v[190:191], v[132:133], v[128:129]
	v_or_b32_e32 v132, 16, v148
	v_mov_b32_e32 v133, v159
	v_lshl_add_u64 v[132:133], v[132:133], 2, s[88:89]
	s_waitcnt vmcnt(0)
;     template <bool LN, int BJ, int LO, int HI> DI void batch(const f32x4 (&acc)[2][2][4][2], unsigned row0, unsigned col0, const f32x4 (&gv)[2], const f32x4 (&bv)[2]) const {
;         f32x4 r[HI - LO]; float mean[(HI - LO) / 2], rstd[(HI - LO) / 2];
; #pragma unroll
;         for (int i = LO; i < HI; ++i) { const int ai = i >> 3, m = (i >> 1) & 3, n = i & 1; const unsigned row = row0 + ai * HALF + m * 16;
;             if (n == 0) { mean[(i - LO) >> 1] = 0.f; rstd[(i - LO) >> 1] = 1.f;
;                 if (LN) { const float2 st = *(const float2*)(stats + row * 2u); mean[(i - LO) >> 1] = st.x; rstd[(i - LO) >> 1] = st.y; } }
;             r[i - LO] = *(const f32x4*)(src + (row * (unsigned)DM + col0 + BJ * HALF + n * 16)); }
; #pragma unroll
;         for (int i = LO; i < HI; ++i) { const int ai = i >> 3, m = (i >> 1) & 3, n = i & 1; const unsigned row = row0 + ai * HALF + m * 16;
;             *(f32x4*)(Y + (row * (unsigned)DM + col0 + BJ * HALF + n * 16)) = acc[ai][BJ][m][n] + ((r[i - LO] - mean[(i - LO) >> 1]) * rstd[(i - LO) >> 1]) * gv[n] + bv[n]; }
	v_pk_fma_f32 v[130:131], v[98:99], s[78:79], v[130:131] op_sel_hi:[1,0,1]
	v_pk_fma_f32 v[128:129], v[96:97], s[78:79], v[128:129] op_sel_hi:[1,0,1]
	global_store_dwordx4 v[132:133], v[128:131], off
	s_nop 1
	v_sub_f32_e32 v129, v215, v196
	v_sub_f32_e32 v128, v214, v196
	v_sub_f32_e32 v131, v217, v196
	v_sub_f32_e32 v130, v216, v196
	v_pk_mul_f32 v[130:131], v[196:197], v[130:131] op_sel:[1,0]
	v_pk_mul_f32 v[128:129], v[196:197], v[128:129] op_sel:[1,0]
	v_pk_fma_f32 v[126:127], v[192:193], v[130:131], v[126:127]
	v_pk_fma_f32 v[124:125], v[194:195], v[128:129], v[124:125]
	v_add_u32_e32 v128, 0x8000, v148
	v_mov_b32_e32 v129, v159
	v_pk_fma_f32 v[126:127], v[102:103], s[78:79], v[126:127] op_sel_hi:[1,0,1]
	v_pk_fma_f32 v[124:125], v[100:101], s[78:79], v[124:125] op_sel_hi:[1,0,1]
	v_lshl_add_u64 v[128:129], v[128:129], 2, s[88:89]
	global_store_dwordx4 v[128:129], v[124:127], off
	s_nop 1
	v_sub_f32_e32 v125, v137, v196
	v_sub_f32_e32 v124, v136, v196
	v_sub_f32_e32 v127, v139, v196
	v_sub_f32_e32 v126, v138, v196
	v_pk_mul_f32 v[126:127], v[196:197], v[126:127] op_sel:[1,0]
	v_pk_mul_f32 v[124:125], v[196:197], v[124:125] op_sel:[1,0]
	v_pk_fma_f32 v[122:123], v[188:189], v[126:127], v[122:123]
	v_pk_fma_f32 v[120:121], v[190:191], v[124:125], v[120:121]
	v_add_u32_e32 v124, 0x8010, v148
	v_mov_b32_e32 v125, v159
	v_pk_fma_f32 v[122:123], v[98:99], s[78:79], v[122:123] op_sel_hi:[1,0,1]
	v_pk_fma_f32 v[120:121], v[96:97], s[78:79], v[120:121] op_sel_hi:[1,0,1]
	v_lshl_add_u64 v[124:125], v[124:125], 2, s[88:89]
	global_store_dwordx4 v[124:125], v[120:123], off
	s_nop 1
	v_or_b32_e32 v122, 32, v203
	v_lshlrev_b32_e32 v124, 11, v122
	v_lshlrev_b32_e32 v120, 1, v122
	v_mov_b32_e32 v121, v159
	v_add_u32_e32 v122, v124, v158
	v_mov_b32_e32 v123, v159
	v_lshl_add_u64 v[120:121], v[120:121], 2, s[96:97]
	v_lshl_add_u64 v[122:123], v[122:123], 2, s[90:91]
	global_load_dwordx2 v[138:139], v[120:121], off
	global_load_dwordx4 v[126:129], v[122:123], off
	v_add_u32_e32 v122, v124, v204
	v_mov_b32_e32 v123, v159
	v_lshl_add_u64 v[122:123], v[122:123], 2, s[90:91]
	global_load_dwordx4 v[130:133], v[122:123], off
	v_or_b32_e32 v125, 48, v203
	v_lshlrev_b32_e32 v122, 1, v125
	v_lshlrev_b32_e32 v125, 11, v125
	v_mov_b32_e32 v123, v159
	v_add_u32_e32 v134, v125, v158
	v_mov_b32_e32 v135, v159
	v_lshl_add_u64 v[122:123], v[122:123], 2, s[96:97]
	v_lshl_add_u64 v[134:135], v[134:135], 2, s[90:91]
	global_load_dwordx2 v[196:197], v[122:123], off
	v_add_u32_e32 v206, v125, v204
	global_load_dwordx4 v[134:137], v[134:135], off
	v_mov_b32_e32 v207, v159
	v_lshl_add_u64 v[206:207], v[206:207], 2, s[90:91]
	global_load_dwordx4 v[206:209], v[206:207], off
	s_waitcnt vmcnt(0)
	v_sub_f32_e32 v127, v127, v138
	v_sub_f32_e32 v126, v126, v138
	v_sub_f32_e32 v129, v129, v138
	v_sub_f32_e32 v128, v128, v138
	v_pk_mul_f32 v[128:129], v[138:139], v[128:129] op_sel:[1,0]
	v_pk_mul_f32 v[126:127], v[138:139], v[126:127] op_sel:[1,0]
	v_pk_fma_f32 v[118:119], v[192:193], v[128:129], v[118:119]
	v_pk_fma_f32 v[116:117], v[194:195], v[126:127], v[116:117]
	v_add_u32_e32 v126, 0x10000, v148
	v_mov_b32_e32 v127, v159
	v_pk_fma_f32 v[118:119], v[102:103], s[78:79], v[118:119] op_sel_hi:[1,0,1]
	v_pk_fma_f32 v[116:117], v[100:101], s[78:79], v[116:117] op_sel_hi:[1,0,1]
	v_lshl_add_u64 v[126:127], v[126:127], 2, s[88:89]
	global_store_dwordx4 v[126:127], v[116:119], off
	s_nop 1
	v_sub_f32_e32 v117, v131, v138
	v_sub_f32_e32 v116, v130, v138
	v_sub_f32_e32 v119, v133, v138
	v_sub_f32_e32 v118, v132, v138
	v_pk_mul_f32 v[118:119], v[138:139], v[118:119] op_sel:[1,0]
	v_pk_mul_f32 v[116:117], v[138:139], v[116:117] op_sel:[1,0]
	v_pk_fma_f32 v[114:115], v[188:189], v[118:119], v[114:115]
	v_pk_fma_f32 v[112:113], v[190:191], v[116:117], v[112:113]
	v_add_u32_e32 v116, 0x10010, v148
	v_mov_b32_e32 v117, v159
	v_pk_fma_f32 v[114:115], v[98:99], s[78:79], v[114:115] op_sel_hi:[1,0,1]
	v_pk_fma_f32 v[112:113], v[96:97], s[78:79], v[112:113] op_sel_hi:[1,0,1]
	v_lshl_add_u64 v[116:117], v[116:117], 2, s[88:89]
	global_store_dwordx4 v[116:117], v[112:115], off
	s_nop 1
	v_sub_f32_e32 v113, v135, v196
	v_sub_f32_e32 v112, v134, v196
	v_sub_f32_e32 v115, v137, v196
	v_sub_f32_e32 v114, v136, v196
	v_pk_mul_f32 v[114:115], v[196:197], v[114:115] op_sel:[1,0]
	v_pk_mul_f32 v[112:113], v[196:197], v[112:113] op_sel:[1,0]
	v_pk_fma_f32 v[110:111], v[192:193], v[114:115], v[110:111]
	v_pk_fma_f32 v[108:109], v[194:195], v[112:113], v[108:109]
	v_add_u32_e32 v112, 0x18000, v148
	v_mov_b32_e32 v113, v159
	v_pk_fma_f32 v[110:111], v[102:103], s[78:79], v[110:111] op_sel_hi:[1,0,1]
	v_pk_fma_f32 v[108:109], v[100:101], s[78:79], v[108:109] op_sel_hi:[1,0,1]
	v_lshl_add_u64 v[112:113], v[112:113], 2, s[88:89]
	global_store_dwordx4 v[112:113], v[108:111], off
	s_nop 1
	v_sub_f32_e32 v109, v207, v196
	v_sub_f32_e32 v108, v206, v196
	v_sub_f32_e32 v111, v209, v196
	v_sub_f32_e32 v110, v208, v196
	v_pk_mul_f32 v[110:111], v[196:197], v[110:111] op_sel:[1,0]
	v_pk_mul_f32 v[108:109], v[196:197], v[108:109] op_sel:[1,0]
	v_pk_fma_f32 v[106:107], v[188:189], v[110:111], v[106:107]
	v_pk_fma_f32 v[104:105], v[190:191], v[108:109], v[104:105]
	v_add_u32_e32 v108, 0x18010, v148
	v_mov_b32_e32 v109, v159
	v_pk_fma_f32 v[106:107], v[98:99], s[78:79], v[106:107] op_sel_hi:[1,0,1]
	v_pk_fma_f32 v[104:105], v[96:97], s[78:79], v[104:105] op_sel_hi:[1,0,1]
	v_lshl_add_u64 v[108:109], v[108:109], 2, s[88:89]
	global_store_dwordx4 v[108:109], v[104:107], off
	s_nop 1
	v_add_u32_e32 v106, 0x80, v203
	v_lshlrev_b32_e32 v114, 11, v106
	v_lshlrev_b32_e32 v104, 1, v106
	v_mov_b32_e32 v105, v159
	v_add_u32_e32 v106, v114, v158
	v_mov_b32_e32 v107, v159
	v_lshl_add_u64 v[104:105], v[104:105], 2, s[96:97]
	v_lshl_add_u64 v[106:107], v[106:107], 2, s[90:91]
	global_load_dwordx2 v[112:113], v[104:105], off
	global_load_dwordx4 v[108:111], v[106:107], off
	v_add_u32_e32 v106, v114, v204
	v_mov_b32_e32 v107, v159
	v_lshl_add_u64 v[106:107], v[106:107], 2, s[90:91]
	global_load_dwordx4 v[116:119], v[106:107], off
	v_add_u32_e32 v115, 0x90, v203
	v_lshlrev_b32_e32 v106, 1, v115
	v_lshlrev_b32_e32 v115, 11, v115
	v_mov_b32_e32 v107, v159
	v_add_u32_e32 v126, v115, v158
	v_mov_b32_e32 v127, v159
	v_lshl_add_u64 v[106:107], v[106:107], 2, s[96:97]
	v_lshl_add_u64 v[126:127], v[126:127], 2, s[90:91]
	global_load_dwordx2 v[134:135], v[106:107], off
	v_add_u32_e32 v130, v115, v204
	global_load_dwordx4 v[126:129], v[126:127], off
	v_mov_b32_e32 v131, v159
	v_lshl_add_u64 v[130:131], v[130:131], 2, s[90:91]
	global_load_dwordx4 v[130:133], v[130:131], off
	s_waitcnt vmcnt(0)
;     template <bool LN, int BJ, int LO, int HI> DI void batch(const f32x4 (&acc)[2][2][4][2], unsigned row0, unsigned col0, const f32x4 (&gv)[2], const f32x4 (&bv)[2]) const {
;         f32x4 r[HI - LO]; float mean[(HI - LO) / 2], rstd[(HI - LO) / 2];
; #pragma unroll
;         for (int i = LO; i < HI; ++i) { const int ai = i >> 3, m = (i >> 1) & 3, n = i & 1; const unsigned row = row0 + ai * HALF + m * 16;
;             if (n == 0) { mean[(i - LO) >> 1] = 0.f; rstd[(i - LO) >> 1] = 1.f;
;                 if (LN) { const float2 st = *(const float2*)(stats + row * 2u); mean[(i - LO) >> 1] = st.x; rstd[(i - LO) >> 1] = st.y; } }
;             r[i - LO] = *(const f32x4*)(src + (row * (unsigned)DM + col0 + BJ * HALF + n * 16)); }
; #pragma unroll
;         for (int i = LO; i < HI; ++i) { const int ai = i >> 3, m = (i >> 1) & 3, n = i & 1; const unsigned row = row0 + ai * HALF + m * 16;
;             *(f32x4*)(Y + (row * (unsigned)DM + col0 + BJ * HALF + n * 16)) = acc[ai][BJ][m][n] + ((r[i - LO] - mean[(i - LO) >> 1]) * rstd[(i - LO) >> 1]) * gv[n] + bv[n]; }
	v_sub_f32_e32 v109, v109, v112
	v_sub_f32_e32 v108, v108, v112
	v_sub_f32_e32 v111, v111, v112
	v_sub_f32_e32 v110, v110, v112
	v_pk_mul_f32 v[110:111], v[112:113], v[110:111] op_sel:[1,0]
	v_pk_mul_f32 v[108:109], v[112:113], v[108:109] op_sel:[1,0]
	v_pk_fma_f32 v[94:95], v[192:193], v[110:111], v[94:95]
	v_pk_fma_f32 v[92:93], v[194:195], v[108:109], v[92:93]
	v_add_u32_e32 v108, 0x40000, v148
	v_mov_b32_e32 v109, v159
	v_pk_fma_f32 v[94:95], v[102:103], s[78:79], v[94:95] op_sel_hi:[1,0,1]
	v_pk_fma_f32 v[92:93], v[100:101], s[78:79], v[92:93] op_sel_hi:[1,0,1]
	v_lshl_add_u64 v[108:109], v[108:109], 2, s[88:89]
	global_store_dwordx4 v[108:109], v[92:95], off
	s_nop 1
	v_sub_f32_e32 v93, v117, v112
	v_sub_f32_e32 v92, v116, v112
	v_sub_f32_e32 v95, v119, v112
	v_sub_f32_e32 v94, v118, v112
	v_pk_mul_f32 v[94:95], v[112:113], v[94:95] op_sel:[1,0]
	v_pk_mul_f32 v[92:93], v[112:113], v[92:93] op_sel:[1,0]
	v_pk_fma_f32 v[90:91], v[188:189], v[94:95], v[90:91]
	v_pk_fma_f32 v[88:89], v[190:191], v[92:93], v[88:89]
	v_add_u32_e32 v92, 0x40010, v148
	v_mov_b32_e32 v93, v159
	v_pk_fma_f32 v[90:91], v[98:99], s[78:79], v[90:91] op_sel_hi:[1,0,1]
	v_pk_fma_f32 v[88:89], v[96:97], s[78:79], v[88:89] op_sel_hi:[1,0,1]
	v_lshl_add_u64 v[92:93], v[92:93], 2, s[88:89]
	global_store_dwordx4 v[92:93], v[88:91], off
	s_nop 1
	v_sub_f32_e32 v89, v127, v134
	v_sub_f32_e32 v88, v126, v134
	v_sub_f32_e32 v91, v129, v134
	v_sub_f32_e32 v90, v128, v134
	v_pk_mul_f32 v[90:91], v[134:135], v[90:91] op_sel:[1,0]
	v_pk_mul_f32 v[88:89], v[134:135], v[88:89] op_sel:[1,0]
	v_pk_fma_f32 v[86:87], v[192:193], v[90:91], v[86:87]
	v_pk_fma_f32 v[84:85], v[194:195], v[88:89], v[84:85]
	v_add_u32_e32 v88, 0x48000, v148
	v_mov_b32_e32 v89, v159
	v_pk_fma_f32 v[86:87], v[102:103], s[78:79], v[86:87] op_sel_hi:[1,0,1]
	v_pk_fma_f32 v[84:85], v[100:101], s[78:79], v[84:85] op_sel_hi:[1,0,1]
	v_lshl_add_u64 v[88:89], v[88:89], 2, s[88:89]
	global_store_dwordx4 v[88:89], v[84:87], off
	s_nop 1
	v_sub_f32_e32 v85, v131, v134
	v_sub_f32_e32 v84, v130, v134
	v_sub_f32_e32 v87, v133, v134
	v_sub_f32_e32 v86, v132, v134
	v_pk_mul_f32 v[86:87], v[134:135], v[86:87] op_sel:[1,0]
	v_pk_mul_f32 v[84:85], v[134:135], v[84:85] op_sel:[1,0]
	v_pk_fma_f32 v[82:83], v[188:189], v[86:87], v[82:83]
	v_pk_fma_f32 v[80:81], v[190:191], v[84:85], v[80:81]
	v_add_u32_e32 v84, 0x48010, v148
	v_mov_b32_e32 v85, v159
	v_pk_fma_f32 v[82:83], v[98:99], s[78:79], v[82:83] op_sel_hi:[1,0,1]
	v_pk_fma_f32 v[80:81], v[96:97], s[78:79], v[80:81] op_sel_hi:[1,0,1]
	v_lshl_add_u64 v[84:85], v[84:85], 2, s[88:89]
	global_store_dwordx4 v[84:85], v[80:83], off
	s_nop 1
	v_add_u32_e32 v82, 0xa0, v203
	v_lshlrev_b32_e32 v80, 1, v82
	v_mov_b32_e32 v81, v159
	v_lshlrev_b32_e32 v116, 11, v82
	v_lshl_add_u64 v[108:109], v[80:81], 2, s[96:97]
	v_add_u32_e32 v80, v116, v158
	v_lshl_add_u64 v[80:81], v[80:81], 2, s[90:91]
	global_load_dwordx2 v[112:113], v[108:109], off
	v_add_u32_e32 v84, v116, v204
	global_load_dwordx4 v[80:83], v[80:81], off
	v_mov_b32_e32 v85, v159
	v_lshl_add_u64 v[84:85], v[84:85], 2, s[90:91]
	global_load_dwordx4 v[84:87], v[84:85], off
	v_add_u32_e32 v90, 0xb0, v203
	v_lshlrev_b32_e32 v88, 1, v90
	v_mov_b32_e32 v89, v159
	v_lshlrev_b32_e32 v117, 11, v90
	v_lshl_add_u64 v[110:111], v[88:89], 2, s[96:97]
	v_add_u32_e32 v88, v117, v158
	v_lshl_add_u64 v[88:89], v[88:89], 2, s[90:91]
	global_load_dwordx2 v[118:119], v[110:111], off
	v_add_u32_e32 v92, v117, v204
	global_load_dwordx4 v[88:91], v[88:89], off
	v_mov_b32_e32 v93, v159
	v_lshl_add_u64 v[92:93], v[92:93], 2, s[90:91]
	global_load_dwordx4 v[92:95], v[92:93], off
	s_waitcnt vmcnt(0)
	v_sub_f32_e32 v81, v81, v112
	v_sub_f32_e32 v80, v80, v112
	v_sub_f32_e32 v83, v83, v112
	v_sub_f32_e32 v82, v82, v112
	v_pk_mul_f32 v[82:83], v[112:113], v[82:83] op_sel:[1,0]
	v_pk_mul_f32 v[80:81], v[112:113], v[80:81] op_sel:[1,0]
	v_pk_fma_f32 v[78:79], v[192:193], v[82:83], v[78:79]
	v_pk_fma_f32 v[76:77], v[194:195], v[80:81], v[76:77]
	v_add_u32_e32 v80, 0x50000, v148
	v_mov_b32_e32 v81, v159
	v_pk_fma_f32 v[78:79], v[102:103], s[78:79], v[78:79] op_sel_hi:[1,0,1]
	v_pk_fma_f32 v[76:77], v[100:101], s[78:79], v[76:77] op_sel_hi:[1,0,1]
	v_lshl_add_u64 v[80:81], v[80:81], 2, s[88:89]
	global_store_dwordx4 v[80:81], v[76:79], off
	s_nop 1
	v_sub_f32_e32 v77, v85, v112
	v_sub_f32_e32 v76, v84, v112
	v_sub_f32_e32 v79, v87, v112
	v_sub_f32_e32 v78, v86, v112
	v_pk_mul_f32 v[78:79], v[112:113], v[78:79] op_sel:[1,0]
	v_pk_mul_f32 v[76:77], v[112:113], v[76:77] op_sel:[1,0]
	v_pk_fma_f32 v[74:75], v[188:189], v[78:79], v[74:75]
	v_pk_fma_f32 v[72:73], v[190:191], v[76:77], v[72:73]
	v_add_u32_e32 v76, 0x50010, v148
	v_mov_b32_e32 v77, v159
	v_pk_fma_f32 v[74:75], v[98:99], s[78:79], v[74:75] op_sel_hi:[1,0,1]
	v_pk_fma_f32 v[72:73], v[96:97], s[78:79], v[72:73] op_sel_hi:[1,0,1]
	v_lshl_add_u64 v[76:77], v[76:77], 2, s[88:89]
	global_store_dwordx4 v[76:77], v[72:75], off
	s_nop 1
	v_sub_f32_e32 v73, v89, v118
	v_sub_f32_e32 v72, v88, v118
	v_sub_f32_e32 v75, v91, v118
	v_sub_f32_e32 v74, v90, v118
	v_pk_mul_f32 v[74:75], v[118:119], v[74:75] op_sel:[1,0]
	v_pk_mul_f32 v[72:73], v[118:119], v[72:73] op_sel:[1,0]
	v_pk_fma_f32 v[70:71], v[192:193], v[74:75], v[70:71]
	v_pk_fma_f32 v[68:69], v[194:195], v[72:73], v[68:69]
	v_add_u32_e32 v72, 0x58000, v148
	v_mov_b32_e32 v73, v159
	v_pk_fma_f32 v[70:71], v[102:103], s[78:79], v[70:71] op_sel_hi:[1,0,1]
	v_pk_fma_f32 v[68:69], v[100:101], s[78:79], v[68:69] op_sel_hi:[1,0,1]
	v_lshl_add_u64 v[72:73], v[72:73], 2, s[88:89]
	global_store_dwordx4 v[72:73], v[68:71], off
	s_nop 1
	v_sub_f32_e32 v69, v93, v118
	v_sub_f32_e32 v68, v92, v118
	v_sub_f32_e32 v71, v95, v118
	v_sub_f32_e32 v70, v94, v118
	v_pk_mul_f32 v[70:71], v[118:119], v[70:71] op_sel:[1,0]
	v_pk_mul_f32 v[68:69], v[118:119], v[68:69] op_sel:[1,0]
	v_pk_fma_f32 v[66:67], v[188:189], v[70:71], v[66:67]
	v_pk_fma_f32 v[64:65], v[190:191], v[68:69], v[64:65]
	v_add_u32_e32 v68, 0x58010, v148
	v_mov_b32_e32 v69, v159
	v_pk_fma_f32 v[66:67], v[98:99], s[78:79], v[66:67] op_sel_hi:[1,0,1]
	v_pk_fma_f32 v[64:65], v[96:97], s[78:79], v[64:65] op_sel_hi:[1,0,1]
	v_lshl_add_u64 v[68:69], v[68:69], 2, s[88:89]
	global_store_dwordx4 v[68:69], v[64:67], off
	global_load_dwordx4 v[64:67], v[150:151], off offset:512
	v_or_b32_e32 v119, 0x80, v158
	v_add_u32_e32 v72, v202, v119
	v_mov_b32_e32 v73, v159
	v_lshl_add_u64 v[72:73], v[72:73], 2, s[90:91]
	v_or_b32_e32 v118, 0x90, v158
	v_add_u32_e32 v158, v202, v118
	s_waitcnt vmcnt(0)
;     template <bool LN, int BJ, int LO, int HI> DI void batch(const f32x4 (&acc)[2][2][4][2], unsigned row0, unsigned col0, const f32x4 (&gv)[2], const f32x4 (&bv)[2]) const {
;         f32x4 r[HI - LO]; float mean[(HI - LO) / 2], rstd[(HI - LO) / 2];
; #pragma unroll
;         for (int i = LO; i < HI; ++i) { const int ai = i >> 3, m = (i >> 1) & 3, n = i & 1; const unsigned row = row0 + ai * HALF + m * 16;
;             if (n == 0) { mean[(i - LO) >> 1] = 0.f; rstd[(i - LO) >> 1] = 1.f;
;                 if (LN) { const float2 st = *(const float2*)(stats + row * 2u); mean[(i - LO) >> 1] = st.x; rstd[(i - LO) >> 1] = st.y; } }
;             r[i - LO] = *(const f32x4*)(src + (row * (unsigned)DM + col0 + BJ * HALF + n * 16)); }
; #pragma unroll
;         for (int i = LO; i < HI; ++i) { const int ai = i >> 3, m = (i >> 1) & 3, n = i & 1; const unsigned row = row0 + ai * HALF + m * 16;
;             *(f32x4*)(Y + (row * (unsigned)DM + col0 + BJ * HALF + n * 16)) = acc[ai][BJ][m][n] + ((r[i - LO] - mean[(i - LO) >> 1]) * rstd[(i - LO) >> 1]) * gv[n] + bv[n]; }
;         __builtin_amdgcn_sched_barrier(0);
;     }
;     template <bool LN, int BJ> DI void load_gb(unsigned col0, f32x4 (&gv)[2], f32x4 (&bv)[2]) const {
; #pragma unroll
;         for (int n = 0; n < 2; ++n) {
;             if (LN) { gv[n] = *(const f32x4*)(gam + col0 + BJ * HALF + n * 16) * ALPHA; bv[n] = *(const f32x4*)(bet + col0 + BJ * HALF + n * 16) * ALPHA; }
;             else { gv[n] = (f32x4){ALPHA, ALPHA, ALPHA, ALPHA}; bv[n] = (f32x4){0.f, 0.f, 0.f, 0.f}; }
;         }
;     }
;     template <bool LN> DI void run(const f32x4 (&acc)[2][2][4][2], const Unit& u, int wr, int wc, int fr, int fq) const {
;         const unsigned row0 = u.pm * BM + wr * 64 + fr, col0 = u.pn * BM + wc * 32 + 4 * fq;
;         f32x4 gv[2], bv[2];
;         load_gb<LN, 0>(col0, gv, bv);
;         batch<LN, 0, 0, 4>(acc, row0, col0, gv, bv);
;         batch<LN, 0, 4, 8>(acc, row0, col0, gv, bv);
;         batch<LN, 0, 8, 12>(acc, row0, col0, gv, bv);
;         batch<LN, 0, 12, 16>(acc, row0, col0, gv, bv);
;         load_gb<LN, 1>(col0, gv, bv);
;         batch<LN, 1, 0, 8>(acc, row0, col0, gv, bv);
;         batch<LN, 1, 8, 16>(acc, row0, col0, gv, bv);
	v_pk_mul_f32 v[96:97], v[66:67], s[78:79] op_sel_hi:[1,0]
	v_pk_mul_f32 v[98:99], v[64:65], s[78:79] op_sel_hi:[1,0]
	global_load_dwordx4 v[68:71], v[152:153], off offset:512
	global_load_dwordx4 v[64:67], v[150:151], off offset:576
	global_load_dwordx2 v[138:139], v[154:155], off
	global_load_dwordx4 v[126:129], v[72:73], off
	v_lshl_add_u64 v[72:73], v[158:159], 2, s[90:91]
	v_add_u32_e32 v158, v149, v119
	s_waitcnt vmcnt(0)
	v_pk_mul_f32 v[92:93], v[66:67], s[78:79] op_sel_hi:[1,0]
	v_pk_mul_f32 v[94:95], v[64:65], s[78:79] op_sel_hi:[1,0]
	global_load_dwordx4 v[64:67], v[152:153], off offset:576
	global_load_dwordx4 v[130:133], v[72:73], off
	global_load_dwordx2 v[112:113], v[186:187], off
	v_lshl_add_u64 v[72:73], v[158:159], 2, s[90:91]
	global_load_dwordx4 v[134:137], v[72:73], off
	v_add_u32_e32 v158, v149, v118
	v_lshl_add_u64 v[72:73], v[158:159], 2, s[90:91]
	global_load_dwordx4 v[88:91], v[72:73], off
	global_load_dwordx2 v[102:103], v[120:121], off
	v_add_u32_e32 v158, v124, v119
	v_lshl_add_u64 v[72:73], v[158:159], 2, s[90:91]
	global_load_dwordx4 v[84:87], v[72:73], off
	v_add_u32_e32 v158, v124, v118
	v_lshl_add_u64 v[72:73], v[158:159], 2, s[90:91]
	global_load_dwordx4 v[80:83], v[72:73], off
	global_load_dwordx2 v[100:101], v[122:123], off
	v_add_u32_e32 v158, v125, v119
	v_lshl_add_u64 v[72:73], v[158:159], 2, s[90:91]
	global_load_dwordx4 v[76:79], v[72:73], off
	v_add_u32_e32 v158, v125, v118
	v_lshl_add_u64 v[72:73], v[158:159], 2, s[90:91]
	global_load_dwordx4 v[72:75], v[72:73], off
	v_sub_f32_e32 v121, v127, v138
	v_sub_f32_e32 v120, v126, v138
	v_sub_f32_e32 v123, v129, v138
	v_sub_f32_e32 v122, v128, v138
	v_pk_mul_f32 v[122:123], v[138:139], v[122:123] op_sel:[1,0]
	v_pk_mul_f32 v[120:121], v[138:139], v[120:121] op_sel:[1,0]
	v_or_b32_e32 v158, 0x80, v148
	v_pk_fma_f32 v[60:61], v[98:99], v[120:121], v[60:61]
	v_pk_fma_f32 v[62:63], v[96:97], v[122:123], v[62:63]
	v_pk_fma_f32 v[60:61], v[68:69], s[78:79], v[60:61] op_sel_hi:[1,0,1]
	v_pk_fma_f32 v[62:63], v[70:71], s[78:79], v[62:63] op_sel_hi:[1,0,1]
	v_lshl_add_u64 v[120:121], v[158:159], 2, s[88:89]
	global_store_dwordx4 v[120:121], v[60:63], off
	v_or_b32_e32 v158, 0x90, v148
	s_waitcnt vmcnt(0)
	v_sub_f32_e32 v61, v131, v138
	v_sub_f32_e32 v60, v130, v138
	v_sub_f32_e32 v63, v133, v138
	v_sub_f32_e32 v62, v132, v138
	v_pk_mul_f32 v[62:63], v[138:139], v[62:63] op_sel:[1,0]
	v_pk_mul_f32 v[60:61], v[138:139], v[60:61] op_sel:[1,0]
	v_pk_fma_f32 v[58:59], v[92:93], v[62:63], v[58:59]
	v_pk_fma_f32 v[56:57], v[94:95], v[60:61], v[56:57]
	v_pk_fma_f32 v[58:59], v[66:67], s[78:79], v[58:59] op_sel_hi:[1,0,1]
	v_pk_fma_f32 v[56:57], v[64:65], s[78:79], v[56:57] op_sel_hi:[1,0,1]
	v_lshl_add_u64 v[60:61], v[158:159], 2, s[88:89]
	global_store_dwordx4 v[60:61], v[56:59], off
	v_add_u32_e32 v158, 0x8080, v148
	s_nop 0
	v_sub_f32_e32 v57, v135, v112
	v_sub_f32_e32 v56, v134, v112
	v_sub_f32_e32 v59, v137, v112
	v_sub_f32_e32 v58, v136, v112
	v_pk_mul_f32 v[58:59], v[112:113], v[58:59] op_sel:[1,0]
	v_pk_mul_f32 v[56:57], v[112:113], v[56:57] op_sel:[1,0]
	v_pk_fma_f32 v[54:55], v[96:97], v[58:59], v[54:55]
	v_pk_fma_f32 v[52:53], v[98:99], v[56:57], v[52:53]
	v_pk_fma_f32 v[54:55], v[70:71], s[78:79], v[54:55] op_sel_hi:[1,0,1]
	v_pk_fma_f32 v[52:53], v[68:69], s[78:79], v[52:53] op_sel_hi:[1,0,1]
	v_lshl_add_u64 v[56:57], v[158:159], 2, s[88:89]
	global_store_dwordx4 v[56:57], v[52:55], off
	v_add_u32_e32 v158, 0x8090, v148
	s_nop 0
	v_sub_f32_e32 v53, v89, v112
	v_sub_f32_e32 v52, v88, v112
	v_sub_f32_e32 v55, v91, v112
	v_sub_f32_e32 v54, v90, v112
	v_pk_mul_f32 v[54:55], v[112:113], v[54:55] op_sel:[1,0]
	v_pk_mul_f32 v[52:53], v[112:113], v[52:53] op_sel:[1,0]
	v_pk_fma_f32 v[50:51], v[92:93], v[54:55], v[50:51]
	v_pk_fma_f32 v[48:49], v[94:95], v[52:53], v[48:49]
	v_pk_fma_f32 v[50:51], v[66:67], s[78:79], v[50:51] op_sel_hi:[1,0,1]
	v_pk_fma_f32 v[48:49], v[64:65], s[78:79], v[48:49] op_sel_hi:[1,0,1]
	v_lshl_add_u64 v[52:53], v[158:159], 2, s[88:89]
	global_store_dwordx4 v[52:53], v[48:51], off
	v_add_u32_e32 v158, 0x10080, v148
	s_nop 0
	v_sub_f32_e32 v49, v85, v102
	v_sub_f32_e32 v48, v84, v102
	v_sub_f32_e32 v51, v87, v102
	v_sub_f32_e32 v50, v86, v102
	v_pk_mul_f32 v[50:51], v[102:103], v[50:51] op_sel:[1,0]
	v_pk_mul_f32 v[48:49], v[102:103], v[48:49] op_sel:[1,0]
	v_pk_fma_f32 v[46:47], v[96:97], v[50:51], v[46:47]
	v_pk_fma_f32 v[44:45], v[98:99], v[48:49], v[44:45]
	v_pk_fma_f32 v[46:47], v[70:71], s[78:79], v[46:47] op_sel_hi:[1,0,1]
	v_pk_fma_f32 v[44:45], v[68:69], s[78:79], v[44:45] op_sel_hi:[1,0,1]
	v_lshl_add_u64 v[48:49], v[158:159], 2, s[88:89]
	global_store_dwordx4 v[48:49], v[44:47], off
	v_add_u32_e32 v158, 0x10090, v148
	s_nop 0
	v_sub_f32_e32 v45, v81, v102
	v_sub_f32_e32 v44, v80, v102
	v_sub_f32_e32 v47, v83, v102
	v_sub_f32_e32 v46, v82, v102
	v_pk_mul_f32 v[46:47], v[102:103], v[46:47] op_sel:[1,0]
	v_pk_mul_f32 v[44:45], v[102:103], v[44:45] op_sel:[1,0]
	v_pk_fma_f32 v[42:43], v[92:93], v[46:47], v[42:43]
	v_pk_fma_f32 v[40:41], v[94:95], v[44:45], v[40:41]
	v_pk_fma_f32 v[42:43], v[66:67], s[78:79], v[42:43] op_sel_hi:[1,0,1]
	v_pk_fma_f32 v[40:41], v[64:65], s[78:79], v[40:41] op_sel_hi:[1,0,1]
	v_lshl_add_u64 v[44:45], v[158:159], 2, s[88:89]
	global_store_dwordx4 v[44:45], v[40:43], off
	v_add_u32_e32 v158, 0x18080, v148
	s_nop 0
	v_sub_f32_e32 v41, v77, v100
	v_sub_f32_e32 v40, v76, v100
	v_sub_f32_e32 v43, v79, v100
	v_sub_f32_e32 v42, v78, v100
	v_pk_mul_f32 v[42:43], v[100:101], v[42:43] op_sel:[1,0]
	v_pk_mul_f32 v[40:41], v[100:101], v[40:41] op_sel:[1,0]
	v_pk_fma_f32 v[38:39], v[96:97], v[42:43], v[38:39]
;     template <bool LN, int BJ, int LO, int HI> DI void batch(const f32x4 (&acc)[2][2][4][2], unsigned row0, unsigned col0, const f32x4 (&gv)[2], const f32x4 (&bv)[2]) const {
;         f32x4 r[HI - LO]; float mean[(HI - LO) / 2], rstd[(HI - LO) / 2];
; #pragma unroll
;         for (int i = LO; i < HI; ++i) { const int ai = i >> 3, m = (i >> 1) & 3, n = i & 1; const unsigned row = row0 + ai * HALF + m * 16;
;             if (n == 0) { mean[(i - LO) >> 1] = 0.f; rstd[(i - LO) >> 1] = 1.f;
;                 if (LN) { const float2 st = *(const float2*)(stats + row * 2u); mean[(i - LO) >> 1] = st.x; rstd[(i - LO) >> 1] = st.y; } }
;             r[i - LO] = *(const f32x4*)(src + (row * (unsigned)DM + col0 + BJ * HALF + n * 16)); }
; #pragma unroll
;         for (int i = LO; i < HI; ++i) { const int ai = i >> 3, m = (i >> 1) & 3, n = i & 1; const unsigned row = row0 + ai * HALF + m * 16;
;             *(f32x4*)(Y + (row * (unsigned)DM + col0 + BJ * HALF + n * 16)) = acc[ai][BJ][m][n] + ((r[i - LO] - mean[(i - LO) >> 1]) * rstd[(i - LO) >> 1]) * gv[n] + bv[n]; }
	v_pk_fma_f32 v[36:37], v[98:99], v[40:41], v[36:37]
	v_pk_fma_f32 v[38:39], v[70:71], s[78:79], v[38:39] op_sel_hi:[1,0,1]
	v_pk_fma_f32 v[36:37], v[68:69], s[78:79], v[36:37] op_sel_hi:[1,0,1]
	v_lshl_add_u64 v[40:41], v[158:159], 2, s[88:89]
	global_store_dwordx4 v[40:41], v[36:39], off
	v_add_u32_e32 v158, 0x18090, v148
	s_nop 0
	v_sub_f32_e32 v37, v73, v100
	v_sub_f32_e32 v36, v72, v100
	v_sub_f32_e32 v39, v75, v100
	v_sub_f32_e32 v38, v74, v100
	v_pk_mul_f32 v[38:39], v[100:101], v[38:39] op_sel:[1,0]
	v_pk_mul_f32 v[36:37], v[100:101], v[36:37] op_sel:[1,0]
	v_pk_fma_f32 v[34:35], v[92:93], v[38:39], v[34:35]
	v_pk_fma_f32 v[32:33], v[94:95], v[36:37], v[32:33]
	v_pk_fma_f32 v[34:35], v[66:67], s[78:79], v[34:35] op_sel_hi:[1,0,1]
	v_pk_fma_f32 v[32:33], v[64:65], s[78:79], v[32:33] op_sel_hi:[1,0,1]
	v_lshl_add_u64 v[36:37], v[158:159], 2, s[88:89]
	global_store_dwordx4 v[36:37], v[32:35], off
	v_add_u32_e32 v158, v114, v119
	s_nop 0
	v_lshl_add_u64 v[32:33], v[158:159], 2, s[90:91]
	global_load_dwordx2 v[62:63], v[104:105], off
	global_load_dwordx4 v[54:57], v[32:33], off
	v_add_u32_e32 v158, v114, v118
	v_lshl_add_u64 v[32:33], v[158:159], 2, s[90:91]
	global_load_dwordx4 v[58:61], v[32:33], off
	global_load_dwordx2 v[52:53], v[106:107], off
	v_add_u32_e32 v158, v115, v119
	v_lshl_add_u64 v[32:33], v[158:159], 2, s[90:91]
	global_load_dwordx4 v[72:75], v[32:33], off
	v_add_u32_e32 v158, v115, v118
	v_lshl_add_u64 v[32:33], v[158:159], 2, s[90:91]
	global_load_dwordx4 v[76:79], v[32:33], off
	global_load_dwordx2 v[50:51], v[108:109], off
	v_add_u32_e32 v158, v116, v119
	v_lshl_add_u64 v[32:33], v[158:159], 2, s[90:91]
	global_load_dwordx4 v[44:47], v[32:33], off
	v_add_u32_e32 v158, v116, v118
	v_lshl_add_u64 v[32:33], v[158:159], 2, s[90:91]
	global_load_dwordx4 v[40:43], v[32:33], off
	global_load_dwordx2 v[48:49], v[110:111], off
	v_add_u32_e32 v158, v117, v119
	v_lshl_add_u64 v[32:33], v[158:159], 2, s[90:91]
	global_load_dwordx4 v[36:39], v[32:33], off
	v_add_u32_e32 v158, v117, v118
	v_lshl_add_u64 v[32:33], v[158:159], 2, s[90:91]
	global_load_dwordx4 v[32:35], v[32:33], off
	v_add_u32_e32 v158, 0x40080, v148
	s_waitcnt vmcnt(0)
; #define PG8_WAIT_V(n) asm volatile("s_waitcnt vmcnt(" #n ")" ::: "memory")
; #define PG8_BAR __builtin_amdgcn_s_barrier()
; template <class Epi>
; DI void gemm_phase(LAS unsigned char* lds, const Gemm g, const StaticOrder& S, const Epi& E) {
;     ...
;         E(acc, cur, wr, wc, fr, fq);
;         if (!has_next) break;
; #pragma unroll
;         for (int a = 0; a < 2; ++a)
; #pragma unroll
;             for (int b = 0; b < 2; ++b)
; #pragma unroll
;                 for (int m = 0; m < 4; ++m)
; #pragma unroll
;                     for (int n = 0; n < 2; ++n) acc[a][b][m][n] = (f32x4){0.f, 0.f, 0.f, 0.f};
;         cur = nxt; cA = nA; cB = nB; ++ui;
;     }
;     PG8_WAIT_V(0);
;     if (wr == 0) PG8_BAR;
;     PG8_BAR;
;     template <bool LN, int BJ, int LO, int HI> DI void batch(const f32x4 (&acc)[2][2][4][2], unsigned row0, unsigned col0, const f32x4 (&gv)[2], const f32x4 (&bv)[2]) const {
;         f32x4 r[HI - LO]; float mean[(HI - LO) / 2], rstd[(HI - LO) / 2];
; #pragma unroll
;         for (int i = LO; i < HI; ++i) { const int ai = i >> 3, m = (i >> 1) & 3, n = i & 1; const unsigned row = row0 + ai * HALF + m * 16;
;             if (n == 0) { mean[(i - LO) >> 1] = 0.f; rstd[(i - LO) >> 1] = 1.f;
;                 if (LN) { const float2 st = *(const float2*)(stats + row * 2u); mean[(i - LO) >> 1] = st.x; rstd[(i - LO) >> 1] = st.y; } }
;             r[i - LO] = *(const f32x4*)(src + (row * (unsigned)DM + col0 + BJ * HALF + n * 16)); }
; #pragma unroll
;         for (int i = LO; i < HI; ++i) { const int ai = i >> 3, m = (i >> 1) & 3, n = i & 1; const unsigned row = row0 + ai * HALF + m * 16;
;             *(f32x4*)(Y + (row * (unsigned)DM + col0 + BJ * HALF + n * 16)) = acc[ai][BJ][m][n] + ((r[i - LO] - mean[(i - LO) >> 1]) * rstd[(i - LO) >> 1]) * gv[n] + bv[n]; }
	v_sub_f32_e32 v55, v55, v62
	v_sub_f32_e32 v54, v54, v62
	v_sub_f32_e32 v57, v57, v62
	v_sub_f32_e32 v56, v56, v62
	v_pk_mul_f32 v[56:57], v[62:63], v[56:57] op_sel:[1,0]
	v_pk_mul_f32 v[54:55], v[62:63], v[54:55] op_sel:[1,0]
	v_pk_fma_f32 v[30:31], v[96:97], v[56:57], v[30:31]
	v_pk_fma_f32 v[28:29], v[98:99], v[54:55], v[28:29]
	v_pk_fma_f32 v[30:31], v[70:71], s[78:79], v[30:31] op_sel_hi:[1,0,1]
	v_pk_fma_f32 v[28:29], v[68:69], s[78:79], v[28:29] op_sel_hi:[1,0,1]
	v_lshl_add_u64 v[54:55], v[158:159], 2, s[88:89]
	global_store_dwordx4 v[54:55], v[28:31], off
	v_add_u32_e32 v158, 0x40090, v148
	s_nop 0
	v_sub_f32_e32 v29, v59, v62
	v_sub_f32_e32 v28, v58, v62
	v_sub_f32_e32 v31, v61, v62
	v_sub_f32_e32 v30, v60, v62
	v_pk_mul_f32 v[30:31], v[62:63], v[30:31] op_sel:[1,0]
	v_pk_mul_f32 v[28:29], v[62:63], v[28:29] op_sel:[1,0]
	v_pk_fma_f32 v[26:27], v[92:93], v[30:31], v[26:27]
	v_pk_fma_f32 v[24:25], v[94:95], v[28:29], v[24:25]
	v_pk_fma_f32 v[26:27], v[66:67], s[78:79], v[26:27] op_sel_hi:[1,0,1]
	v_pk_fma_f32 v[24:25], v[64:65], s[78:79], v[24:25] op_sel_hi:[1,0,1]
	v_lshl_add_u64 v[28:29], v[158:159], 2, s[88:89]
	global_store_dwordx4 v[28:29], v[24:27], off
	v_add_u32_e32 v158, 0x48080, v148
	s_nop 0
	v_sub_f32_e32 v25, v73, v52
	v_sub_f32_e32 v24, v72, v52
	v_sub_f32_e32 v27, v75, v52
	v_sub_f32_e32 v26, v74, v52
	v_pk_mul_f32 v[26:27], v[52:53], v[26:27] op_sel:[1,0]
	v_pk_mul_f32 v[24:25], v[52:53], v[24:25] op_sel:[1,0]
	v_pk_fma_f32 v[22:23], v[96:97], v[26:27], v[22:23]
	v_pk_fma_f32 v[20:21], v[98:99], v[24:25], v[20:21]
	v_pk_fma_f32 v[22:23], v[70:71], s[78:79], v[22:23] op_sel_hi:[1,0,1]
	v_pk_fma_f32 v[20:21], v[68:69], s[78:79], v[20:21] op_sel_hi:[1,0,1]
	v_lshl_add_u64 v[24:25], v[158:159], 2, s[88:89]
	global_store_dwordx4 v[24:25], v[20:23], off
	v_add_u32_e32 v158, 0x48090, v148
	s_nop 0
	v_sub_f32_e32 v21, v77, v52
	v_sub_f32_e32 v20, v76, v52
	v_sub_f32_e32 v23, v79, v52
	v_sub_f32_e32 v22, v78, v52
	v_pk_mul_f32 v[22:23], v[52:53], v[22:23] op_sel:[1,0]
	v_pk_mul_f32 v[20:21], v[52:53], v[20:21] op_sel:[1,0]
	v_pk_fma_f32 v[18:19], v[92:93], v[22:23], v[18:19]
	v_pk_fma_f32 v[16:17], v[94:95], v[20:21], v[16:17]
	v_pk_fma_f32 v[18:19], v[66:67], s[78:79], v[18:19] op_sel_hi:[1,0,1]
	v_pk_fma_f32 v[16:17], v[64:65], s[78:79], v[16:17] op_sel_hi:[1,0,1]
	v_lshl_add_u64 v[20:21], v[158:159], 2, s[88:89]
	global_store_dwordx4 v[20:21], v[16:19], off
	v_add_u32_e32 v158, 0x50080, v148
	s_nop 0
	v_sub_f32_e32 v17, v45, v50
	v_sub_f32_e32 v16, v44, v50
	v_sub_f32_e32 v19, v47, v50
	v_sub_f32_e32 v18, v46, v50
	v_pk_mul_f32 v[18:19], v[50:51], v[18:19] op_sel:[1,0]
	v_pk_mul_f32 v[16:17], v[50:51], v[16:17] op_sel:[1,0]
	v_pk_fma_f32 v[14:15], v[96:97], v[18:19], v[14:15]
	v_pk_fma_f32 v[12:13], v[98:99], v[16:17], v[12:13]
	v_pk_fma_f32 v[14:15], v[70:71], s[78:79], v[14:15] op_sel_hi:[1,0,1]
	v_pk_fma_f32 v[12:13], v[68:69], s[78:79], v[12:13] op_sel_hi:[1,0,1]
	v_lshl_add_u64 v[16:17], v[158:159], 2, s[88:89]
	global_store_dwordx4 v[16:17], v[12:15], off
	v_add_u32_e32 v158, 0x50090, v148
	s_nop 0
	v_sub_f32_e32 v13, v41, v50
	v_sub_f32_e32 v12, v40, v50
	v_sub_f32_e32 v15, v43, v50
	v_sub_f32_e32 v14, v42, v50
	v_pk_mul_f32 v[14:15], v[50:51], v[14:15] op_sel:[1,0]
	v_pk_mul_f32 v[12:13], v[50:51], v[12:13] op_sel:[1,0]
	v_pk_fma_f32 v[10:11], v[92:93], v[14:15], v[10:11]
	v_pk_fma_f32 v[8:9], v[94:95], v[12:13], v[8:9]
	v_pk_fma_f32 v[10:11], v[66:67], s[78:79], v[10:11] op_sel_hi:[1,0,1]
	v_pk_fma_f32 v[8:9], v[64:65], s[78:79], v[8:9] op_sel_hi:[1,0,1]
	v_lshl_add_u64 v[12:13], v[158:159], 2, s[88:89]
	global_store_dwordx4 v[12:13], v[8:11], off
	v_add_u32_e32 v158, 0x58080, v148
	s_nop 0
	v_sub_f32_e32 v9, v37, v48
	v_sub_f32_e32 v8, v36, v48
	v_sub_f32_e32 v11, v39, v48
	v_sub_f32_e32 v10, v38, v48
	v_pk_mul_f32 v[10:11], v[48:49], v[10:11] op_sel:[1,0]
	v_pk_mul_f32 v[8:9], v[48:49], v[8:9] op_sel:[1,0]
	v_pk_fma_f32 v[6:7], v[96:97], v[10:11], v[6:7]
	v_pk_fma_f32 v[4:5], v[98:99], v[8:9], v[4:5]
	v_pk_fma_f32 v[6:7], v[70:71], s[78:79], v[6:7] op_sel_hi:[1,0,1]
	v_pk_fma_f32 v[4:5], v[68:69], s[78:79], v[4:5] op_sel_hi:[1,0,1]
	v_lshl_add_u64 v[8:9], v[158:159], 2, s[88:89]
	global_store_dwordx4 v[8:9], v[4:7], off
	v_add_u32_e32 v158, 0x58090, v148
	s_nop 0
	v_sub_f32_e32 v5, v33, v48
	v_sub_f32_e32 v4, v32, v48
	v_sub_f32_e32 v7, v35, v48
	v_sub_f32_e32 v6, v34, v48
	v_pk_mul_f32 v[6:7], v[48:49], v[6:7] op_sel:[1,0]
	v_pk_mul_f32 v[4:5], v[48:49], v[4:5] op_sel:[1,0]
	v_pk_fma_f32 v[2:3], v[92:93], v[6:7], v[2:3]
	v_pk_fma_f32 v[0:1], v[94:95], v[4:5], v[0:1]
	v_pk_fma_f32 v[2:3], v[66:67], s[78:79], v[2:3] op_sel_hi:[1,0,1]
	v_pk_fma_f32 v[0:1], v[64:65], s[78:79], v[0:1] op_sel_hi:[1,0,1]
	v_lshl_add_u64 v[4:5], v[158:159], 2, s[88:89]
	global_store_dwordx4 v[4:5], v[0:3], off
	s_and_b64 vcc, exec, s[6:7]
	s_mov_b32 s2, s37
	s_mov_b32 s3, s38
	s_mov_b64 s[18:19], s[10:11]
	s_mov_b64 s[16:17], s[8:9]
	v_readlane_b32 s33, v255, 39
	s_cbranch_vccz .LBB0_123
	s_waitcnt vmcnt(0)
	s_cmpk_gt_u32 s24, 0xff
	s_cbranch_scc1 .LBB0_138
	s_barrier

; #define PG8_STAGE(bufoff, gbase) do { _Pragma("unroll") for (int _i = 0; _i < 2; ++_i) \
;         __builtin_amdgcn_global_load_lds((const unsigned*)((const char*)(gbase) + voff[_i]), (LAS unsigned*)(lds + (bufoff) + ldsw + _i * 8192), 16, 0, 0); } while (0)
; #define PG8_LDA(dst, b, h) do { _Pragma("unroll") for (int m = 0; m < 4; ++m) _Pragma("unroll") for (int k = 0; k < 2; ++k) dst[m][k] = *(const LAS bf16x8*)(lds + PG8_SA(b, h) + aoff + m * 2048 + k * 1024); } while (0)
; #define PG8_LDB(dst, b, h) do { _Pragma("unroll") for (int n = 0; n < 2; ++n) _Pragma("unroll") for (int k = 0; k < 2; ++k) dst[n][k] = *(const LAS bf16x8*)(lds + PG8_SB(b, h) + boff + n * 2048 + k * 1024); } while (0)
; #define PG8_MMA(ai, bj, At, Bt) do { __builtin_amdgcn_s_setprio(1); _Pragma("unroll") for (int m = 0; m < 4; ++m) _Pragma("unroll") for (int n = 0; n < 2; ++n) _Pragma("unroll") for (int k = 0; k < 2; ++k) \
;         acc[ai][bj][m][n] = __builtin_amdgcn_mfma_f32_16x16x32_bf16(Bt[n][k], At[m][k], acc[ai][bj][m][n], 0, 0, 0); __builtin_amdgcn_s_setprio(0); } while (0)
; #define PG8_WAIT_V(n) asm volatile("s_waitcnt vmcnt(" #n ")" ::: "memory")
; #define PG8_WAIT_L(n) asm volatile("s_waitcnt lgkmcnt(" #n ")" ::: "memory")
; #define PG8_BAR __builtin_amdgcn_s_barrier()
; #define PG8_SCHED __builtin_amdgcn_sched_barrier(0)
; template <class Epi>
; DI void gemm_phase(LAS unsigned char* lds, const Gemm g, const StaticOrder& S, const Epi& E) {
;     ...
;         for (int t = 0; t < nt; t += 2) {
;             const bool last = (t == nt - 2);
;             const char* a1 = cA + (size_t)(t + 1) * kstep;
;             const char* a2 = last ? nA : cA + (size_t)(t + 2) * kstep; const char* b2 = last ? nB : cB + (size_t)(t + 2) * kstep;
;             const char* a3 = a2 + kstep; const char* b3 = b2 + kstep;
;             PG8_LDB(B0, 0, 0); PG8_SCHED; PG8_LDA(At, 0, 0); PG8_STAGE(PG8_SA(1, 1), a1 + hstep);
;             PG8_WAIT_L(8); PG8_BAR; PG8_WAIT_L(0); PG8_MMA(0, 0, At, B0); PG8_BAR; PG8_SCHED;
;             PG8_LDB(B1, 0, 1); PG8_STAGE(PG8_SB(0, 0), b2);
;             PG8_BAR; PG8_WAIT_L(0); PG8_MMA(0, 1, At, B1); PG8_BAR;
;             PG8_LDA(At, 0, 1); PG8_STAGE(PG8_SA(0, 0), a2);
;             PG8_BAR; PG8_WAIT_L(0); PG8_MMA(1, 0, At, B0); PG8_BAR; PG8_SCHED;
;             PG8_STAGE(PG8_SB(0, 1), b2 + hstep);
;             PG8_WAIT_V(6); PG8_BAR; PG8_MMA(1, 1, At, B1); PG8_BAR;
.LBB0_202:
	s_add_u32 s18, s8, 0xfff80080
	s_addc_u32 s19, s9, -1
	s_add_i32 s37, 0, 0x10000
	s_waitcnt lgkmcnt(0)
	ds_read_b128 v[128:131], v187
	ds_read_b128 v[132:135], v187 offset:1024
	ds_read_b128 v[136:139], v187 offset:2048
	ds_read_b128 v[190:193], v187 offset:3072
	s_cmp_eq_u32 s36, 28
	s_cselect_b32 s21, s4, s19
	s_cselect_b32 s20, s5, s18
	s_cselect_b32 s19, s11, s35
	s_cselect_b32 s18, s13, s33
	s_add_i32 m0, s26, 0xc000
	ds_read_b128 v[194:197], v189
	ds_read_b128 v[198:201], v189 offset:1024
	ds_read_b128 v[202:205], v189 offset:2048
	ds_read_b128 v[206:209], v189 offset:3072
	ds_read_b128 v[210:213], v189 offset:4096
	ds_read_b128 v[214:217], v189 offset:5120
	ds_read_b128 v[226:229], v189 offset:6144
	ds_read_b128 v[230:233], v189 offset:7168
	global_load_lds_dwordx4 v150, s[8:9]
	s_add_i32 m0, s26, 0xe000
	s_nop 0
	global_load_lds_dwordx4 v152, s[8:9]
	s_waitcnt lgkmcnt(8)
	s_setprio 1
	s_barrier
	s_waitcnt lgkmcnt(0)
	v_mfma_f32_16x16x32_bf16 v[124:127], v[128:131], v[194:197], v[124:127]
	v_mfma_f32_16x16x32_bf16 v[120:123], v[136:139], v[194:197], v[120:123]
	v_mfma_f32_16x16x32_bf16 v[108:111], v[128:131], v[202:205], v[108:111]
	v_mfma_f32_16x16x32_bf16 v[104:107], v[136:139], v[202:205], v[104:107]
	v_mfma_f32_16x16x32_bf16 v[92:95], v[128:131], v[210:213], v[92:95]
	v_mfma_f32_16x16x32_bf16 v[88:91], v[136:139], v[210:213], v[88:91]
	v_mfma_f32_16x16x32_bf16 v[76:79], v[128:131], v[226:229], v[76:79]
	v_mfma_f32_16x16x32_bf16 v[72:75], v[136:139], v[226:229], v[72:75]
	v_mfma_f32_16x16x32_bf16 v[124:127], v[132:135], v[198:201], v[124:127]
	v_mfma_f32_16x16x32_bf16 v[120:123], v[190:193], v[198:201], v[120:123]
	ds_read_b128 v[234:237], v187 offset:16384
	v_mfma_f32_16x16x32_bf16 v[108:111], v[132:135], v[206:209], v[108:111]
	ds_read_b128 v[238:241], v187 offset:17408
	v_mfma_f32_16x16x32_bf16 v[104:107], v[190:193], v[206:209], v[104:107]
	ds_read_b128 v[242:245], v187 offset:18432
	v_mfma_f32_16x16x32_bf16 v[92:95], v[132:135], v[214:217], v[92:95]
	ds_read_b128 v[246:249], v187 offset:19456
	v_mfma_f32_16x16x32_bf16 v[88:91], v[190:193], v[214:217], v[88:91]
	v_mfma_f32_16x16x32_bf16 v[76:79], v[132:135], v[230:233], v[76:79]
	s_setprio 0
	v_mfma_f32_16x16x32_bf16 v[72:75], v[190:193], v[230:233], v[72:75]
	s_barrier
	s_add_i32 s40, 0, 0x14000
	s_add_i32 s37, s37, s25
	s_mov_b32 m0, s37
	s_nop 0
	global_load_lds_dwordx4 v144, s[18:19]
	s_add_i32 m0, s37, 0x2000
	s_nop 0
	global_load_lds_dwordx4 v142, s[18:19]
	s_waitcnt lgkmcnt(0)
	s_setprio 1
	s_barrier
	v_mfma_f32_16x16x32_bf16 v[116:119], v[234:237], v[194:197], v[116:119]
	v_mfma_f32_16x16x32_bf16 v[112:115], v[242:245], v[194:197], v[112:115]
	v_mfma_f32_16x16x32_bf16 v[100:103], v[234:237], v[202:205], v[100:103]
	v_mfma_f32_16x16x32_bf16 v[96:99], v[242:245], v[202:205], v[96:99]
	v_mfma_f32_16x16x32_bf16 v[84:87], v[234:237], v[210:213], v[84:87]
	v_mfma_f32_16x16x32_bf16 v[80:83], v[242:245], v[210:213], v[80:83]
	v_mfma_f32_16x16x32_bf16 v[68:71], v[234:237], v[226:229], v[68:71]
	v_mfma_f32_16x16x32_bf16 v[64:67], v[242:245], v[226:229], v[64:67]
	v_mfma_f32_16x16x32_bf16 v[116:119], v[238:241], v[198:201], v[116:119]
	ds_read_b128 v[194:197], v189 offset:16384
	s_mov_b32 m0, s26
	v_mfma_f32_16x16x32_bf16 v[112:115], v[246:249], v[198:201], v[112:115]
	ds_read_b128 v[198:201], v189 offset:17408
	v_mfma_f32_16x16x32_bf16 v[100:103], v[238:241], v[206:209], v[100:103]
	ds_read_b128 v[202:205], v189 offset:18432
	v_mfma_f32_16x16x32_bf16 v[96:99], v[246:249], v[206:209], v[96:99]
	ds_read_b128 v[206:209], v189 offset:19456
	v_mfma_f32_16x16x32_bf16 v[84:87], v[238:241], v[214:217], v[84:87]
	ds_read_b128 v[210:213], v189 offset:20480
	v_mfma_f32_16x16x32_bf16 v[80:83], v[246:249], v[214:217], v[80:83]
	ds_read_b128 v[214:217], v189 offset:21504
	v_mfma_f32_16x16x32_bf16 v[68:71], v[238:241], v[230:233], v[68:71]
	ds_read_b128 v[226:229], v189 offset:22528
	s_setprio 0
	v_mfma_f32_16x16x32_bf16 v[64:67], v[246:249], v[230:233], v[64:67]
	s_barrier
	ds_read_b128 v[230:233], v189 offset:23552
	global_load_lds_dwordx4 v144, s[20:21]
	s_mov_b64 s[100:101], s[20:21]
	s_mov_b32 m0, s27
	s_nop 0
	global_load_lds_dwordx4 v142, s[20:21]
	s_waitcnt lgkmcnt(0)
	s_setprio 1
	s_barrier
	v_mfma_f32_16x16x32_bf16 v[60:63], v[128:131], v[194:197], v[60:63]
	v_mfma_f32_16x16x32_bf16 v[56:59], v[136:139], v[194:197], v[56:59]
	v_mfma_f32_16x16x32_bf16 v[44:47], v[128:131], v[202:205], v[44:47]
	v_mfma_f32_16x16x32_bf16 v[40:43], v[136:139], v[202:205], v[40:43]
	v_mfma_f32_16x16x32_bf16 v[28:31], v[128:131], v[210:213], v[28:31]
	v_mfma_f32_16x16x32_bf16 v[24:27], v[136:139], v[210:213], v[24:27]
	v_mfma_f32_16x16x32_bf16 v[12:15], v[128:131], v[226:229], v[12:15]
	v_mfma_f32_16x16x32_bf16 v[8:11], v[136:139], v[226:229], v[8:11]
	v_mfma_f32_16x16x32_bf16 v[60:63], v[132:135], v[198:201], v[60:63]
	v_mfma_f32_16x16x32_bf16 v[56:59], v[190:193], v[198:201], v[56:59]
	v_mfma_f32_16x16x32_bf16 v[44:47], v[132:135], v[206:209], v[44:47]
	v_mfma_f32_16x16x32_bf16 v[40:43], v[190:193], v[206:209], v[40:43]
	v_mfma_f32_16x16x32_bf16 v[28:31], v[132:135], v[214:217], v[28:31]
	v_mfma_f32_16x16x32_bf16 v[24:27], v[190:193], v[214:217], v[24:27]
	v_mfma_f32_16x16x32_bf16 v[12:15], v[132:135], v[230:233], v[12:15]
	s_setprio 0
	v_mfma_f32_16x16x32_bf16 v[8:11], v[190:193], v[230:233], v[8:11]
	s_barrier
	s_add_u32 s38, s18, 0x80000
	s_addc_u32 s39, s19, 0
	s_add_i32 s37, s40, s25
	s_mov_b32 m0, s37
	s_nop 0
	global_load_lds_dwordx4 v144, s[38:39]
	s_add_i32 m0, s37, 0x2000
	s_nop 0
	global_load_lds_dwordx4 v142, s[38:39]
	s_waitcnt vmcnt(6)
	s_setprio 1
	s_barrier
; #define PG8_STAGE(bufoff, gbase) do { _Pragma("unroll") for (int _i = 0; _i < 2; ++_i) \
;         __builtin_amdgcn_global_load_lds((const unsigned*)((const char*)(gbase) + voff[_i]), (LAS unsigned*)(lds + (bufoff) + ldsw + _i * 8192), 16, 0, 0); } while (0)
; #define PG8_LDA(dst, b, h) do { _Pragma("unroll") for (int m = 0; m < 4; ++m) _Pragma("unroll") for (int k = 0; k < 2; ++k) dst[m][k] = *(const LAS bf16x8*)(lds + PG8_SA(b, h) + aoff + m * 2048 + k * 1024); } while (0)
; #define PG8_LDB(dst, b, h) do { _Pragma("unroll") for (int n = 0; n < 2; ++n) _Pragma("unroll") for (int k = 0; k < 2; ++k) dst[n][k] = *(const LAS bf16x8*)(lds + PG8_SB(b, h) + boff + n * 2048 + k * 1024); } while (0)
; #define PG8_MMA(ai, bj, At, Bt) do { __builtin_amdgcn_s_setprio(1); _Pragma("unroll") for (int m = 0; m < 4; ++m) _Pragma("unroll") for (int n = 0; n < 2; ++n) _Pragma("unroll") for (int k = 0; k < 2; ++k) \
;         acc[ai][bj][m][n] = __builtin_amdgcn_mfma_f32_16x16x32_bf16(Bt[n][k], At[m][k], acc[ai][bj][m][n], 0, 0, 0); __builtin_amdgcn_s_setprio(0); } while (0)
; #define PG8_WAIT_V(n) asm volatile("s_waitcnt vmcnt(" #n ")" ::: "memory")
; #define PG8_WAIT_L(n) asm volatile("s_waitcnt lgkmcnt(" #n ")" ::: "memory")
; #define PG8_BAR __builtin_amdgcn_s_barrier()
; #define PG8_SCHED __builtin_amdgcn_sched_barrier(0)
; template <class Epi>
; DI void gemm_phase(LAS unsigned char* lds, const Gemm g, const StaticOrder& S, const Epi& E) {
;     ...
;             PG8_STAGE(PG8_SB(0, 1), b2 + hstep);
;             PG8_WAIT_V(6); PG8_BAR; PG8_MMA(1, 1, At, B1); PG8_BAR;
;             PG8_LDB(B0, 1, 0); PG8_SCHED; PG8_LDA(At, 1, 0); PG8_STAGE(PG8_SA(0, 1), a2 + hstep);
;             PG8_WAIT_L(8); PG8_BAR; PG8_WAIT_L(0); PG8_MMA(0, 0, At, B0); PG8_BAR; PG8_SCHED;
;             PG8_LDB(B1, 1, 1); PG8_STAGE(PG8_SB(1, 0), b3);
;             PG8_BAR; PG8_WAIT_L(0); PG8_MMA(0, 1, At, B1); PG8_BAR;
;             PG8_LDA(At, 1, 1); PG8_STAGE(PG8_SA(1, 0), a3);
	v_mfma_f32_16x16x32_bf16 v[52:55], v[234:237], v[194:197], v[52:55]
	v_mfma_f32_16x16x32_bf16 v[48:51], v[242:245], v[194:197], v[48:51]
	v_mfma_f32_16x16x32_bf16 v[36:39], v[234:237], v[202:205], v[36:39]
	v_mfma_f32_16x16x32_bf16 v[32:35], v[242:245], v[202:205], v[32:35]
	v_mfma_f32_16x16x32_bf16 v[20:23], v[234:237], v[210:213], v[20:23]
	v_mfma_f32_16x16x32_bf16 v[16:19], v[242:245], v[210:213], v[16:19]
	v_mfma_f32_16x16x32_bf16 v[4:7], v[234:237], v[226:229], v[4:7]
	v_mfma_f32_16x16x32_bf16 v[0:3], v[242:245], v[226:229], v[0:3]
	v_mfma_f32_16x16x32_bf16 v[52:55], v[238:241], v[198:201], v[52:55]
	s_add_i32 s37, 0, 0x18000
	v_mfma_f32_16x16x32_bf16 v[48:51], v[246:249], v[198:201], v[48:51]
	v_mfma_f32_16x16x32_bf16 v[36:39], v[238:241], v[206:209], v[36:39]
	v_mfma_f32_16x16x32_bf16 v[32:35], v[246:249], v[206:209], v[32:35]
	v_mfma_f32_16x16x32_bf16 v[20:23], v[238:241], v[214:217], v[20:23]
	v_mfma_f32_16x16x32_bf16 v[16:19], v[246:249], v[214:217], v[16:19]
	v_mfma_f32_16x16x32_bf16 v[4:7], v[238:241], v[230:233], v[4:7]
	s_setprio 0
	v_mfma_f32_16x16x32_bf16 v[0:3], v[246:249], v[230:233], v[0:3]
	s_barrier
	ds_read_b128 v[128:131], v187 offset:32768
	ds_read_b128 v[132:135], v187 offset:33792
	ds_read_b128 v[136:139], v187 offset:34816
	ds_read_b128 v[190:193], v187 offset:35840
	ds_read_b128 v[194:197], v189 offset:32768
	ds_read_b128 v[198:201], v189 offset:33792
	ds_read_b128 v[202:205], v189 offset:34816
	ds_read_b128 v[206:209], v189 offset:35840
	ds_read_b128 v[210:213], v189 offset:36864
	ds_read_b128 v[214:217], v189 offset:37888
	ds_read_b128 v[226:229], v189 offset:38912
	ds_read_b128 v[230:233], v189 offset:39936
	s_add_u32 s20, s20, 0x80000
	s_addc_u32 s21, s21, 0
	s_mov_b32 m0, s28
	s_nop 0
	global_load_lds_dwordx4 v144, s[20:21]
	s_mov_b32 m0, s29
	s_nop 0
	global_load_lds_dwordx4 v142, s[20:21]
	s_waitcnt lgkmcnt(8)
	s_setprio 1
	s_barrier
	s_waitcnt lgkmcnt(0)
	v_mfma_f32_16x16x32_bf16 v[124:127], v[128:131], v[194:197], v[124:127]
	v_mfma_f32_16x16x32_bf16 v[120:123], v[136:139], v[194:197], v[120:123]
	v_mfma_f32_16x16x32_bf16 v[108:111], v[128:131], v[202:205], v[108:111]
	v_mfma_f32_16x16x32_bf16 v[104:107], v[136:139], v[202:205], v[104:107]
	v_mfma_f32_16x16x32_bf16 v[92:95], v[128:131], v[210:213], v[92:95]
	v_mfma_f32_16x16x32_bf16 v[88:91], v[136:139], v[210:213], v[88:91]
	v_mfma_f32_16x16x32_bf16 v[76:79], v[128:131], v[226:229], v[76:79]
	v_mfma_f32_16x16x32_bf16 v[72:75], v[136:139], v[226:229], v[72:75]
	v_mfma_f32_16x16x32_bf16 v[124:127], v[132:135], v[198:201], v[124:127]
	v_mfma_f32_16x16x32_bf16 v[120:123], v[190:193], v[198:201], v[120:123]
	ds_read_b128 v[234:237], v187 offset:49152
	v_mfma_f32_16x16x32_bf16 v[108:111], v[132:135], v[206:209], v[108:111]
	ds_read_b128 v[238:241], v187 offset:50176
	v_mfma_f32_16x16x32_bf16 v[104:107], v[190:193], v[206:209], v[104:107]
	ds_read_b128 v[242:245], v187 offset:51200
	v_mfma_f32_16x16x32_bf16 v[92:95], v[132:135], v[214:217], v[92:95]
	ds_read_b128 v[246:249], v187 offset:52224
	v_mfma_f32_16x16x32_bf16 v[88:91], v[190:193], v[214:217], v[88:91]
	v_mfma_f32_16x16x32_bf16 v[76:79], v[132:135], v[230:233], v[76:79]
	s_setprio 0
	v_mfma_f32_16x16x32_bf16 v[72:75], v[190:193], v[230:233], v[72:75]
	s_barrier
	s_add_i32 s20, 0, 0x1c000
	s_add_i32 s21, s37, s25
	s_add_i32 m0, s21, 0xffffff80
	s_nop 0
	global_load_lds_dwordx4 v144, s[18:19] offset:128
	s_add_i32 m0, s21, 0x1f80
	s_nop 0
	global_load_lds_dwordx4 v142, s[18:19] offset:128
	s_waitcnt lgkmcnt(0)
	s_setprio 1
	s_barrier
	v_mfma_f32_16x16x32_bf16 v[116:119], v[234:237], v[194:197], v[116:119]
	v_mfma_f32_16x16x32_bf16 v[112:115], v[242:245], v[194:197], v[112:115]
	v_mfma_f32_16x16x32_bf16 v[100:103], v[234:237], v[202:205], v[100:103]
	v_mfma_f32_16x16x32_bf16 v[96:99], v[242:245], v[202:205], v[96:99]
	v_mfma_f32_16x16x32_bf16 v[84:87], v[234:237], v[210:213], v[84:87]
	v_mfma_f32_16x16x32_bf16 v[80:83], v[242:245], v[210:213], v[80:83]
	v_mfma_f32_16x16x32_bf16 v[68:71], v[234:237], v[226:229], v[68:71]
	v_mfma_f32_16x16x32_bf16 v[64:67], v[242:245], v[226:229], v[64:67]
	v_mfma_f32_16x16x32_bf16 v[116:119], v[238:241], v[198:201], v[116:119]
	ds_read_b128 v[194:197], v189 offset:49152
	s_add_i32 m0, s30, 0xffffff80
	v_mfma_f32_16x16x32_bf16 v[112:115], v[246:249], v[198:201], v[112:115]
	ds_read_b128 v[198:201], v189 offset:50176
	v_mfma_f32_16x16x32_bf16 v[100:103], v[238:241], v[206:209], v[100:103]
	ds_read_b128 v[202:205], v189 offset:51200
	v_mfma_f32_16x16x32_bf16 v[96:99], v[246:249], v[206:209], v[96:99]
	ds_read_b128 v[206:209], v189 offset:52224
	v_mfma_f32_16x16x32_bf16 v[84:87], v[238:241], v[214:217], v[84:87]
	ds_read_b128 v[210:213], v189 offset:53248
	v_mfma_f32_16x16x32_bf16 v[80:83], v[246:249], v[214:217], v[80:83]
	ds_read_b128 v[214:217], v189 offset:54272
	v_mfma_f32_16x16x32_bf16 v[68:71], v[238:241], v[230:233], v[68:71]
	ds_read_b128 v[226:229], v189 offset:55296
	s_setprio 0
	v_mfma_f32_16x16x32_bf16 v[64:67], v[246:249], v[230:233], v[64:67]
	s_barrier
; #define PG8_STAGE(bufoff, gbase) do { _Pragma("unroll") for (int _i = 0; _i < 2; ++_i) \
;         __builtin_amdgcn_global_load_lds((const unsigned*)((const char*)(gbase) + voff[_i]), (LAS unsigned*)(lds + (bufoff) + ldsw + _i * 8192), 16, 0, 0); } while (0)
; #define PG8_LDA(dst, b, h) do { _Pragma("unroll") for (int m = 0; m < 4; ++m) _Pragma("unroll") for (int k = 0; k < 2; ++k) dst[m][k] = *(const LAS bf16x8*)(lds + PG8_SA(b, h) + aoff + m * 2048 + k * 1024); } while (0)
; #define PG8_MMA(ai, bj, At, Bt) do { __builtin_amdgcn_s_setprio(1); _Pragma("unroll") for (int m = 0; m < 4; ++m) _Pragma("unroll") for (int n = 0; n < 2; ++n) _Pragma("unroll") for (int k = 0; k < 2; ++k) \
;         acc[ai][bj][m][n] = __builtin_amdgcn_mfma_f32_16x16x32_bf16(Bt[n][k], At[m][k], acc[ai][bj][m][n], 0, 0, 0); __builtin_amdgcn_s_setprio(0); } while (0)
; #define PG8_WAIT_V(n) asm volatile("s_waitcnt vmcnt(" #n ")" ::: "memory")
; #define PG8_WAIT_L(n) asm volatile("s_waitcnt lgkmcnt(" #n ")" ::: "memory")
; #define PG8_BAR __builtin_amdgcn_s_barrier()
; #define PG8_SCHED __builtin_amdgcn_sched_barrier(0)
; template <class Epi>
; DI void gemm_phase(LAS unsigned char* lds, const Gemm g, const StaticOrder& S, const Epi& E) {
;     ...
;             PG8_LDA(At, 1, 1); PG8_STAGE(PG8_SA(1, 0), a3);
;             PG8_BAR; PG8_WAIT_L(0); PG8_MMA(1, 0, At, B0); PG8_BAR; PG8_SCHED;
;             PG8_STAGE(PG8_SB(1, 1), b3 + hstep);
;             PG8_WAIT_V(6); PG8_BAR; PG8_MMA(1, 1, At, B1); PG8_BAR;
;     DI void operator()(const f32x4 (&acc)[2][2][4][2], const Unit& u, int wr, int wc, int fr, int fq) const {
;         const int row0 = u.pm * BM + wr * 64 + fr, col0 = u.pn * BM + wc * 16 + 4 * fq;
;         const bool rot = u.pn < 18;
; #pragma unroll
;         for (int ai = 0; ai < 2; ++ai)
; #pragma unroll
;             for (int m = 0; m < 4; ++m) { const int row = row0 + ai * HALF + m * 16; u16* rowp = O + (size_t)row * NQKV_DIL + col0;
;                 f32x4 c4 = (f32x4){1.f, 1.f, 1.f, 1.f}, s4 = (f32x4){0.f, 0.f, 0.f, 0.f};
;                 if (rot) { const int pos = row & (SEQ - 1); c4 = *(const f32x4*)(cs + pos * 64 + wc * 16 + 4 * fq); s4 = *(const f32x4*)(sn + pos * 64 + wc * 16 + 4 * fq); }
	ds_read_b128 v[230:233], v189 offset:56320
	global_load_lds_dwordx4 v144, s[100:101] offset:128
	s_add_i32 m0, s31, 0xffffff80
	s_nop 0
	global_load_lds_dwordx4 v142, s[100:101] offset:128
	s_waitcnt lgkmcnt(0)
	s_setprio 1
	s_barrier
	v_mfma_f32_16x16x32_bf16 v[60:63], v[128:131], v[194:197], v[60:63]
	v_mfma_f32_16x16x32_bf16 v[56:59], v[136:139], v[194:197], v[56:59]
	v_mfma_f32_16x16x32_bf16 v[44:47], v[128:131], v[202:205], v[44:47]
	v_mfma_f32_16x16x32_bf16 v[40:43], v[136:139], v[202:205], v[40:43]
	v_mfma_f32_16x16x32_bf16 v[28:31], v[128:131], v[210:213], v[28:31]
	v_mfma_f32_16x16x32_bf16 v[24:27], v[136:139], v[210:213], v[24:27]
	v_mfma_f32_16x16x32_bf16 v[12:15], v[128:131], v[226:229], v[12:15]
	v_mfma_f32_16x16x32_bf16 v[8:11], v[136:139], v[226:229], v[8:11]
	v_mfma_f32_16x16x32_bf16 v[60:63], v[132:135], v[198:201], v[60:63]
	v_mfma_f32_16x16x32_bf16 v[56:59], v[190:193], v[198:201], v[56:59]
	v_mfma_f32_16x16x32_bf16 v[44:47], v[132:135], v[206:209], v[44:47]
	v_mfma_f32_16x16x32_bf16 v[40:43], v[190:193], v[206:209], v[40:43]
	v_mfma_f32_16x16x32_bf16 v[28:31], v[132:135], v[214:217], v[28:31]
	v_mfma_f32_16x16x32_bf16 v[24:27], v[190:193], v[214:217], v[24:27]
	v_mfma_f32_16x16x32_bf16 v[12:15], v[132:135], v[230:233], v[12:15]
	s_setprio 0
	v_mfma_f32_16x16x32_bf16 v[8:11], v[190:193], v[230:233], v[8:11]
	s_barrier
	s_add_u32 s18, s18, 0x80080
	s_addc_u32 s19, s19, 0
	s_add_i32 s20, s20, s25
	s_mov_b32 m0, s20
	s_nop 0
	global_load_lds_dwordx4 v144, s[18:19]
	s_add_i32 m0, s20, 0x2000
	s_nop 0
	global_load_lds_dwordx4 v142, s[18:19]
	s_waitcnt vmcnt(6)
	s_setprio 1
	s_barrier
	v_mfma_f32_16x16x32_bf16 v[52:55], v[234:237], v[194:197], v[52:55]
	v_mfma_f32_16x16x32_bf16 v[48:51], v[242:245], v[194:197], v[48:51]
	v_mfma_f32_16x16x32_bf16 v[36:39], v[234:237], v[202:205], v[36:39]
	v_mfma_f32_16x16x32_bf16 v[32:35], v[242:245], v[202:205], v[32:35]
	v_mfma_f32_16x16x32_bf16 v[20:23], v[234:237], v[210:213], v[20:23]
	v_mfma_f32_16x16x32_bf16 v[16:19], v[242:245], v[210:213], v[16:19]
	v_mfma_f32_16x16x32_bf16 v[4:7], v[234:237], v[226:229], v[4:7]
	v_mfma_f32_16x16x32_bf16 v[0:3], v[242:245], v[226:229], v[0:3]
	v_mfma_f32_16x16x32_bf16 v[52:55], v[238:241], v[198:201], v[52:55]
	s_add_i32 s36, s36, 2
	v_mfma_f32_16x16x32_bf16 v[48:51], v[246:249], v[198:201], v[48:51]
	s_add_u32 s8, s8, 0x100
	v_mfma_f32_16x16x32_bf16 v[36:39], v[238:241], v[206:209], v[36:39]
	s_addc_u32 s9, s9, 0
	v_mfma_f32_16x16x32_bf16 v[32:35], v[246:249], v[206:209], v[32:35]
	s_add_u32 s33, s33, 0x100
	v_mfma_f32_16x16x32_bf16 v[20:23], v[238:241], v[214:217], v[20:23]
	s_addc_u32 s35, s35, 0
	v_mfma_f32_16x16x32_bf16 v[16:19], v[246:249], v[214:217], v[16:19]
	s_cmp_gt_u32 s36, 29
	v_mfma_f32_16x16x32_bf16 v[4:7], v[238:241], v[230:233], v[4:7]
	s_setprio 0
	v_mfma_f32_16x16x32_bf16 v[0:3], v[246:249], v[230:233], v[0:3]
	s_barrier
	s_cbranch_scc0 .LBB0_202
	s_cmp_lt_i32 s2, 18
	v_lshl_add_u32 v190, s3, 8, v186
	v_mov_b32_e32 v128, 1.0
	v_mov_b32_e32 v132, 0
	s_cselect_b64 s[18:19], -1, 0
	s_cmp_gt_i32 s2, 17
	v_mov_b32_e32 v134, 0
	v_mov_b32_e32 v135, 0
	v_mov_b32_e32 v136, 0
	v_mov_b32_e32 v137, 0
	v_mov_b32_e32 v138, 1.0
	v_mov_b32_e32 v139, 1.0
	v_mov_b32_e32 v140, 1.0
	v_mov_b32_e32 v141, 1.0
	s_cbranch_scc1 .LBB0_205
	v_lshlrev_b32_e32 v129, 8, v190
	v_and_b32_e32 v158, 0xfcf00, v129
	v_lshl_add_u64 v[130:131], v[146:147], 0, v[158:159]
	v_lshl_add_u64 v[134:135], v[148:149], 0, v[158:159]
	global_load_dwordx4 v[138:141], v[130:131], off
	s_nop 0
	global_load_dwordx4 v[134:137], v[134:135], off

; #define PG8_STAGE(bufoff, gbase) do { _Pragma("unroll") for (int _i = 0; _i < 2; ++_i) \
;         __builtin_amdgcn_global_load_lds((const unsigned*)((const char*)(gbase) + voff[_i]), (LAS unsigned*)(lds + (bufoff) + ldsw + _i * 8192), 16, 0, 0); } while (0)
; #define PG8_LDA(dst, b, h) do { _Pragma("unroll") for (int m = 0; m < 4; ++m) _Pragma("unroll") for (int k = 0; k < 2; ++k) dst[m][k] = *(const LAS bf16x8*)(lds + PG8_SA(b, h) + aoff + m * 2048 + k * 1024); } while (0)
; #define PG8_LDB(dst, b, h) do { _Pragma("unroll") for (int n = 0; n < 2; ++n) _Pragma("unroll") for (int k = 0; k < 2; ++k) dst[n][k] = *(const LAS bf16x8*)(lds + PG8_SB(b, h) + boff + n * 2048 + k * 1024); } while (0)
; #define PG8_MMA(ai, bj, At, Bt) do { __builtin_amdgcn_s_setprio(1); _Pragma("unroll") for (int m = 0; m < 4; ++m) _Pragma("unroll") for (int n = 0; n < 2; ++n) _Pragma("unroll") for (int k = 0; k < 2; ++k) \
;         acc[ai][bj][m][n] = __builtin_amdgcn_mfma_f32_16x16x32_bf16(Bt[n][k], At[m][k], acc[ai][bj][m][n], 0, 0, 0); __builtin_amdgcn_s_setprio(0); } while (0)
; #define PG8_WAIT_V(n) asm volatile("s_waitcnt vmcnt(" #n ")" ::: "memory")
; #define PG8_WAIT_L(n) asm volatile("s_waitcnt lgkmcnt(" #n ")" ::: "memory")
; #define PG8_BAR __builtin_amdgcn_s_barrier()
; #define PG8_SCHED __builtin_amdgcn_sched_barrier(0)
; template <class Epi>
; DI void gemm_phase(LAS unsigned char* lds, const Gemm g, const StaticOrder& S, const Epi& E) {
;     ...
;         for (int t = 0; t < nt; t += 2) {
;             const bool last = (t == nt - 2);
;             const char* a1 = cA + (size_t)(t + 1) * kstep;
;             const char* a2 = last ? nA : cA + (size_t)(t + 2) * kstep; const char* b2 = last ? nB : cB + (size_t)(t + 2) * kstep;
;             const char* a3 = a2 + kstep; const char* b3 = b2 + kstep;
;             PG8_LDB(B0, 0, 0); PG8_SCHED; PG8_LDA(At, 0, 0); PG8_STAGE(PG8_SA(1, 1), a1 + hstep);
;             PG8_WAIT_L(8); PG8_BAR; PG8_WAIT_L(0); PG8_MMA(0, 0, At, B0); PG8_BAR; PG8_SCHED;
;             PG8_LDB(B1, 0, 1); PG8_STAGE(PG8_SB(0, 0), b2);
;             PG8_BAR; PG8_WAIT_L(0); PG8_MMA(0, 1, At, B1); PG8_BAR;
;             PG8_LDA(At, 0, 1); PG8_STAGE(PG8_SA(0, 0), a2);
;             PG8_BAR; PG8_WAIT_L(0); PG8_MMA(1, 0, At, B0); PG8_BAR; PG8_SCHED;
;             PG8_STAGE(PG8_SB(0, 1), b2 + hstep);
;             PG8_WAIT_V(6); PG8_BAR; PG8_MMA(1, 1, At, B1); PG8_BAR;
.LBB0_231:
	ds_read_b128 v[138:141], v135
	ds_read_b128 v[142:145], v135 offset:1024
	ds_read_b128 v[146:149], v135 offset:2048
	ds_read_b128 v[150:153], v135 offset:3072
	ds_read_b128 v[186:189], v137
	ds_read_b128 v[190:193], v137 offset:1024
	ds_read_b128 v[194:197], v137 offset:2048
	ds_read_b128 v[198:201], v137 offset:3072
	ds_read_b128 v[202:205], v137 offset:4096
	ds_read_b128 v[206:209], v137 offset:5120
	ds_read_b128 v[210:213], v137 offset:6144
	ds_read_b128 v[214:217], v137 offset:7168
	s_add_u32 s18, s16, 0xfff80080
	s_addc_u32 s19, s17, -1
	s_add_i32 s37, 0, 0x10000
	s_cmp_eq_u32 s36, 28
	s_cselect_b32 s21, s4, s19
	s_cselect_b32 s20, s5, s18
	s_cselect_b32 s19, s9, s35
	s_cselect_b32 s18, s11, s34
	s_add_i32 m0, s24, 0xc000
	s_nop 0
	global_load_lds_dwordx4 v130, s[16:17]
	s_add_i32 m0, s24, 0xe000
	s_nop 0
	global_load_lds_dwordx4 v132, s[16:17]
	s_waitcnt lgkmcnt(8)
	s_setprio 1
	s_barrier
	s_waitcnt lgkmcnt(0)
	v_mfma_f32_16x16x32_bf16 v[124:127], v[138:141], v[186:189], v[124:127]
	v_mfma_f32_16x16x32_bf16 v[120:123], v[146:149], v[186:189], v[120:123]
	v_mfma_f32_16x16x32_bf16 v[116:119], v[138:141], v[194:197], v[116:119]
	v_mfma_f32_16x16x32_bf16 v[112:115], v[146:149], v[194:197], v[112:115]
	v_mfma_f32_16x16x32_bf16 v[100:103], v[138:141], v[202:205], v[100:103]
	v_mfma_f32_16x16x32_bf16 v[96:99], v[146:149], v[202:205], v[96:99]
	v_mfma_f32_16x16x32_bf16 v[84:87], v[138:141], v[210:213], v[84:87]
	v_mfma_f32_16x16x32_bf16 v[80:83], v[146:149], v[210:213], v[80:83]
	v_mfma_f32_16x16x32_bf16 v[124:127], v[142:145], v[190:193], v[124:127]
	v_mfma_f32_16x16x32_bf16 v[120:123], v[150:153], v[190:193], v[120:123]
	ds_read_b128 v[226:229], v135 offset:16384
	v_mfma_f32_16x16x32_bf16 v[116:119], v[142:145], v[198:201], v[116:119]
	ds_read_b128 v[230:233], v135 offset:17408
	v_mfma_f32_16x16x32_bf16 v[112:115], v[150:153], v[198:201], v[112:115]
	ds_read_b128 v[234:237], v135 offset:18432
	v_mfma_f32_16x16x32_bf16 v[100:103], v[142:145], v[206:209], v[100:103]
	ds_read_b128 v[238:241], v135 offset:19456
	v_mfma_f32_16x16x32_bf16 v[96:99], v[150:153], v[206:209], v[96:99]
	v_mfma_f32_16x16x32_bf16 v[84:87], v[142:145], v[214:217], v[84:87]
	s_setprio 0
	v_mfma_f32_16x16x32_bf16 v[80:83], v[150:153], v[214:217], v[80:83]
	s_barrier
	s_add_i32 s40, 0, 0x14000
	s_add_i32 s37, s37, s23
	s_mov_b32 m0, s37
	s_nop 0
	global_load_lds_dwordx4 v158, s[18:19]
	s_add_i32 m0, s37, 0x2000
	s_nop 0
	global_load_lds_dwordx4 v128, s[18:19]
	s_waitcnt lgkmcnt(0)
	s_setprio 1
	s_barrier
	v_mfma_f32_16x16x32_bf16 v[108:111], v[226:229], v[186:189], v[108:111]
	v_mfma_f32_16x16x32_bf16 v[104:107], v[234:237], v[186:189], v[104:107]
	v_mfma_f32_16x16x32_bf16 v[92:95], v[226:229], v[194:197], v[92:95]
	v_mfma_f32_16x16x32_bf16 v[88:91], v[234:237], v[194:197], v[88:91]
	v_mfma_f32_16x16x32_bf16 v[76:79], v[226:229], v[202:205], v[76:79]
	v_mfma_f32_16x16x32_bf16 v[72:75], v[234:237], v[202:205], v[72:75]
	v_mfma_f32_16x16x32_bf16 v[68:71], v[226:229], v[210:213], v[68:71]
	v_mfma_f32_16x16x32_bf16 v[64:67], v[234:237], v[210:213], v[64:67]
	v_mfma_f32_16x16x32_bf16 v[108:111], v[230:233], v[190:193], v[108:111]
	ds_read_b128 v[186:189], v137 offset:16384
	s_mov_b32 m0, s24
	v_mfma_f32_16x16x32_bf16 v[104:107], v[238:241], v[190:193], v[104:107]
	ds_read_b128 v[190:193], v137 offset:17408
	v_mfma_f32_16x16x32_bf16 v[92:95], v[230:233], v[198:201], v[92:95]
	ds_read_b128 v[194:197], v137 offset:18432
	v_mfma_f32_16x16x32_bf16 v[88:91], v[238:241], v[198:201], v[88:91]
	ds_read_b128 v[198:201], v137 offset:19456
	v_mfma_f32_16x16x32_bf16 v[76:79], v[230:233], v[206:209], v[76:79]
	ds_read_b128 v[202:205], v137 offset:20480
	v_mfma_f32_16x16x32_bf16 v[72:75], v[238:241], v[206:209], v[72:75]
	ds_read_b128 v[206:209], v137 offset:21504
	v_mfma_f32_16x16x32_bf16 v[68:71], v[230:233], v[214:217], v[68:71]
	ds_read_b128 v[210:213], v137 offset:22528
	s_setprio 0
	v_mfma_f32_16x16x32_bf16 v[64:67], v[238:241], v[214:217], v[64:67]
	s_barrier
	ds_read_b128 v[214:217], v137 offset:23552
	global_load_lds_dwordx4 v158, s[20:21]
	s_mov_b64 s[100:101], s[20:21]
	s_mov_b32 m0, s25
	s_nop 0
	global_load_lds_dwordx4 v128, s[20:21]
	s_waitcnt lgkmcnt(0)
	s_setprio 1
	s_barrier
	v_mfma_f32_16x16x32_bf16 v[60:63], v[138:141], v[186:189], v[60:63]
	v_mfma_f32_16x16x32_bf16 v[56:59], v[146:149], v[186:189], v[56:59]
	v_mfma_f32_16x16x32_bf16 v[52:55], v[138:141], v[194:197], v[52:55]
	v_mfma_f32_16x16x32_bf16 v[48:51], v[146:149], v[194:197], v[48:51]
	v_mfma_f32_16x16x32_bf16 v[36:39], v[138:141], v[202:205], v[36:39]
	v_mfma_f32_16x16x32_bf16 v[32:35], v[146:149], v[202:205], v[32:35]
	v_mfma_f32_16x16x32_bf16 v[20:23], v[138:141], v[210:213], v[20:23]
	v_mfma_f32_16x16x32_bf16 v[16:19], v[146:149], v[210:213], v[16:19]
	v_mfma_f32_16x16x32_bf16 v[60:63], v[142:145], v[190:193], v[60:63]
	v_mfma_f32_16x16x32_bf16 v[56:59], v[150:153], v[190:193], v[56:59]
	v_mfma_f32_16x16x32_bf16 v[52:55], v[142:145], v[198:201], v[52:55]
	v_mfma_f32_16x16x32_bf16 v[48:51], v[150:153], v[198:201], v[48:51]
	v_mfma_f32_16x16x32_bf16 v[36:39], v[142:145], v[206:209], v[36:39]
	v_mfma_f32_16x16x32_bf16 v[32:35], v[150:153], v[206:209], v[32:35]
	v_mfma_f32_16x16x32_bf16 v[20:23], v[142:145], v[214:217], v[20:23]
	s_setprio 0
	v_mfma_f32_16x16x32_bf16 v[16:19], v[150:153], v[214:217], v[16:19]
	s_barrier
	s_add_u32 s38, s18, 0x80000
	s_addc_u32 s39, s19, 0
	s_add_i32 s37, s40, s23
	s_mov_b32 m0, s37
	s_nop 0
	global_load_lds_dwordx4 v158, s[38:39]
	s_add_i32 m0, s37, 0x2000
	s_nop 0
	global_load_lds_dwordx4 v128, s[38:39]
	s_waitcnt vmcnt(6)
	s_setprio 1
	s_barrier
; #define PG8_STAGE(bufoff, gbase) do { _Pragma("unroll") for (int _i = 0; _i < 2; ++_i) \
;         __builtin_amdgcn_global_load_lds((const unsigned*)((const char*)(gbase) + voff[_i]), (LAS unsigned*)(lds + (bufoff) + ldsw + _i * 8192), 16, 0, 0); } while (0)
; #define PG8_LDA(dst, b, h) do { _Pragma("unroll") for (int m = 0; m < 4; ++m) _Pragma("unroll") for (int k = 0; k < 2; ++k) dst[m][k] = *(const LAS bf16x8*)(lds + PG8_SA(b, h) + aoff + m * 2048 + k * 1024); } while (0)
; #define PG8_LDB(dst, b, h) do { _Pragma("unroll") for (int n = 0; n < 2; ++n) _Pragma("unroll") for (int k = 0; k < 2; ++k) dst[n][k] = *(const LAS bf16x8*)(lds + PG8_SB(b, h) + boff + n * 2048 + k * 1024); } while (0)
; #define PG8_MMA(ai, bj, At, Bt) do { __builtin_amdgcn_s_setprio(1); _Pragma("unroll") for (int m = 0; m < 4; ++m) _Pragma("unroll") for (int n = 0; n < 2; ++n) _Pragma("unroll") for (int k = 0; k < 2; ++k) \
;         acc[ai][bj][m][n] = __builtin_amdgcn_mfma_f32_16x16x32_bf16(Bt[n][k], At[m][k], acc[ai][bj][m][n], 0, 0, 0); __builtin_amdgcn_s_setprio(0); } while (0)
; #define PG8_WAIT_V(n) asm volatile("s_waitcnt vmcnt(" #n ")" ::: "memory")
; #define PG8_WAIT_L(n) asm volatile("s_waitcnt lgkmcnt(" #n ")" ::: "memory")
; #define PG8_BAR __builtin_amdgcn_s_barrier()
; #define PG8_SCHED __builtin_amdgcn_sched_barrier(0)
; template <class Epi>
; DI void gemm_phase(LAS unsigned char* lds, const Gemm g, const StaticOrder& S, const Epi& E) {
;     ...
;             PG8_STAGE(PG8_SB(0, 1), b2 + hstep);
;             PG8_WAIT_V(6); PG8_BAR; PG8_MMA(1, 1, At, B1); PG8_BAR;
;             PG8_LDB(B0, 1, 0); PG8_SCHED; PG8_LDA(At, 1, 0); PG8_STAGE(PG8_SA(0, 1), a2 + hstep);
;             PG8_WAIT_L(8); PG8_BAR; PG8_WAIT_L(0); PG8_MMA(0, 0, At, B0); PG8_BAR; PG8_SCHED;
;             PG8_LDB(B1, 1, 1); PG8_STAGE(PG8_SB(1, 0), b3);
;             PG8_BAR; PG8_WAIT_L(0); PG8_MMA(0, 1, At, B1); PG8_BAR;
;             PG8_LDA(At, 1, 1); PG8_STAGE(PG8_SA(1, 0), a3);
	v_mfma_f32_16x16x32_bf16 v[44:47], v[226:229], v[186:189], v[44:47]
	v_mfma_f32_16x16x32_bf16 v[40:43], v[234:237], v[186:189], v[40:43]
	v_mfma_f32_16x16x32_bf16 v[28:31], v[226:229], v[194:197], v[28:31]
	v_mfma_f32_16x16x32_bf16 v[24:27], v[234:237], v[194:197], v[24:27]
	v_mfma_f32_16x16x32_bf16 v[12:15], v[226:229], v[202:205], v[12:15]
	v_mfma_f32_16x16x32_bf16 v[8:11], v[234:237], v[202:205], v[8:11]
	v_mfma_f32_16x16x32_bf16 v[4:7], v[226:229], v[210:213], v[4:7]
	v_mfma_f32_16x16x32_bf16 v[0:3], v[234:237], v[210:213], v[0:3]
	v_mfma_f32_16x16x32_bf16 v[44:47], v[230:233], v[190:193], v[44:47]
	s_add_i32 s37, 0, 0x18000
	v_mfma_f32_16x16x32_bf16 v[40:43], v[238:241], v[190:193], v[40:43]
	v_mfma_f32_16x16x32_bf16 v[28:31], v[230:233], v[198:201], v[28:31]
	v_mfma_f32_16x16x32_bf16 v[24:27], v[238:241], v[198:201], v[24:27]
	v_mfma_f32_16x16x32_bf16 v[12:15], v[230:233], v[206:209], v[12:15]
	v_mfma_f32_16x16x32_bf16 v[8:11], v[238:241], v[206:209], v[8:11]
	v_mfma_f32_16x16x32_bf16 v[4:7], v[230:233], v[214:217], v[4:7]
	s_setprio 0
	v_mfma_f32_16x16x32_bf16 v[0:3], v[238:241], v[214:217], v[0:3]
	s_barrier
	ds_read_b128 v[138:141], v135 offset:32768
	ds_read_b128 v[142:145], v135 offset:33792
	ds_read_b128 v[146:149], v135 offset:34816
	ds_read_b128 v[150:153], v135 offset:35840
	ds_read_b128 v[186:189], v137 offset:32768
	ds_read_b128 v[190:193], v137 offset:33792
	ds_read_b128 v[194:197], v137 offset:34816
	ds_read_b128 v[198:201], v137 offset:35840
	ds_read_b128 v[202:205], v137 offset:36864
	ds_read_b128 v[206:209], v137 offset:37888
	ds_read_b128 v[210:213], v137 offset:38912
	ds_read_b128 v[214:217], v137 offset:39936
	s_add_u32 s20, s20, 0x80000
	s_addc_u32 s21, s21, 0
	s_mov_b32 m0, s26
	s_nop 0
	global_load_lds_dwordx4 v158, s[20:21]
	s_mov_b32 m0, s27
	s_nop 0
	global_load_lds_dwordx4 v128, s[20:21]
	s_waitcnt lgkmcnt(8)
	s_setprio 1
	s_barrier
	s_waitcnt lgkmcnt(0)
	v_mfma_f32_16x16x32_bf16 v[124:127], v[138:141], v[186:189], v[124:127]
	v_mfma_f32_16x16x32_bf16 v[120:123], v[146:149], v[186:189], v[120:123]
	v_mfma_f32_16x16x32_bf16 v[116:119], v[138:141], v[194:197], v[116:119]
	v_mfma_f32_16x16x32_bf16 v[112:115], v[146:149], v[194:197], v[112:115]
	v_mfma_f32_16x16x32_bf16 v[100:103], v[138:141], v[202:205], v[100:103]
	v_mfma_f32_16x16x32_bf16 v[96:99], v[146:149], v[202:205], v[96:99]
	v_mfma_f32_16x16x32_bf16 v[84:87], v[138:141], v[210:213], v[84:87]
	v_mfma_f32_16x16x32_bf16 v[80:83], v[146:149], v[210:213], v[80:83]
	v_mfma_f32_16x16x32_bf16 v[124:127], v[142:145], v[190:193], v[124:127]
	v_mfma_f32_16x16x32_bf16 v[120:123], v[150:153], v[190:193], v[120:123]
	ds_read_b128 v[226:229], v135 offset:49152
	v_mfma_f32_16x16x32_bf16 v[116:119], v[142:145], v[198:201], v[116:119]
	ds_read_b128 v[230:233], v135 offset:50176
	v_mfma_f32_16x16x32_bf16 v[112:115], v[150:153], v[198:201], v[112:115]
	ds_read_b128 v[234:237], v135 offset:51200
	v_mfma_f32_16x16x32_bf16 v[100:103], v[142:145], v[206:209], v[100:103]
	ds_read_b128 v[238:241], v135 offset:52224
	v_mfma_f32_16x16x32_bf16 v[96:99], v[150:153], v[206:209], v[96:99]
	v_mfma_f32_16x16x32_bf16 v[84:87], v[142:145], v[214:217], v[84:87]
	s_setprio 0
	v_mfma_f32_16x16x32_bf16 v[80:83], v[150:153], v[214:217], v[80:83]
	s_barrier
	s_add_i32 s20, 0, 0x1c000
	s_add_i32 s21, s37, s23
	s_add_i32 m0, s21, 0xffffff80
	s_nop 0
	global_load_lds_dwordx4 v158, s[18:19] offset:128
	s_add_i32 m0, s21, 0x1f80
	s_nop 0
	global_load_lds_dwordx4 v128, s[18:19] offset:128
	s_waitcnt lgkmcnt(0)
	s_setprio 1
	s_barrier
	v_mfma_f32_16x16x32_bf16 v[108:111], v[226:229], v[186:189], v[108:111]
	v_mfma_f32_16x16x32_bf16 v[104:107], v[234:237], v[186:189], v[104:107]
	v_mfma_f32_16x16x32_bf16 v[92:95], v[226:229], v[194:197], v[92:95]
	v_mfma_f32_16x16x32_bf16 v[88:91], v[234:237], v[194:197], v[88:91]
	v_mfma_f32_16x16x32_bf16 v[76:79], v[226:229], v[202:205], v[76:79]
	v_mfma_f32_16x16x32_bf16 v[72:75], v[234:237], v[202:205], v[72:75]
	v_mfma_f32_16x16x32_bf16 v[68:71], v[226:229], v[210:213], v[68:71]
	v_mfma_f32_16x16x32_bf16 v[64:67], v[234:237], v[210:213], v[64:67]
	v_mfma_f32_16x16x32_bf16 v[108:111], v[230:233], v[190:193], v[108:111]
	ds_read_b128 v[186:189], v137 offset:49152
	s_add_i32 m0, s28, 0xffffff80
	v_mfma_f32_16x16x32_bf16 v[104:107], v[238:241], v[190:193], v[104:107]
	ds_read_b128 v[190:193], v137 offset:50176
	v_mfma_f32_16x16x32_bf16 v[92:95], v[230:233], v[198:201], v[92:95]
	ds_read_b128 v[194:197], v137 offset:51200
	v_mfma_f32_16x16x32_bf16 v[88:91], v[238:241], v[198:201], v[88:91]
	ds_read_b128 v[198:201], v137 offset:52224
	v_mfma_f32_16x16x32_bf16 v[76:79], v[230:233], v[206:209], v[76:79]
	ds_read_b128 v[202:205], v137 offset:53248
	v_mfma_f32_16x16x32_bf16 v[72:75], v[238:241], v[206:209], v[72:75]
	ds_read_b128 v[206:209], v137 offset:54272
	v_mfma_f32_16x16x32_bf16 v[68:71], v[230:233], v[214:217], v[68:71]
	ds_read_b128 v[210:213], v137 offset:55296
	s_setprio 0
	v_mfma_f32_16x16x32_bf16 v[64:67], v[238:241], v[214:217], v[64:67]
	s_barrier
	ds_read_b128 v[214:217], v137 offset:56320
	global_load_lds_dwordx4 v158, s[100:101] offset:128
	s_add_i32 m0, s29, 0xffffff80
	s_nop 0
	global_load_lds_dwordx4 v128, s[100:101] offset:128
	s_waitcnt lgkmcnt(0)
	s_setprio 1
	s_barrier
; #define PG8_STAGE(bufoff, gbase) do { _Pragma("unroll") for (int _i = 0; _i < 2; ++_i) \
;         __builtin_amdgcn_global_load_lds((const unsigned*)((const char*)(gbase) + voff[_i]), (LAS unsigned*)(lds + (bufoff) + ldsw + _i * 8192), 16, 0, 0); } while (0)
; #define PG8_LDA(dst, b, h) do { _Pragma("unroll") for (int m = 0; m < 4; ++m) _Pragma("unroll") for (int k = 0; k < 2; ++k) dst[m][k] = *(const LAS bf16x8*)(lds + PG8_SA(b, h) + aoff + m * 2048 + k * 1024); } while (0)
; #define PG8_MMA(ai, bj, At, Bt) do { __builtin_amdgcn_s_setprio(1); _Pragma("unroll") for (int m = 0; m < 4; ++m) _Pragma("unroll") for (int n = 0; n < 2; ++n) _Pragma("unroll") for (int k = 0; k < 2; ++k) \
;         acc[ai][bj][m][n] = __builtin_amdgcn_mfma_f32_16x16x32_bf16(Bt[n][k], At[m][k], acc[ai][bj][m][n], 0, 0, 0); __builtin_amdgcn_s_setprio(0); } while (0)
; #define PG8_WAIT_V(n) asm volatile("s_waitcnt vmcnt(" #n ")" ::: "memory")
; #define PG8_WAIT_L(n) asm volatile("s_waitcnt lgkmcnt(" #n ")" ::: "memory")
; #define PG8_BAR __builtin_amdgcn_s_barrier()
; #define PG8_SCHED __builtin_amdgcn_sched_barrier(0)
; template <class Epi>
; DI void gemm_phase(LAS unsigned char* lds, const Gemm g, const StaticOrder& S, const Epi& E) {
;     ...
;             PG8_LDA(At, 1, 1); PG8_STAGE(PG8_SA(1, 0), a3);
;             PG8_BAR; PG8_WAIT_L(0); PG8_MMA(1, 0, At, B0); PG8_BAR; PG8_SCHED;
;             PG8_STAGE(PG8_SB(1, 1), b3 + hstep);
;             PG8_WAIT_V(6); PG8_BAR; PG8_MMA(1, 1, At, B1); PG8_BAR;
	v_mfma_f32_16x16x32_bf16 v[60:63], v[138:141], v[186:189], v[60:63]
	v_mfma_f32_16x16x32_bf16 v[56:59], v[146:149], v[186:189], v[56:59]
	v_mfma_f32_16x16x32_bf16 v[52:55], v[138:141], v[194:197], v[52:55]
	v_mfma_f32_16x16x32_bf16 v[48:51], v[146:149], v[194:197], v[48:51]
	v_mfma_f32_16x16x32_bf16 v[36:39], v[138:141], v[202:205], v[36:39]
	v_mfma_f32_16x16x32_bf16 v[32:35], v[146:149], v[202:205], v[32:35]
	v_mfma_f32_16x16x32_bf16 v[20:23], v[138:141], v[210:213], v[20:23]
	v_mfma_f32_16x16x32_bf16 v[16:19], v[146:149], v[210:213], v[16:19]
	v_mfma_f32_16x16x32_bf16 v[60:63], v[142:145], v[190:193], v[60:63]
	v_mfma_f32_16x16x32_bf16 v[56:59], v[150:153], v[190:193], v[56:59]
	v_mfma_f32_16x16x32_bf16 v[52:55], v[142:145], v[198:201], v[52:55]
	v_mfma_f32_16x16x32_bf16 v[48:51], v[150:153], v[198:201], v[48:51]
	v_mfma_f32_16x16x32_bf16 v[36:39], v[142:145], v[206:209], v[36:39]
	v_mfma_f32_16x16x32_bf16 v[32:35], v[150:153], v[206:209], v[32:35]
	v_mfma_f32_16x16x32_bf16 v[20:23], v[142:145], v[214:217], v[20:23]
	s_setprio 0
	v_mfma_f32_16x16x32_bf16 v[16:19], v[150:153], v[214:217], v[16:19]
	s_barrier
	s_add_u32 s18, s18, 0x80080
	s_addc_u32 s19, s19, 0
	s_add_i32 s20, s20, s23
	s_mov_b32 m0, s20
	s_nop 0
	global_load_lds_dwordx4 v158, s[18:19]
	s_add_i32 m0, s20, 0x2000
	s_nop 0
	global_load_lds_dwordx4 v128, s[18:19]
	s_waitcnt vmcnt(6)
	s_setprio 1
	s_barrier
	v_mfma_f32_16x16x32_bf16 v[44:47], v[226:229], v[186:189], v[44:47]
	v_mfma_f32_16x16x32_bf16 v[40:43], v[234:237], v[186:189], v[40:43]
	v_mfma_f32_16x16x32_bf16 v[28:31], v[226:229], v[194:197], v[28:31]
	v_mfma_f32_16x16x32_bf16 v[24:27], v[234:237], v[194:197], v[24:27]
	v_mfma_f32_16x16x32_bf16 v[12:15], v[226:229], v[202:205], v[12:15]
	v_mfma_f32_16x16x32_bf16 v[8:11], v[234:237], v[202:205], v[8:11]
	v_mfma_f32_16x16x32_bf16 v[4:7], v[226:229], v[210:213], v[4:7]
	v_mfma_f32_16x16x32_bf16 v[0:3], v[234:237], v[210:213], v[0:3]
	v_mfma_f32_16x16x32_bf16 v[44:47], v[230:233], v[190:193], v[44:47]
	s_add_i32 s36, s36, 2
	v_mfma_f32_16x16x32_bf16 v[40:43], v[238:241], v[190:193], v[40:43]
	s_add_u32 s16, s16, 0x100
	v_mfma_f32_16x16x32_bf16 v[28:31], v[230:233], v[198:201], v[28:31]
	s_addc_u32 s17, s17, 0
	v_mfma_f32_16x16x32_bf16 v[24:27], v[238:241], v[198:201], v[24:27]
	s_add_u32 s34, s34, 0x100
	v_mfma_f32_16x16x32_bf16 v[12:15], v[230:233], v[206:209], v[12:15]
	s_addc_u32 s35, s35, 0
	v_mfma_f32_16x16x32_bf16 v[8:11], v[238:241], v[206:209], v[8:11]
	s_cmp_gt_u32 s36, 29
	v_mfma_f32_16x16x32_bf16 v[4:7], v[230:233], v[214:217], v[4:7]
	s_setprio 0
	v_mfma_f32_16x16x32_bf16 v[0:3], v[238:241], v[214:217], v[0:3]
	s_barrier
	s_cbranch_scc0 .LBB0_231
; #define PG8_WAIT_V(n) asm volatile("s_waitcnt vmcnt(" #n ")" ::: "memory")
; #define PG8_BAR __builtin_amdgcn_s_barrier()
; template <class Epi>
; DI void gemm_phase(LAS unsigned char* lds, const Gemm g, const StaticOrder& S, const Epi& E) {
;     ...
;         E(acc, cur, wr, wc, fr, fq);
;         if (!has_next) break;
; #pragma unroll
;         for (int a = 0; a < 2; ++a)
; #pragma unroll
;             for (int b = 0; b < 2; ++b)
; #pragma unroll
;                 for (int m = 0; m < 4; ++m)
; #pragma unroll
;                     for (int n = 0; n < 2; ++n) acc[a][b][m][n] = (f32x4){0.f, 0.f, 0.f, 0.f};
;         cur = nxt; cA = nA; cB = nB; ++ui;
;     }
;     PG8_WAIT_V(0);
;     if (wr == 0) PG8_BAR;
;     PG8_BAR;
;     DI void operator()(const f32x4 (&acc)[2][2][4][2], const Unit& u, int wr, int wc, int fr, int fq) const {
;         const int row0 = u.pm * BM + wr * 64 + fr, col0 = u.pn * BM + wc * 32 + 8 * fq;
; #pragma unroll
;         for (int ai = 0; ai < 2; ++ai)
; #pragma unroll
;             for (int m = 0; m < 4; ++m) { u16* rowp = O + (size_t)(row0 + ai * HALF + m * 16) * ldc + col0;
; #pragma unroll
;                 for (int bj = 0; bj < 2; ++bj) { const f32x4 v0 = acc[ai][bj][m][0], v1 = acc[ai][bj][m][1];
;                     *(u32x4*)(rowp + bj * HALF) = (u32x4){pk(v0[0], v0[1]), pk(v0[2], v0[3]), pk(v1[0], v1[1]), pk(v1[2], v1[3])}; } }
;     }
	v_lshl_add_u32 v144, s33, 8, v134
	v_lshl_or_b32 v138, s31, 8, v136
	v_ashrrev_i32_e32 v139, 31, v138
	v_mov_b64_e32 v[140:141], s[50:51]
	s_movk_i32 s9, 0x3000
	v_cvt_pk_bf16_f32 v68, v68, v69
	v_cvt_pk_bf16_f32 v69, v70, v71
	v_cvt_pk_bf16_f32 v70, v64, v65
	v_add_u32_e32 v64, 0x80, v144
	v_mad_i64_i32 v[142:143], s[4:5], v144, s9, v[140:141]
	v_lshlrev_b64 v[138:139], 1, v[138:139]
	v_cvt_pk_bf16_f32 v108, v108, v109
	v_cvt_pk_bf16_f32 v109, v110, v111
	v_cvt_pk_bf16_f32 v110, v104, v105
	v_or_b32_e32 v104, 16, v144
	v_mad_i64_i32 v[64:65], s[4:5], v64, s9, v[140:141]
	v_cvt_pk_bf16_f32 v44, v44, v45
	v_cvt_pk_bf16_f32 v45, v46, v47
	v_cvt_pk_bf16_f32 v46, v40, v41
	v_add_u32_e32 v40, 0x90, v144
	v_lshl_add_u64 v[142:143], v[142:143], 0, v[138:139]
	v_cvt_pk_bf16_f32 v111, v106, v107
	v_mad_i64_i32 v[104:105], s[4:5], v104, s9, v[140:141]
	v_cvt_pk_bf16_f32 v92, v92, v93
	v_cvt_pk_bf16_f32 v93, v94, v95
	v_cvt_pk_bf16_f32 v94, v88, v89
	v_or_b32_e32 v88, 32, v144
	v_lshl_add_u64 v[64:65], v[64:65], 0, v[138:139]
	v_cvt_pk_bf16_f32 v47, v42, v43
	v_mad_i64_i32 v[40:41], s[4:5], v40, s9, v[140:141]
	v_cvt_pk_bf16_f32 v28, v28, v29
	v_cvt_pk_bf16_f32 v29, v30, v31
	v_cvt_pk_bf16_f32 v30, v24, v25
	v_add_u32_e32 v24, 0xa0, v144
	global_store_dwordx4 v[142:143], v[108:111], off offset:256
	v_cvt_pk_bf16_f32 v95, v90, v91
	v_mad_i64_i32 v[88:89], s[4:5], v88, s9, v[140:141]
	v_lshl_add_u64 v[108:109], v[104:105], 0, v[138:139]
	v_cvt_pk_bf16_f32 v76, v76, v77
	v_cvt_pk_bf16_f32 v77, v78, v79
	v_cvt_pk_bf16_f32 v78, v72, v73
	v_or_b32_e32 v72, 48, v144
	global_store_dwordx4 v[64:65], v[44:47], off offset:256
	v_cvt_pk_bf16_f32 v31, v26, v27
	v_mad_i64_i32 v[24:25], s[4:5], v24, s9, v[140:141]
	v_lshl_add_u64 v[44:45], v[40:41], 0, v[138:139]
	v_cvt_pk_bf16_f32 v12, v12, v13
	v_cvt_pk_bf16_f32 v13, v14, v15
	v_cvt_pk_bf16_f32 v14, v8, v9
	v_add_u32_e32 v8, 0xb0, v144
	global_store_dwordx4 v[108:109], v[92:95], off offset:256
	v_cvt_pk_bf16_f32 v79, v74, v75
	v_mad_i64_i32 v[72:73], s[4:5], v72, s9, v[140:141]
	v_lshl_add_u64 v[92:93], v[88:89], 0, v[138:139]
	global_store_dwordx4 v[44:45], v[28:31], off offset:256
	v_cvt_pk_bf16_f32 v15, v10, v11
	v_mad_i64_i32 v[8:9], s[4:5], v8, s9, v[140:141]
	v_lshl_add_u64 v[28:29], v[24:25], 0, v[138:139]
	v_cvt_pk_bf16_f32 v124, v124, v125
	v_cvt_pk_bf16_f32 v125, v126, v127
	v_cvt_pk_bf16_f32 v126, v120, v121
	v_cvt_pk_bf16_f32 v127, v122, v123
	v_cvt_pk_bf16_f32 v104, v116, v117
	v_cvt_pk_bf16_f32 v105, v118, v119
	v_cvt_pk_bf16_f32 v106, v112, v113
	v_cvt_pk_bf16_f32 v107, v114, v115
	v_cvt_pk_bf16_f32 v88, v100, v101
	v_cvt_pk_bf16_f32 v89, v102, v103
	v_cvt_pk_bf16_f32 v90, v96, v97
	v_cvt_pk_bf16_f32 v91, v98, v99
	global_store_dwordx4 v[92:93], v[76:79], off offset:256
	v_cvt_pk_bf16_f32 v74, v80, v81
	v_cvt_pk_bf16_f32 v75, v82, v83
	v_lshl_add_u64 v[76:77], v[72:73], 0, v[138:139]
	v_cvt_pk_bf16_f32 v72, v84, v85
	v_cvt_pk_bf16_f32 v73, v86, v87
	v_cvt_pk_bf16_f32 v71, v66, v67
	v_cvt_pk_bf16_f32 v60, v60, v61
	v_cvt_pk_bf16_f32 v61, v62, v63
	v_cvt_pk_bf16_f32 v62, v56, v57
	v_cvt_pk_bf16_f32 v63, v58, v59
	v_cvt_pk_bf16_f32 v40, v52, v53
	v_cvt_pk_bf16_f32 v41, v54, v55
	v_cvt_pk_bf16_f32 v42, v48, v49
	v_cvt_pk_bf16_f32 v43, v50, v51
	v_cvt_pk_bf16_f32 v24, v36, v37
	v_cvt_pk_bf16_f32 v25, v38, v39
	v_cvt_pk_bf16_f32 v26, v32, v33
	v_cvt_pk_bf16_f32 v27, v34, v35
	global_store_dwordx4 v[28:29], v[12:15], off offset:256
	v_cvt_pk_bf16_f32 v10, v16, v17
	v_cvt_pk_bf16_f32 v11, v18, v19
	v_lshl_add_u64 v[12:13], v[8:9], 0, v[138:139]
	v_cvt_pk_bf16_f32 v8, v20, v21
	v_cvt_pk_bf16_f32 v9, v22, v23
	v_cvt_pk_bf16_f32 v4, v4, v5
	v_cvt_pk_bf16_f32 v5, v6, v7
	v_cvt_pk_bf16_f32 v6, v0, v1
	v_cvt_pk_bf16_f32 v7, v2, v3
	s_and_b64 vcc, exec, s[6:7]
	s_mov_b32 s31, s8
	s_mov_b32 s33, s10
	s_mov_b64 s[18:19], s[14:15]
	s_mov_b64 s[16:17], s[12:13]
	global_store_dwordx4 v[142:143], v[124:127], off
	global_store_dwordx4 v[108:109], v[104:107], off
	global_store_dwordx4 v[92:93], v[88:91], off
	global_store_dwordx4 v[76:77], v[72:75], off
	global_store_dwordx4 v[76:77], v[68:71], off offset:256
	global_store_dwordx4 v[64:65], v[60:63], off
	global_store_dwordx4 v[44:45], v[40:43], off
	global_store_dwordx4 v[28:29], v[24:27], off
	global_store_dwordx4 v[12:13], v[8:11], off
	global_store_dwordx4 v[12:13], v[4:7], off offset:256
	s_cbranch_vccz .LBB0_228
	s_waitcnt vmcnt(0)
	s_cmpk_gt_u32 s2, 0xff
	s_cbranch_scc1 .LBB0_235
	s_barrier

; #define PG8_STAGE(bufoff, gbase) do { _Pragma("unroll") for (int _i = 0; _i < 2; ++_i) \
;         __builtin_amdgcn_global_load_lds((const unsigned*)((const char*)(gbase) + voff[_i]), (LAS unsigned*)(lds + (bufoff) + ldsw + _i * 8192), 16, 0, 0); } while (0)
; #define PG8_LDA(dst, b, h) do { _Pragma("unroll") for (int m = 0; m < 4; ++m) _Pragma("unroll") for (int k = 0; k < 2; ++k) dst[m][k] = *(const LAS bf16x8*)(lds + PG8_SA(b, h) + aoff + m * 2048 + k * 1024); } while (0)
; #define PG8_LDB(dst, b, h) do { _Pragma("unroll") for (int n = 0; n < 2; ++n) _Pragma("unroll") for (int k = 0; k < 2; ++k) dst[n][k] = *(const LAS bf16x8*)(lds + PG8_SB(b, h) + boff + n * 2048 + k * 1024); } while (0)
; #define PG8_MMA(ai, bj, At, Bt) do { __builtin_amdgcn_s_setprio(1); _Pragma("unroll") for (int m = 0; m < 4; ++m) _Pragma("unroll") for (int n = 0; n < 2; ++n) _Pragma("unroll") for (int k = 0; k < 2; ++k) \
;         acc[ai][bj][m][n] = __builtin_amdgcn_mfma_f32_16x16x32_bf16(Bt[n][k], At[m][k], acc[ai][bj][m][n], 0, 0, 0); __builtin_amdgcn_s_setprio(0); } while (0)
; #define PG8_WAIT_V(n) asm volatile("s_waitcnt vmcnt(" #n ")" ::: "memory")
; #define PG8_WAIT_L(n) asm volatile("s_waitcnt lgkmcnt(" #n ")" ::: "memory")
; #define PG8_BAR __builtin_amdgcn_s_barrier()
; #define PG8_SCHED __builtin_amdgcn_sched_barrier(0)
; template <class Epi>
; DI void gemm_phase(LAS unsigned char* lds, const Gemm g, const StaticOrder& S, const Epi& E) {
;     ...
;         for (int t = 0; t < nt; t += 2) {
;             const bool last = (t == nt - 2);
;             const char* a1 = cA + (size_t)(t + 1) * kstep;
;             const char* a2 = last ? nA : cA + (size_t)(t + 2) * kstep; const char* b2 = last ? nB : cB + (size_t)(t + 2) * kstep;
;             const char* a3 = a2 + kstep; const char* b3 = b2 + kstep;
;             PG8_LDB(B0, 0, 0); PG8_SCHED; PG8_LDA(At, 0, 0); PG8_STAGE(PG8_SA(1, 1), a1 + hstep);
;             PG8_WAIT_L(8); PG8_BAR; PG8_WAIT_L(0); PG8_MMA(0, 0, At, B0); PG8_BAR; PG8_SCHED;
;             PG8_LDB(B1, 0, 1); PG8_STAGE(PG8_SB(0, 0), b2);
;             PG8_BAR; PG8_WAIT_L(0); PG8_MMA(0, 1, At, B1); PG8_BAR;
;             PG8_LDA(At, 0, 1); PG8_STAGE(PG8_SA(0, 0), a2);
;             PG8_BAR; PG8_WAIT_L(0); PG8_MMA(1, 0, At, B0); PG8_BAR; PG8_SCHED;
;             PG8_STAGE(PG8_SB(0, 1), b2 + hstep);
;             PG8_WAIT_V(6); PG8_BAR; PG8_MMA(1, 1, At, B1); PG8_BAR;
.LBB0_320:
	s_add_u32 s26, s24, 0x100
	s_addc_u32 s27, s25, 0
	s_add_i32 s47, 0, 0x10000
	ds_read_b128 v[128:131], v226
	ds_read_b128 v[132:135], v226 offset:1024
	ds_read_b128 v[136:139], v226 offset:2048
	ds_read_b128 v[140:143], v226 offset:3072
	s_cmp_eq_u32 s46, 28
	s_cselect_b32 s31, s4, s27
	s_cselect_b32 s30, s5, s26
	s_cselect_b32 s29, s9, s45
	s_cselect_b32 s28, s11, s33
	v_lshl_add_u64 v[214:215], s[24:25], 0, v[190:191]
	s_add_i32 m0, s38, 0xc000
	ds_read_b128 v[144:147], v228
	ds_read_b128 v[148:151], v228 offset:1024
	ds_read_b128 v[152:155], v228 offset:2048
	ds_read_b128 v[194:197], v228 offset:3072
	ds_read_b128 v[198:201], v228 offset:4096
	ds_read_b128 v[202:205], v228 offset:5120
	ds_read_b128 v[206:209], v228 offset:6144
	ds_read_b128 v[210:213], v228 offset:7168
	global_load_lds_dwordx4 v[214:215], off
	v_lshl_add_u64 v[214:215], s[24:25], 0, v[192:193]
	s_add_i32 m0, s38, 0xe000
	s_nop 0
	global_load_lds_dwordx4 v[214:215], off
	s_waitcnt lgkmcnt(8)
	s_setprio 1
	s_barrier
	s_waitcnt lgkmcnt(0)
	v_mfma_f32_16x16x32_bf16 v[124:127], v[128:131], v[144:147], v[124:127]
	v_mfma_f32_16x16x32_bf16 v[120:123], v[136:139], v[144:147], v[120:123]
	v_mfma_f32_16x16x32_bf16 v[116:119], v[128:131], v[152:155], v[116:119]
	v_mfma_f32_16x16x32_bf16 v[112:115], v[136:139], v[152:155], v[112:115]
	v_mfma_f32_16x16x32_bf16 v[108:111], v[128:131], v[198:201], v[108:111]
	v_mfma_f32_16x16x32_bf16 v[104:107], v[136:139], v[198:201], v[104:107]
	v_mfma_f32_16x16x32_bf16 v[100:103], v[128:131], v[206:209], v[100:103]
	v_mfma_f32_16x16x32_bf16 v[96:99], v[136:139], v[206:209], v[96:99]
	v_mfma_f32_16x16x32_bf16 v[124:127], v[132:135], v[148:151], v[124:127]
	v_mfma_f32_16x16x32_bf16 v[120:123], v[140:143], v[148:151], v[120:123]
	ds_read_b128 v[214:217], v226 offset:16384
	v_mfma_f32_16x16x32_bf16 v[116:119], v[132:135], v[194:197], v[116:119]
	ds_read_b128 v[230:233], v226 offset:17408
	v_mfma_f32_16x16x32_bf16 v[112:115], v[140:143], v[194:197], v[112:115]
	ds_read_b128 v[234:237], v226 offset:18432
	v_mfma_f32_16x16x32_bf16 v[108:111], v[132:135], v[202:205], v[108:111]
	ds_read_b128 v[238:241], v226 offset:19456
	v_mfma_f32_16x16x32_bf16 v[104:107], v[140:143], v[202:205], v[104:107]
	v_mfma_f32_16x16x32_bf16 v[100:103], v[132:135], v[210:213], v[100:103]
	s_setprio 0
	v_mfma_f32_16x16x32_bf16 v[96:99], v[140:143], v[210:213], v[96:99]
	s_barrier
	s_add_i32 s48, 0, 0x14000
	s_add_i32 s24, s47, s37
	s_mov_b32 m0, s24
	s_nop 0
	global_load_lds_dwordx4 v188, s[28:29]
	s_add_i32 m0, s24, 0x2000
	s_nop 0
	global_load_lds_dwordx4 v186, s[28:29]
	s_waitcnt lgkmcnt(0)
	s_setprio 1
	s_barrier
	v_mfma_f32_16x16x32_bf16 v[60:63], v[214:217], v[144:147], v[60:63]
	v_mfma_f32_16x16x32_bf16 v[56:59], v[234:237], v[144:147], v[56:59]
	v_mfma_f32_16x16x32_bf16 v[52:55], v[214:217], v[152:155], v[52:55]
	v_mfma_f32_16x16x32_bf16 v[48:51], v[234:237], v[152:155], v[48:51]
	v_mfma_f32_16x16x32_bf16 v[44:47], v[214:217], v[198:201], v[44:47]
	v_mfma_f32_16x16x32_bf16 v[40:43], v[234:237], v[198:201], v[40:43]
	v_mfma_f32_16x16x32_bf16 v[36:39], v[214:217], v[206:209], v[36:39]
	v_mfma_f32_16x16x32_bf16 v[32:35], v[234:237], v[206:209], v[32:35]
	v_mfma_f32_16x16x32_bf16 v[60:63], v[230:233], v[148:151], v[60:63]
	ds_read_b128 v[144:147], v228 offset:16384
	s_mov_b32 m0, s38
	v_mfma_f32_16x16x32_bf16 v[56:59], v[238:241], v[148:151], v[56:59]
	ds_read_b128 v[148:151], v228 offset:17408
	v_mfma_f32_16x16x32_bf16 v[52:55], v[230:233], v[194:197], v[52:55]
	ds_read_b128 v[152:155], v228 offset:18432
	v_mfma_f32_16x16x32_bf16 v[48:51], v[238:241], v[194:197], v[48:51]
	ds_read_b128 v[194:197], v228 offset:19456
	v_mfma_f32_16x16x32_bf16 v[44:47], v[230:233], v[202:205], v[44:47]
	ds_read_b128 v[198:201], v228 offset:20480
	v_mfma_f32_16x16x32_bf16 v[40:43], v[238:241], v[202:205], v[40:43]
	ds_read_b128 v[202:205], v228 offset:21504
	v_mfma_f32_16x16x32_bf16 v[36:39], v[230:233], v[210:213], v[36:39]
	ds_read_b128 v[206:209], v228 offset:22528
	s_setprio 0
	v_mfma_f32_16x16x32_bf16 v[32:35], v[238:241], v[210:213], v[32:35]
	s_barrier
	ds_read_b128 v[210:213], v228 offset:23552
	global_load_lds_dwordx4 v188, s[30:31]
	s_mov_b64 s[100:101], s[30:31]
	s_mov_b32 m0, s39
	s_nop 0
	global_load_lds_dwordx4 v186, s[30:31]
	s_waitcnt lgkmcnt(0)
	s_setprio 1
	s_barrier
	v_mfma_f32_16x16x32_bf16 v[92:95], v[128:131], v[144:147], v[92:95]
	v_mfma_f32_16x16x32_bf16 v[88:91], v[136:139], v[144:147], v[88:91]
	v_mfma_f32_16x16x32_bf16 v[84:87], v[128:131], v[152:155], v[84:87]
	v_mfma_f32_16x16x32_bf16 v[80:83], v[136:139], v[152:155], v[80:83]
	v_mfma_f32_16x16x32_bf16 v[76:79], v[128:131], v[198:201], v[76:79]
	v_mfma_f32_16x16x32_bf16 v[72:75], v[136:139], v[198:201], v[72:75]
	v_mfma_f32_16x16x32_bf16 v[68:71], v[128:131], v[206:209], v[68:71]
	v_mfma_f32_16x16x32_bf16 v[64:67], v[136:139], v[206:209], v[64:67]
	v_mfma_f32_16x16x32_bf16 v[92:95], v[132:135], v[148:151], v[92:95]
	v_mfma_f32_16x16x32_bf16 v[88:91], v[140:143], v[148:151], v[88:91]
	v_mfma_f32_16x16x32_bf16 v[84:87], v[132:135], v[194:197], v[84:87]
	v_mfma_f32_16x16x32_bf16 v[80:83], v[140:143], v[194:197], v[80:83]
	v_mfma_f32_16x16x32_bf16 v[76:79], v[132:135], v[202:205], v[76:79]
	v_mfma_f32_16x16x32_bf16 v[72:75], v[140:143], v[202:205], v[72:75]
	v_mfma_f32_16x16x32_bf16 v[68:71], v[132:135], v[210:213], v[68:71]
	s_setprio 0
	v_mfma_f32_16x16x32_bf16 v[64:67], v[140:143], v[210:213], v[64:67]
	s_barrier
	s_add_u32 s24, s28, 0x80000
	s_addc_u32 s25, s29, 0
	s_add_i32 s47, s48, s37
	s_mov_b32 m0, s47
	s_nop 0
	global_load_lds_dwordx4 v188, s[24:25]
	s_add_i32 m0, s47, 0x2000
	s_nop 0
	global_load_lds_dwordx4 v186, s[24:25]
	s_waitcnt vmcnt(6)
	s_setprio 1
	s_barrier
; #define PG8_STAGE(bufoff, gbase) do { _Pragma("unroll") for (int _i = 0; _i < 2; ++_i) \
;         __builtin_amdgcn_global_load_lds((const unsigned*)((const char*)(gbase) + voff[_i]), (LAS unsigned*)(lds + (bufoff) + ldsw + _i * 8192), 16, 0, 0); } while (0)
; #define PG8_LDA(dst, b, h) do { _Pragma("unroll") for (int m = 0; m < 4; ++m) _Pragma("unroll") for (int k = 0; k < 2; ++k) dst[m][k] = *(const LAS bf16x8*)(lds + PG8_SA(b, h) + aoff + m * 2048 + k * 1024); } while (0)
; #define PG8_LDB(dst, b, h) do { _Pragma("unroll") for (int n = 0; n < 2; ++n) _Pragma("unroll") for (int k = 0; k < 2; ++k) dst[n][k] = *(const LAS bf16x8*)(lds + PG8_SB(b, h) + boff + n * 2048 + k * 1024); } while (0)
; #define PG8_MMA(ai, bj, At, Bt) do { __builtin_amdgcn_s_setprio(1); _Pragma("unroll") for (int m = 0; m < 4; ++m) _Pragma("unroll") for (int n = 0; n < 2; ++n) _Pragma("unroll") for (int k = 0; k < 2; ++k) \
;         acc[ai][bj][m][n] = __builtin_amdgcn_mfma_f32_16x16x32_bf16(Bt[n][k], At[m][k], acc[ai][bj][m][n], 0, 0, 0); __builtin_amdgcn_s_setprio(0); } while (0)
; #define PG8_WAIT_V(n) asm volatile("s_waitcnt vmcnt(" #n ")" ::: "memory")
; #define PG8_WAIT_L(n) asm volatile("s_waitcnt lgkmcnt(" #n ")" ::: "memory")
; #define PG8_BAR __builtin_amdgcn_s_barrier()
; #define PG8_SCHED __builtin_amdgcn_sched_barrier(0)
; template <class Epi>
; DI void gemm_phase(LAS unsigned char* lds, const Gemm g, const StaticOrder& S, const Epi& E) {
;     ...
;             PG8_STAGE(PG8_SB(0, 1), b2 + hstep);
;             PG8_WAIT_V(6); PG8_BAR; PG8_MMA(1, 1, At, B1); PG8_BAR;
;             PG8_LDB(B0, 1, 0); PG8_SCHED; PG8_LDA(At, 1, 0); PG8_STAGE(PG8_SA(0, 1), a2 + hstep);
;             PG8_WAIT_L(8); PG8_BAR; PG8_WAIT_L(0); PG8_MMA(0, 0, At, B0); PG8_BAR; PG8_SCHED;
;             PG8_LDB(B1, 1, 1); PG8_STAGE(PG8_SB(1, 0), b3);
;             PG8_BAR; PG8_WAIT_L(0); PG8_MMA(0, 1, At, B1); PG8_BAR;
;             PG8_LDA(At, 1, 1); PG8_STAGE(PG8_SA(1, 0), a3);
	v_mfma_f32_16x16x32_bf16 v[28:31], v[214:217], v[144:147], v[28:31]
	v_mfma_f32_16x16x32_bf16 v[24:27], v[234:237], v[144:147], v[24:27]
	v_mfma_f32_16x16x32_bf16 v[20:23], v[214:217], v[152:155], v[20:23]
	v_mfma_f32_16x16x32_bf16 v[16:19], v[234:237], v[152:155], v[16:19]
	v_mfma_f32_16x16x32_bf16 v[12:15], v[214:217], v[198:201], v[12:15]
	v_mfma_f32_16x16x32_bf16 v[8:11], v[234:237], v[198:201], v[8:11]
	v_mfma_f32_16x16x32_bf16 v[4:7], v[214:217], v[206:209], v[4:7]
	v_mfma_f32_16x16x32_bf16 v[0:3], v[234:237], v[206:209], v[0:3]
	v_mfma_f32_16x16x32_bf16 v[28:31], v[230:233], v[148:151], v[28:31]
	s_add_i32 s47, 0, 0x18000
	v_mfma_f32_16x16x32_bf16 v[24:27], v[238:241], v[148:151], v[24:27]
	v_mfma_f32_16x16x32_bf16 v[20:23], v[230:233], v[194:197], v[20:23]
	v_mfma_f32_16x16x32_bf16 v[16:19], v[238:241], v[194:197], v[16:19]
	v_mfma_f32_16x16x32_bf16 v[12:15], v[230:233], v[202:205], v[12:15]
	v_mfma_f32_16x16x32_bf16 v[8:11], v[238:241], v[202:205], v[8:11]
	v_mfma_f32_16x16x32_bf16 v[4:7], v[230:233], v[210:213], v[4:7]
	s_setprio 0
	v_mfma_f32_16x16x32_bf16 v[0:3], v[238:241], v[210:213], v[0:3]
	s_barrier
	ds_read_b128 v[128:131], v226 offset:32768
	ds_read_b128 v[132:135], v226 offset:33792
	ds_read_b128 v[136:139], v226 offset:34816
	ds_read_b128 v[140:143], v226 offset:35840
	ds_read_b128 v[144:147], v228 offset:32768
	ds_read_b128 v[148:151], v228 offset:33792
	ds_read_b128 v[152:155], v228 offset:34816
	ds_read_b128 v[194:197], v228 offset:35840
	ds_read_b128 v[198:201], v228 offset:36864
	ds_read_b128 v[202:205], v228 offset:37888
	ds_read_b128 v[206:209], v228 offset:38912
	ds_read_b128 v[210:213], v228 offset:39936
	s_add_u32 s24, s30, 0x80000
	s_addc_u32 s25, s31, 0
	s_mov_b32 m0, s40
	s_nop 0
	global_load_lds_dwordx4 v188, s[24:25]
	s_mov_b32 m0, s41
	s_nop 0
	global_load_lds_dwordx4 v186, s[24:25]
	s_waitcnt lgkmcnt(8)
	s_setprio 1
	s_barrier
	s_waitcnt lgkmcnt(0)
	v_mfma_f32_16x16x32_bf16 v[124:127], v[128:131], v[144:147], v[124:127]
	v_mfma_f32_16x16x32_bf16 v[120:123], v[136:139], v[144:147], v[120:123]
	v_mfma_f32_16x16x32_bf16 v[116:119], v[128:131], v[152:155], v[116:119]
	v_mfma_f32_16x16x32_bf16 v[112:115], v[136:139], v[152:155], v[112:115]
	v_mfma_f32_16x16x32_bf16 v[108:111], v[128:131], v[198:201], v[108:111]
	v_mfma_f32_16x16x32_bf16 v[104:107], v[136:139], v[198:201], v[104:107]
	v_mfma_f32_16x16x32_bf16 v[100:103], v[128:131], v[206:209], v[100:103]
	v_mfma_f32_16x16x32_bf16 v[96:99], v[136:139], v[206:209], v[96:99]
	v_mfma_f32_16x16x32_bf16 v[124:127], v[132:135], v[148:151], v[124:127]
	v_mfma_f32_16x16x32_bf16 v[120:123], v[140:143], v[148:151], v[120:123]
	ds_read_b128 v[214:217], v226 offset:49152
	v_mfma_f32_16x16x32_bf16 v[116:119], v[132:135], v[194:197], v[116:119]
	ds_read_b128 v[230:233], v226 offset:50176
	v_mfma_f32_16x16x32_bf16 v[112:115], v[140:143], v[194:197], v[112:115]
	ds_read_b128 v[234:237], v226 offset:51200
	v_mfma_f32_16x16x32_bf16 v[108:111], v[132:135], v[202:205], v[108:111]
	ds_read_b128 v[238:241], v226 offset:52224
	v_mfma_f32_16x16x32_bf16 v[104:107], v[140:143], v[202:205], v[104:107]
	v_mfma_f32_16x16x32_bf16 v[100:103], v[132:135], v[210:213], v[100:103]
	s_setprio 0
	v_mfma_f32_16x16x32_bf16 v[96:99], v[140:143], v[210:213], v[96:99]
	s_barrier
	s_add_i32 s30, 0, 0x1c000
	s_add_i32 s24, s47, s37
	s_add_i32 m0, s24, 0xffffff80
	s_nop 0
	global_load_lds_dwordx4 v188, s[28:29] offset:128
	s_add_i32 m0, s24, 0x1f80
	s_nop 0
	global_load_lds_dwordx4 v186, s[28:29] offset:128
	s_waitcnt lgkmcnt(0)
	s_setprio 1
	s_barrier
	v_mfma_f32_16x16x32_bf16 v[60:63], v[214:217], v[144:147], v[60:63]
	v_mfma_f32_16x16x32_bf16 v[56:59], v[234:237], v[144:147], v[56:59]
	v_mfma_f32_16x16x32_bf16 v[52:55], v[214:217], v[152:155], v[52:55]
	v_mfma_f32_16x16x32_bf16 v[48:51], v[234:237], v[152:155], v[48:51]
	v_mfma_f32_16x16x32_bf16 v[44:47], v[214:217], v[198:201], v[44:47]
	v_mfma_f32_16x16x32_bf16 v[40:43], v[234:237], v[198:201], v[40:43]
	v_mfma_f32_16x16x32_bf16 v[36:39], v[214:217], v[206:209], v[36:39]
	v_mfma_f32_16x16x32_bf16 v[32:35], v[234:237], v[206:209], v[32:35]
	v_mfma_f32_16x16x32_bf16 v[60:63], v[230:233], v[148:151], v[60:63]
	ds_read_b128 v[144:147], v228 offset:49152
	s_add_i32 m0, s42, 0xffffff80
	v_mfma_f32_16x16x32_bf16 v[56:59], v[238:241], v[148:151], v[56:59]
	ds_read_b128 v[148:151], v228 offset:50176
	v_mfma_f32_16x16x32_bf16 v[52:55], v[230:233], v[194:197], v[52:55]
	ds_read_b128 v[152:155], v228 offset:51200
	v_mfma_f32_16x16x32_bf16 v[48:51], v[238:241], v[194:197], v[48:51]
	ds_read_b128 v[194:197], v228 offset:52224
	v_mfma_f32_16x16x32_bf16 v[44:47], v[230:233], v[202:205], v[44:47]
	ds_read_b128 v[198:201], v228 offset:53248
	v_mfma_f32_16x16x32_bf16 v[40:43], v[238:241], v[202:205], v[40:43]
	ds_read_b128 v[202:205], v228 offset:54272
	v_mfma_f32_16x16x32_bf16 v[36:39], v[230:233], v[210:213], v[36:39]
	ds_read_b128 v[206:209], v228 offset:55296
	s_setprio 0
	v_mfma_f32_16x16x32_bf16 v[32:35], v[238:241], v[210:213], v[32:35]
	s_barrier
	ds_read_b128 v[210:213], v228 offset:56320
	global_load_lds_dwordx4 v188, s[100:101] offset:128
	s_add_i32 m0, s43, 0xffffff80
	s_nop 0
	global_load_lds_dwordx4 v186, s[100:101] offset:128
	s_waitcnt lgkmcnt(0)
	s_setprio 1
	s_barrier
; #define PG8_WAIT_V(n) asm volatile("s_waitcnt vmcnt(" #n ")" ::: "memory")
; #define PG8_WAIT_L(n) asm volatile("s_waitcnt lgkmcnt(" #n ")" ::: "memory")
; template <class Epi>
; DI void gemm_phase(LAS unsigned char* lds, const Gemm g, const StaticOrder& S, const Epi& E) {
;     ...
;             PG8_BAR; PG8_WAIT_L(0); PG8_MMA(1, 0, At, B0); PG8_BAR; PG8_SCHED;
;             PG8_STAGE(PG8_SB(1, 1), b3 + hstep);
;             PG8_WAIT_V(6); PG8_BAR; PG8_MMA(1, 1, At, B1); PG8_BAR;
;     template <bool LN, int BJ, int LO, int HI> DI void batch(const f32x4 (&acc)[2][2][4][2], unsigned row0, unsigned col0, const f32x4 (&gv)[2], const f32x4 (&bv)[2]) const {
;         f32x4 r[HI - LO]; float mean[(HI - LO) / 2], rstd[(HI - LO) / 2];
; #pragma unroll
;         for (int i = LO; i < HI; ++i) { const int ai = i >> 3, m = (i >> 1) & 3, n = i & 1; const unsigned row = row0 + ai * HALF + m * 16;
;             if (n == 0) { mean[(i - LO) >> 1] = 0.f; rstd[(i - LO) >> 1] = 1.f;
;                 if (LN) { const float2 st = *(const float2*)(stats + row * 2u); mean[(i - LO) >> 1] = st.x; rstd[(i - LO) >> 1] = st.y; } }
;             r[i - LO] = *(const f32x4*)(src + (row * (unsigned)DM + col0 + BJ * HALF + n * 16)); }
; #pragma unroll
;         for (int i = LO; i < HI; ++i) { const int ai = i >> 3, m = (i >> 1) & 3, n = i & 1; const unsigned row = row0 + ai * HALF + m * 16;
;             *(f32x4*)(Y + (row * (unsigned)DM + col0 + BJ * HALF + n * 16)) = acc[ai][BJ][m][n] + ((r[i - LO] - mean[(i - LO) >> 1]) * rstd[(i - LO) >> 1]) * gv[n] + bv[n]; }
;         __builtin_amdgcn_sched_barrier(0);
;     }
;     template <bool LN, int BJ> DI void load_gb(unsigned col0, f32x4 (&gv)[2], f32x4 (&bv)[2]) const {
; #pragma unroll
;         for (int n = 0; n < 2; ++n) {
;             if (LN) { gv[n] = *(const f32x4*)(gam + col0 + BJ * HALF + n * 16) * ALPHA; bv[n] = *(const f32x4*)(bet + col0 + BJ * HALF + n * 16) * ALPHA; }
;             else { gv[n] = (f32x4){ALPHA, ALPHA, ALPHA, ALPHA}; bv[n] = (f32x4){0.f, 0.f, 0.f, 0.f}; }
;         }
;     }
;     template <bool LN> DI void run(const f32x4 (&acc)[2][2][4][2], const Unit& u, int wr, int wc, int fr, int fq) const {
;         const unsigned row0 = u.pm * BM + wr * 64 + fr, col0 = u.pn * BM + wc * 32 + 4 * fq;
;         f32x4 gv[2], bv[2];
;         load_gb<LN, 0>(col0, gv, bv);
;         batch<LN, 0, 0, 4>(acc, row0, col0, gv, bv);
	v_mfma_f32_16x16x32_bf16 v[92:95], v[128:131], v[144:147], v[92:95]
	v_mfma_f32_16x16x32_bf16 v[88:91], v[136:139], v[144:147], v[88:91]
	v_mfma_f32_16x16x32_bf16 v[84:87], v[128:131], v[152:155], v[84:87]
	v_mfma_f32_16x16x32_bf16 v[80:83], v[136:139], v[152:155], v[80:83]
	v_mfma_f32_16x16x32_bf16 v[76:79], v[128:131], v[198:201], v[76:79]
	v_mfma_f32_16x16x32_bf16 v[72:75], v[136:139], v[198:201], v[72:75]
	v_mfma_f32_16x16x32_bf16 v[68:71], v[128:131], v[206:209], v[68:71]
	v_mfma_f32_16x16x32_bf16 v[64:67], v[136:139], v[206:209], v[64:67]
	v_mfma_f32_16x16x32_bf16 v[92:95], v[132:135], v[148:151], v[92:95]
	v_mfma_f32_16x16x32_bf16 v[88:91], v[140:143], v[148:151], v[88:91]
	v_mfma_f32_16x16x32_bf16 v[84:87], v[132:135], v[194:197], v[84:87]
	v_mfma_f32_16x16x32_bf16 v[80:83], v[140:143], v[194:197], v[80:83]
	v_mfma_f32_16x16x32_bf16 v[76:79], v[132:135], v[202:205], v[76:79]
	v_mfma_f32_16x16x32_bf16 v[72:75], v[140:143], v[202:205], v[72:75]
	v_mfma_f32_16x16x32_bf16 v[68:71], v[132:135], v[210:213], v[68:71]
	s_setprio 0
	v_mfma_f32_16x16x32_bf16 v[64:67], v[140:143], v[210:213], v[64:67]
	s_barrier
	s_add_u32 s24, s28, 0x80080
	s_addc_u32 s25, s29, 0
	s_add_i32 s28, s30, s37
	s_mov_b32 m0, s28
	s_nop 0
	global_load_lds_dwordx4 v188, s[24:25]
	s_add_i32 m0, s28, 0x2000
	s_nop 0
	global_load_lds_dwordx4 v186, s[24:25]
	s_waitcnt vmcnt(6)
	s_setprio 1
	s_barrier
	v_mfma_f32_16x16x32_bf16 v[28:31], v[214:217], v[144:147], v[28:31]
	v_mfma_f32_16x16x32_bf16 v[24:27], v[234:237], v[144:147], v[24:27]
	v_mfma_f32_16x16x32_bf16 v[20:23], v[214:217], v[152:155], v[20:23]
	v_mfma_f32_16x16x32_bf16 v[16:19], v[234:237], v[152:155], v[16:19]
	v_mfma_f32_16x16x32_bf16 v[12:15], v[214:217], v[198:201], v[12:15]
	v_mfma_f32_16x16x32_bf16 v[8:11], v[234:237], v[198:201], v[8:11]
	v_mfma_f32_16x16x32_bf16 v[4:7], v[214:217], v[206:209], v[4:7]
	v_mfma_f32_16x16x32_bf16 v[0:3], v[234:237], v[206:209], v[0:3]
	v_mfma_f32_16x16x32_bf16 v[28:31], v[230:233], v[148:151], v[28:31]
	s_add_i32 s46, s46, 2
	v_mfma_f32_16x16x32_bf16 v[24:27], v[238:241], v[148:151], v[24:27]
	s_add_u32 s33, s33, 0x100
	v_mfma_f32_16x16x32_bf16 v[20:23], v[230:233], v[194:197], v[20:23]
	s_addc_u32 s45, s45, 0
	v_mfma_f32_16x16x32_bf16 v[16:19], v[238:241], v[194:197], v[16:19]
	s_cmp_gt_u32 s46, 29
	v_mfma_f32_16x16x32_bf16 v[12:15], v[230:233], v[202:205], v[12:15]
	s_mov_b64 s[24:25], s[26:27]
	v_mfma_f32_16x16x32_bf16 v[8:11], v[238:241], v[202:205], v[8:11]
	v_mfma_f32_16x16x32_bf16 v[4:7], v[230:233], v[210:213], v[4:7]
	s_setprio 0
	v_mfma_f32_16x16x32_bf16 v[0:3], v[238:241], v[210:213], v[0:3]
	s_barrier
	s_cbranch_scc0 .LBB0_320
	v_lshl_add_u32 v206, s3, 8, v225
	v_lshl_or_b32 v158, s2, 8, v227
	v_lshlrev_b32_e32 v232, 11, v206
	s_andn2_b64 vcc, exec, s[14:15]
	v_or_b32_e32 v231, 16, v158
	v_add_u32_e32 v194, v232, v158
	v_or_b32_e32 v230, 0x80, v158
	v_or_b32_e32 v229, 0x90, v158
	s_cbranch_vccnz .LBB0_323
	v_lshlrev_b64 v[132:133], 2, v[158:159]
	v_lshl_add_u64 v[140:141], s[16:17], 0, v[132:133]
	global_load_dwordx4 v[128:131], v[140:141], off
	v_lshl_add_u64 v[142:143], s[18:19], 0, v[132:133]
	v_readlane_b32 s2, v253, 8
	v_mov_b32_e32 v195, v159
	v_lshlrev_b32_e32 v136, 1, v206
	v_mov_b32_e32 v137, v159
	v_readlane_b32 s3, v253, 9
	v_lshlrev_b64 v[212:213], 2, v[194:195]
	v_add_u32_e32 v146, v232, v231
	v_lshl_add_u64 v[144:145], v[136:137], 2, s[2:3]
	v_lshl_add_u64 v[136:137], s[88:89], 0, v[212:213]
	v_mov_b32_e32 v147, v159
	v_lshl_add_u64 v[146:147], v[146:147], 2, s[88:89]
	v_or_b32_e32 v195, 16, v206
	v_mov_b32_e32 v201, v159
	v_mov_b32_e32 v209, v159
	v_lshl_add_u64 v[212:213], s[90:91], 0, v[212:213]
	s_waitcnt vmcnt(0)
	v_pk_mul_f32 v[152:153], v[130:131], s[78:79] op_sel_hi:[1,0]
	v_pk_mul_f32 v[154:155], v[128:129], s[78:79] op_sel_hi:[1,0]
	global_load_dwordx4 v[132:135], v[142:143], off
	global_load_dwordx4 v[128:131], v[140:141], off offset:64
	global_load_dwordx2 v[204:205], v[144:145], off
	global_load_dwordx4 v[196:199], v[146:147], off
	v_lshlrev_b32_e32 v146, 1, v195
	global_load_dwordx4 v[136:139], v[136:137], off
	v_lshlrev_b32_e32 v195, 11, v195
	v_mov_b32_e32 v147, v159
	v_add_u32_e32 v200, v195, v158
	v_lshl_add_u64 v[146:147], v[146:147], 2, s[2:3]
	v_lshl_add_u64 v[200:201], v[200:201], 2, s[88:89]
	global_load_dwordx2 v[214:215], v[146:147], off
	v_add_u32_e32 v208, v195, v231
	global_load_dwordx4 v[200:203], v[200:201], off
	v_lshl_add_u64 v[208:209], v[208:209], 2, s[88:89]
	global_load_dwordx4 v[208:211], v[208:209], off
	s_waitcnt vmcnt(0)
	v_pk_mul_f32 v[148:149], v[130:131], s[78:79] op_sel_hi:[1,0]
	v_pk_mul_f32 v[150:151], v[128:129], s[78:79] op_sel_hi:[1,0]
	global_load_dwordx4 v[128:131], v[142:143], off offset:64
	v_sub_f32_e32 v137, v137, v204
	v_sub_f32_e32 v136, v136, v204
	v_sub_f32_e32 v139, v139, v204
	v_sub_f32_e32 v138, v138, v204
	v_pk_mul_f32 v[138:139], v[204:205], v[138:139] op_sel:[1,0]
	v_pk_mul_f32 v[136:137], v[204:205], v[136:137] op_sel:[1,0]
	v_pk_fma_f32 v[138:139], v[152:153], v[138:139], v[126:127]
	v_pk_fma_f32 v[136:137], v[154:155], v[136:137], v[124:125]
	v_pk_fma_f32 v[138:139], v[134:135], s[78:79], v[138:139] op_sel_hi:[1,0,1]
	v_pk_fma_f32 v[136:137], v[132:133], s[78:79], v[136:137] op_sel_hi:[1,0,1]
	global_store_dwordx4 v[212:213], v[136:139], off
	s_nop 1
	v_sub_f32_e32 v137, v197, v204
	v_sub_f32_e32 v136, v196, v204
	v_sub_f32_e32 v139, v199, v204
	v_sub_f32_e32 v138, v198, v204
	v_pk_mul_f32 v[138:139], v[204:205], v[138:139] op_sel:[1,0]
	v_pk_mul_f32 v[136:137], v[204:205], v[136:137] op_sel:[1,0]
	v_pk_fma_f32 v[138:139], v[148:149], v[138:139], v[122:123]
	v_pk_fma_f32 v[136:137], v[150:151], v[136:137], v[120:121]
	v_or_b32_e32 v196, 16, v194
	v_mov_b32_e32 v197, v159
	v_lshl_add_u64 v[196:197], v[196:197], 2, s[90:91]
	s_waitcnt vmcnt(0)
;     template <bool LN, int BJ, int LO, int HI> DI void batch(const f32x4 (&acc)[2][2][4][2], unsigned row0, unsigned col0, const f32x4 (&gv)[2], const f32x4 (&bv)[2]) const {
;         f32x4 r[HI - LO]; float mean[(HI - LO) / 2], rstd[(HI - LO) / 2];
; #pragma unroll
;         for (int i = LO; i < HI; ++i) { const int ai = i >> 3, m = (i >> 1) & 3, n = i & 1; const unsigned row = row0 + ai * HALF + m * 16;
;             if (n == 0) { mean[(i - LO) >> 1] = 0.f; rstd[(i - LO) >> 1] = 1.f;
;                 if (LN) { const float2 st = *(const float2*)(stats + row * 2u); mean[(i - LO) >> 1] = st.x; rstd[(i - LO) >> 1] = st.y; } }
;             r[i - LO] = *(const f32x4*)(src + (row * (unsigned)DM + col0 + BJ * HALF + n * 16)); }
; #pragma unroll
;         for (int i = LO; i < HI; ++i) { const int ai = i >> 3, m = (i >> 1) & 3, n = i & 1; const unsigned row = row0 + ai * HALF + m * 16;
;             *(f32x4*)(Y + (row * (unsigned)DM + col0 + BJ * HALF + n * 16)) = acc[ai][BJ][m][n] + ((r[i - LO] - mean[(i - LO) >> 1]) * rstd[(i - LO) >> 1]) * gv[n] + bv[n]; }
	v_pk_fma_f32 v[138:139], v[130:131], s[78:79], v[138:139] op_sel_hi:[1,0,1]
	v_pk_fma_f32 v[136:137], v[128:129], s[78:79], v[136:137] op_sel_hi:[1,0,1]
	global_store_dwordx4 v[196:197], v[136:139], off
	v_add_u32_e32 v196, 0x8000, v194
	v_mov_b32_e32 v197, v159
	v_sub_f32_e32 v137, v201, v214
	v_sub_f32_e32 v136, v200, v214
	v_sub_f32_e32 v139, v203, v214
	v_sub_f32_e32 v138, v202, v214
	v_pk_mul_f32 v[138:139], v[214:215], v[138:139] op_sel:[1,0]
	v_pk_mul_f32 v[136:137], v[214:215], v[136:137] op_sel:[1,0]
	v_pk_fma_f32 v[138:139], v[152:153], v[138:139], v[118:119]
	v_pk_fma_f32 v[136:137], v[154:155], v[136:137], v[116:117]
	v_pk_fma_f32 v[138:139], v[134:135], s[78:79], v[138:139] op_sel_hi:[1,0,1]
	v_pk_fma_f32 v[136:137], v[132:133], s[78:79], v[136:137] op_sel_hi:[1,0,1]
	v_lshl_add_u64 v[196:197], v[196:197], 2, s[90:91]
	global_store_dwordx4 v[196:197], v[136:139], off
	v_add_u32_e32 v196, 0x8010, v194
	v_mov_b32_e32 v197, v159
	v_sub_f32_e32 v137, v209, v214
	v_sub_f32_e32 v136, v208, v214
	v_sub_f32_e32 v139, v211, v214
	v_sub_f32_e32 v138, v210, v214
	v_pk_mul_f32 v[138:139], v[214:215], v[138:139] op_sel:[1,0]
	v_pk_mul_f32 v[136:137], v[214:215], v[136:137] op_sel:[1,0]
	v_pk_fma_f32 v[138:139], v[148:149], v[138:139], v[114:115]
	v_pk_fma_f32 v[136:137], v[150:151], v[136:137], v[112:113]
	v_pk_fma_f32 v[138:139], v[130:131], s[78:79], v[138:139] op_sel_hi:[1,0,1]
	v_pk_fma_f32 v[136:137], v[128:129], s[78:79], v[136:137] op_sel_hi:[1,0,1]
	v_lshl_add_u64 v[196:197], v[196:197], 2, s[90:91]
	global_store_dwordx4 v[196:197], v[136:139], off
	s_nop 1
	v_or_b32_e32 v138, 32, v206
	v_lshlrev_b32_e32 v136, 1, v138
	v_mov_b32_e32 v137, v159
	v_lshlrev_b32_e32 v236, 11, v138
	v_lshl_add_u64 v[200:201], v[136:137], 2, s[2:3]
	v_add_u32_e32 v136, v236, v158
	v_lshl_add_u64 v[136:137], v[136:137], 2, s[88:89]
	global_load_dwordx2 v[204:205], v[200:201], off
	v_add_u32_e32 v196, v236, v231
	global_load_dwordx4 v[136:139], v[136:137], off
	v_mov_b32_e32 v197, v159
	v_lshl_add_u64 v[196:197], v[196:197], 2, s[88:89]
	global_load_dwordx4 v[196:199], v[196:197], off
	v_or_b32_e32 v207, 48, v206
	v_lshlrev_b32_e32 v235, 11, v207
	v_lshlrev_b32_e32 v202, 1, v207
	v_mov_b32_e32 v203, v159
	v_add_u32_e32 v208, v235, v158
	v_mov_b32_e32 v209, v159
	v_lshl_add_u64 v[202:203], v[202:203], 2, s[2:3]
	v_lshl_add_u64 v[208:209], v[208:209], 2, s[88:89]
	global_load_dwordx2 v[216:217], v[202:203], off
	v_add_u32_e32 v212, v235, v231
	global_load_dwordx4 v[208:211], v[208:209], off
	v_mov_b32_e32 v213, v159
	v_lshl_add_u64 v[212:213], v[212:213], 2, s[88:89]
	global_load_dwordx4 v[212:215], v[212:213], off
	v_add_u32_e32 v218, 0x10000, v194
	v_mov_b32_e32 v219, v159
	v_lshl_add_u64 v[218:219], v[218:219], 2, s[90:91]
	s_waitcnt vmcnt(0)
	v_sub_f32_e32 v137, v137, v204
	v_sub_f32_e32 v136, v136, v204
	v_sub_f32_e32 v139, v139, v204
	v_sub_f32_e32 v138, v138, v204
	v_pk_mul_f32 v[138:139], v[204:205], v[138:139] op_sel:[1,0]
	v_pk_mul_f32 v[136:137], v[204:205], v[136:137] op_sel:[1,0]
	v_pk_fma_f32 v[138:139], v[152:153], v[138:139], v[110:111]
	v_pk_fma_f32 v[136:137], v[154:155], v[136:137], v[108:109]
	v_pk_fma_f32 v[138:139], v[134:135], s[78:79], v[138:139] op_sel_hi:[1,0,1]
	v_pk_fma_f32 v[136:137], v[132:133], s[78:79], v[136:137] op_sel_hi:[1,0,1]
	global_store_dwordx4 v[218:219], v[136:139], off
	s_nop 1
	v_sub_f32_e32 v137, v197, v204
	v_sub_f32_e32 v136, v196, v204
	v_sub_f32_e32 v139, v199, v204
	v_sub_f32_e32 v138, v198, v204
	v_pk_mul_f32 v[138:139], v[204:205], v[138:139] op_sel:[1,0]
	v_pk_mul_f32 v[136:137], v[204:205], v[136:137] op_sel:[1,0]
	v_pk_fma_f32 v[138:139], v[148:149], v[138:139], v[106:107]
	v_pk_fma_f32 v[136:137], v[150:151], v[136:137], v[104:105]
	v_add_u32_e32 v196, 0x10010, v194
	v_mov_b32_e32 v197, v159
	v_pk_fma_f32 v[138:139], v[130:131], s[78:79], v[138:139] op_sel_hi:[1,0,1]
	v_pk_fma_f32 v[136:137], v[128:129], s[78:79], v[136:137] op_sel_hi:[1,0,1]
	v_lshl_add_u64 v[196:197], v[196:197], 2, s[90:91]
	global_store_dwordx4 v[196:197], v[136:139], off
	v_add_u32_e32 v196, 0x18000, v194
	v_mov_b32_e32 v197, v159
	v_sub_f32_e32 v137, v209, v216
	v_sub_f32_e32 v136, v208, v216
	v_sub_f32_e32 v139, v211, v216
	v_sub_f32_e32 v138, v210, v216
	v_pk_mul_f32 v[138:139], v[216:217], v[138:139] op_sel:[1,0]
	v_pk_mul_f32 v[136:137], v[216:217], v[136:137] op_sel:[1,0]
	v_pk_fma_f32 v[138:139], v[152:153], v[138:139], v[102:103]
	v_pk_fma_f32 v[136:137], v[154:155], v[136:137], v[100:101]
	v_pk_fma_f32 v[138:139], v[134:135], s[78:79], v[138:139] op_sel_hi:[1,0,1]
	v_pk_fma_f32 v[136:137], v[132:133], s[78:79], v[136:137] op_sel_hi:[1,0,1]
	v_lshl_add_u64 v[196:197], v[196:197], 2, s[90:91]
	global_store_dwordx4 v[196:197], v[136:139], off
	v_add_u32_e32 v196, 0x18010, v194
	v_mov_b32_e32 v197, v159
	v_sub_f32_e32 v137, v213, v216
	v_sub_f32_e32 v136, v212, v216
	v_sub_f32_e32 v139, v215, v216
	v_sub_f32_e32 v138, v214, v216
	v_pk_mul_f32 v[138:139], v[216:217], v[138:139] op_sel:[1,0]
	v_pk_mul_f32 v[136:137], v[216:217], v[136:137] op_sel:[1,0]
	v_pk_fma_f32 v[138:139], v[148:149], v[138:139], v[98:99]
	v_pk_fma_f32 v[136:137], v[150:151], v[136:137], v[96:97]
	v_pk_fma_f32 v[138:139], v[130:131], s[78:79], v[138:139] op_sel_hi:[1,0,1]
	v_pk_fma_f32 v[136:137], v[128:129], s[78:79], v[136:137] op_sel_hi:[1,0,1]
	v_lshl_add_u64 v[196:197], v[196:197], 2, s[90:91]
	global_store_dwordx4 v[196:197], v[136:139], off
	s_nop 1
	v_add_u32_e32 v138, 0x80, v206
	v_lshlrev_b32_e32 v136, 1, v138
	v_mov_b32_e32 v137, v159
	v_lshlrev_b32_e32 v233, 11, v138
	v_lshl_add_u64 v[196:197], v[136:137], 2, s[2:3]
	v_add_u32_e32 v136, v233, v158
	v_lshl_add_u64 v[136:137], v[136:137], 2, s[88:89]
	global_load_dwordx2 v[204:205], v[196:197], off
	v_add_u32_e32 v198, v233, v231
	global_load_dwordx4 v[136:139], v[136:137], off
	v_mov_b32_e32 v199, v159
	v_add_u32_e32 v207, 0x90, v206
	v_lshl_add_u64 v[198:199], v[198:199], 2, s[88:89]
	v_lshlrev_b32_e32 v234, 11, v207
	global_load_dwordx4 v[208:211], v[198:199], off
	v_add_u32_e32 v212, v234, v158
	v_mov_b32_e32 v213, v159
	v_lshl_add_u64 v[212:213], v[212:213], 2, s[88:89]
	global_load_dwordx4 v[212:215], v[212:213], off
	v_lshlrev_b32_e32 v198, 1, v207
	v_mov_b32_e32 v199, v159
	v_lshl_add_u64 v[198:199], v[198:199], 2, s[2:3]
	global_load_dwordx2 v[238:239], v[198:199], off
	v_add_u32_e32 v216, v234, v231
	v_mov_b32_e32 v217, v159
	v_lshl_add_u64 v[216:217], v[216:217], 2, s[88:89]
	global_load_dwordx4 v[216:219], v[216:217], off
	v_add_u32_e32 v240, 0x40000, v194
	v_mov_b32_e32 v241, v159
	v_lshl_add_u64 v[240:241], v[240:241], 2, s[90:91]
	s_waitcnt vmcnt(0)
;     template <bool LN, int BJ, int LO, int HI> DI void batch(const f32x4 (&acc)[2][2][4][2], unsigned row0, unsigned col0, const f32x4 (&gv)[2], const f32x4 (&bv)[2]) const {
;         f32x4 r[HI - LO]; float mean[(HI - LO) / 2], rstd[(HI - LO) / 2];
; #pragma unroll
;         for (int i = LO; i < HI; ++i) { const int ai = i >> 3, m = (i >> 1) & 3, n = i & 1; const unsigned row = row0 + ai * HALF + m * 16;
;             if (n == 0) { mean[(i - LO) >> 1] = 0.f; rstd[(i - LO) >> 1] = 1.f;
;                 if (LN) { const float2 st = *(const float2*)(stats + row * 2u); mean[(i - LO) >> 1] = st.x; rstd[(i - LO) >> 1] = st.y; } }
;             r[i - LO] = *(const f32x4*)(src + (row * (unsigned)DM + col0 + BJ * HALF + n * 16)); }
; #pragma unroll
;         for (int i = LO; i < HI; ++i) { const int ai = i >> 3, m = (i >> 1) & 3, n = i & 1; const unsigned row = row0 + ai * HALF + m * 16;
;             *(f32x4*)(Y + (row * (unsigned)DM + col0 + BJ * HALF + n * 16)) = acc[ai][BJ][m][n] + ((r[i - LO] - mean[(i - LO) >> 1]) * rstd[(i - LO) >> 1]) * gv[n] + bv[n]; }
	v_sub_f32_e32 v137, v137, v204
	v_sub_f32_e32 v136, v136, v204
	v_sub_f32_e32 v139, v139, v204
	v_sub_f32_e32 v138, v138, v204
	v_pk_mul_f32 v[138:139], v[204:205], v[138:139] op_sel:[1,0]
	v_pk_mul_f32 v[136:137], v[204:205], v[136:137] op_sel:[1,0]
	v_pk_fma_f32 v[138:139], v[152:153], v[138:139], v[94:95]
	v_pk_fma_f32 v[136:137], v[154:155], v[136:137], v[92:93]
	v_pk_fma_f32 v[138:139], v[134:135], s[78:79], v[138:139] op_sel_hi:[1,0,1]
	v_pk_fma_f32 v[136:137], v[132:133], s[78:79], v[136:137] op_sel_hi:[1,0,1]
	global_store_dwordx4 v[240:241], v[136:139], off
	s_nop 1
	v_sub_f32_e32 v137, v209, v204
	v_sub_f32_e32 v136, v208, v204
	v_sub_f32_e32 v139, v211, v204
	v_sub_f32_e32 v138, v210, v204
	v_pk_mul_f32 v[138:139], v[204:205], v[138:139] op_sel:[1,0]
	v_pk_mul_f32 v[136:137], v[204:205], v[136:137] op_sel:[1,0]
	v_pk_fma_f32 v[138:139], v[148:149], v[138:139], v[90:91]
	v_pk_fma_f32 v[136:137], v[150:151], v[136:137], v[88:89]
	v_add_u32_e32 v204, 0x40010, v194
	v_mov_b32_e32 v205, v159
	v_pk_fma_f32 v[138:139], v[130:131], s[78:79], v[138:139] op_sel_hi:[1,0,1]
	v_pk_fma_f32 v[136:137], v[128:129], s[78:79], v[136:137] op_sel_hi:[1,0,1]
	v_lshl_add_u64 v[204:205], v[204:205], 2, s[90:91]
	global_store_dwordx4 v[204:205], v[136:139], off
	v_add_u32_e32 v204, 0x48000, v194
	v_mov_b32_e32 v205, v159
	v_sub_f32_e32 v137, v213, v238
	v_sub_f32_e32 v136, v212, v238
	v_sub_f32_e32 v139, v215, v238
	v_sub_f32_e32 v138, v214, v238
	v_pk_mul_f32 v[138:139], v[238:239], v[138:139] op_sel:[1,0]
	v_pk_mul_f32 v[136:137], v[238:239], v[136:137] op_sel:[1,0]
	v_pk_fma_f32 v[138:139], v[152:153], v[138:139], v[86:87]
	v_pk_fma_f32 v[136:137], v[154:155], v[136:137], v[84:85]
	v_pk_fma_f32 v[138:139], v[134:135], s[78:79], v[138:139] op_sel_hi:[1,0,1]
	v_pk_fma_f32 v[136:137], v[132:133], s[78:79], v[136:137] op_sel_hi:[1,0,1]
	v_lshl_add_u64 v[204:205], v[204:205], 2, s[90:91]
	global_store_dwordx4 v[204:205], v[136:139], off
	v_add_u32_e32 v204, 0x48010, v194
	v_mov_b32_e32 v205, v159
	v_sub_f32_e32 v137, v217, v238
	v_sub_f32_e32 v136, v216, v238
	v_sub_f32_e32 v139, v219, v238
	v_sub_f32_e32 v138, v218, v238
	v_pk_mul_f32 v[138:139], v[238:239], v[138:139] op_sel:[1,0]
	v_pk_mul_f32 v[136:137], v[238:239], v[136:137] op_sel:[1,0]
	v_pk_fma_f32 v[138:139], v[148:149], v[138:139], v[82:83]
	v_pk_fma_f32 v[136:137], v[150:151], v[136:137], v[80:81]
	v_pk_fma_f32 v[138:139], v[130:131], s[78:79], v[138:139] op_sel_hi:[1,0,1]
	v_pk_fma_f32 v[136:137], v[128:129], s[78:79], v[136:137] op_sel_hi:[1,0,1]
	v_lshl_add_u64 v[204:205], v[204:205], 2, s[90:91]
	global_store_dwordx4 v[204:205], v[136:139], off
	s_nop 1
	v_add_u32_e32 v138, 0xa0, v206
	v_lshlrev_b32_e32 v136, 1, v138
	v_mov_b32_e32 v137, v159
	v_lshlrev_b32_e32 v237, 11, v138
	v_lshl_add_u64 v[204:205], v[136:137], 2, s[2:3]
	v_add_u32_e32 v136, v237, v158
	v_lshl_add_u64 v[136:137], v[136:137], 2, s[88:89]
	global_load_dwordx2 v[240:241], v[204:205], off
	v_add_u32_e32 v208, v237, v231
	global_load_dwordx4 v[136:139], v[136:137], off
	v_mov_b32_e32 v209, v159
	v_lshl_add_u64 v[208:209], v[208:209], 2, s[88:89]
	global_load_dwordx4 v[212:215], v[208:209], off
	v_add_u32_e32 v208, 0xb0, v206
	v_lshlrev_b32_e32 v206, 1, v208
	v_mov_b32_e32 v207, v159
	v_lshlrev_b32_e32 v238, 11, v208
	v_lshl_add_u64 v[210:211], v[206:207], 2, s[2:3]
	v_add_u32_e32 v206, v238, v158
	v_lshl_add_u64 v[206:207], v[206:207], 2, s[88:89]
	global_load_dwordx2 v[242:243], v[210:211], off
	v_add_u32_e32 v216, v238, v231
	global_load_dwordx4 v[206:209], v[206:207], off
	v_mov_b32_e32 v217, v159
	v_lshl_add_u64 v[216:217], v[216:217], 2, s[88:89]
	global_load_dwordx4 v[216:219], v[216:217], off
	v_add_u32_e32 v244, 0x50000, v194
	v_mov_b32_e32 v245, v159
	v_lshl_add_u64 v[244:245], v[244:245], 2, s[90:91]
	s_waitcnt vmcnt(0)
	v_sub_f32_e32 v137, v137, v240
	v_sub_f32_e32 v136, v136, v240
	v_sub_f32_e32 v139, v139, v240
	v_sub_f32_e32 v138, v138, v240
	v_pk_mul_f32 v[138:139], v[240:241], v[138:139] op_sel:[1,0]
	v_pk_mul_f32 v[136:137], v[240:241], v[136:137] op_sel:[1,0]
	v_pk_fma_f32 v[138:139], v[152:153], v[138:139], v[78:79]
	v_pk_fma_f32 v[136:137], v[154:155], v[136:137], v[76:77]
	v_pk_fma_f32 v[138:139], v[134:135], s[78:79], v[138:139] op_sel_hi:[1,0,1]
	v_pk_fma_f32 v[136:137], v[132:133], s[78:79], v[136:137] op_sel_hi:[1,0,1]
	global_store_dwordx4 v[244:245], v[136:139], off
	s_nop 1
	v_sub_f32_e32 v137, v213, v240
	v_sub_f32_e32 v136, v212, v240
	v_sub_f32_e32 v139, v215, v240
	v_sub_f32_e32 v138, v214, v240
	v_pk_mul_f32 v[138:139], v[240:241], v[138:139] op_sel:[1,0]
	v_pk_mul_f32 v[136:137], v[240:241], v[136:137] op_sel:[1,0]
	v_pk_fma_f32 v[138:139], v[148:149], v[138:139], v[74:75]
	v_pk_fma_f32 v[136:137], v[150:151], v[136:137], v[72:73]
	v_add_u32_e32 v212, 0x50010, v194
	v_mov_b32_e32 v213, v159
	v_pk_fma_f32 v[138:139], v[130:131], s[78:79], v[138:139] op_sel_hi:[1,0,1]
	v_pk_fma_f32 v[136:137], v[128:129], s[78:79], v[136:137] op_sel_hi:[1,0,1]
	v_lshl_add_u64 v[212:213], v[212:213], 2, s[90:91]
	global_store_dwordx4 v[212:213], v[136:139], off
	s_nop 1
	v_sub_f32_e32 v137, v207, v242
	v_sub_f32_e32 v136, v206, v242
	v_sub_f32_e32 v139, v209, v242
	v_sub_f32_e32 v138, v208, v242
	v_pk_mul_f32 v[136:137], v[242:243], v[136:137] op_sel:[1,0]
	v_pk_mul_f32 v[138:139], v[242:243], v[138:139] op_sel:[1,0]
	v_pk_fma_f32 v[136:137], v[154:155], v[136:137], v[68:69]
	v_pk_fma_f32 v[138:139], v[152:153], v[138:139], v[70:71]
	v_pk_fma_f32 v[132:133], v[132:133], s[78:79], v[136:137] op_sel_hi:[1,0,1]
	v_add_u32_e32 v136, 0x58000, v194
	v_mov_b32_e32 v137, v159
	v_pk_fma_f32 v[134:135], v[134:135], s[78:79], v[138:139] op_sel_hi:[1,0,1]
	v_lshl_add_u64 v[136:137], v[136:137], 2, s[90:91]
	global_store_dwordx4 v[136:137], v[132:135], off
	s_nop 1
	v_sub_f32_e32 v133, v217, v242
	v_sub_f32_e32 v132, v216, v242
	v_sub_f32_e32 v135, v219, v242
	v_sub_f32_e32 v134, v218, v242
	v_pk_mul_f32 v[132:133], v[242:243], v[132:133] op_sel:[1,0]
	v_pk_mul_f32 v[134:135], v[242:243], v[134:135] op_sel:[1,0]
	v_pk_fma_f32 v[132:133], v[150:151], v[132:133], v[64:65]
	v_pk_fma_f32 v[134:135], v[148:149], v[134:135], v[66:67]
	v_pk_fma_f32 v[128:129], v[128:129], s[78:79], v[132:133] op_sel_hi:[1,0,1]
	v_add_u32_e32 v132, 0x58010, v194
	v_mov_b32_e32 v133, v159
	v_pk_fma_f32 v[130:131], v[130:131], s[78:79], v[134:135] op_sel_hi:[1,0,1]
	v_lshl_add_u64 v[132:133], v[132:133], 2, s[90:91]
	global_store_dwordx4 v[132:133], v[128:131], off
	global_load_dwordx4 v[128:131], v[140:141], off offset:512
	v_add_u32_e32 v136, v232, v230
	v_mov_b32_e32 v137, v159
	v_lshl_add_u64 v[136:137], v[136:137], 2, s[88:89]
	s_waitcnt vmcnt(0)
;     template <bool LN, int BJ, int LO, int HI> DI void batch(const f32x4 (&acc)[2][2][4][2], unsigned row0, unsigned col0, const f32x4 (&gv)[2], const f32x4 (&bv)[2]) const {
;         f32x4 r[HI - LO]; float mean[(HI - LO) / 2], rstd[(HI - LO) / 2];
; #pragma unroll
;         for (int i = LO; i < HI; ++i) { const int ai = i >> 3, m = (i >> 1) & 3, n = i & 1; const unsigned row = row0 + ai * HALF + m * 16;
;             if (n == 0) { mean[(i - LO) >> 1] = 0.f; rstd[(i - LO) >> 1] = 1.f;
;                 if (LN) { const float2 st = *(const float2*)(stats + row * 2u); mean[(i - LO) >> 1] = st.x; rstd[(i - LO) >> 1] = st.y; } }
;             r[i - LO] = *(const f32x4*)(src + (row * (unsigned)DM + col0 + BJ * HALF + n * 16)); }
; #pragma unroll
;         for (int i = LO; i < HI; ++i) { const int ai = i >> 3, m = (i >> 1) & 3, n = i & 1; const unsigned row = row0 + ai * HALF + m * 16;
;             *(f32x4*)(Y + (row * (unsigned)DM + col0 + BJ * HALF + n * 16)) = acc[ai][BJ][m][n] + ((r[i - LO] - mean[(i - LO) >> 1]) * rstd[(i - LO) >> 1]) * gv[n] + bv[n]; }
;         __builtin_amdgcn_sched_barrier(0);
;     }
;     template <bool LN, int BJ> DI void load_gb(unsigned col0, f32x4 (&gv)[2], f32x4 (&bv)[2]) const {
; #pragma unroll
;         for (int n = 0; n < 2; ++n) {
;             if (LN) { gv[n] = *(const f32x4*)(gam + col0 + BJ * HALF + n * 16) * ALPHA; bv[n] = *(const f32x4*)(bet + col0 + BJ * HALF + n * 16) * ALPHA; }
;             else { gv[n] = (f32x4){ALPHA, ALPHA, ALPHA, ALPHA}; bv[n] = (f32x4){0.f, 0.f, 0.f, 0.f}; }
;         }
;     }
;     template <bool LN> DI void run(const f32x4 (&acc)[2][2][4][2], const Unit& u, int wr, int wc, int fr, int fq) const {
;         const unsigned row0 = u.pm * BM + wr * 64 + fr, col0 = u.pn * BM + wc * 32 + 4 * fq;
;         f32x4 gv[2], bv[2];
;         load_gb<LN, 0>(col0, gv, bv);
;         batch<LN, 0, 0, 4>(acc, row0, col0, gv, bv);
;         batch<LN, 0, 4, 8>(acc, row0, col0, gv, bv);
;         batch<LN, 0, 8, 12>(acc, row0, col0, gv, bv);
;         batch<LN, 0, 12, 16>(acc, row0, col0, gv, bv);
;         load_gb<LN, 1>(col0, gv, bv);
;         batch<LN, 1, 0, 8>(acc, row0, col0, gv, bv);
;         batch<LN, 1, 8, 16>(acc, row0, col0, gv, bv);
	v_pk_mul_f32 v[212:213], v[130:131], s[78:79] op_sel_hi:[1,0]
	v_pk_mul_f32 v[214:215], v[128:129], s[78:79] op_sel_hi:[1,0]
	global_load_dwordx4 v[132:135], v[142:143], off offset:512
	global_load_dwordx4 v[128:131], v[140:141], off offset:576
	s_waitcnt vmcnt(0)
	v_pk_mul_f32 v[206:207], v[130:131], s[78:79] op_sel_hi:[1,0]
	v_pk_mul_f32 v[208:209], v[128:129], s[78:79] op_sel_hi:[1,0]
	global_load_dwordx4 v[128:131], v[142:143], off offset:576
	global_load_dwordx2 v[220:221], v[144:145], off
	global_load_dwordx4 v[240:243], v[136:137], off
	v_add_u32_e32 v136, v232, v229
	v_mov_b32_e32 v137, v159
	v_lshl_add_u64 v[136:137], v[136:137], 2, s[88:89]
	global_load_dwordx4 v[244:247], v[136:137], off
	global_load_dwordx2 v[218:219], v[146:147], off
	v_add_u32_e32 v136, v195, v230
	v_mov_b32_e32 v137, v159
	v_lshl_add_u64 v[136:137], v[136:137], 2, s[88:89]
	global_load_dwordx4 v[248:251], v[136:137], off
	v_add_u32_e32 v136, v195, v229
	v_mov_b32_e32 v137, v159
	v_lshl_add_u64 v[136:137], v[136:137], 2, s[88:89]
	global_load_dwordx4 v[152:155], v[136:137], off
	global_load_dwordx2 v[216:217], v[200:201], off
	v_add_u32_e32 v136, v236, v230
	v_mov_b32_e32 v137, v159
	v_lshl_add_u64 v[136:137], v[136:137], 2, s[88:89]
	global_load_dwordx4 v[148:151], v[136:137], off
	v_add_u32_e32 v136, v236, v229
	v_mov_b32_e32 v137, v159
	v_lshl_add_u64 v[136:137], v[136:137], 2, s[88:89]
	global_load_dwordx4 v[144:147], v[136:137], off
	global_load_dwordx2 v[200:201], v[202:203], off
	v_add_u32_e32 v136, v235, v230
	v_mov_b32_e32 v137, v159
	v_lshl_add_u64 v[136:137], v[136:137], 2, s[88:89]
	global_load_dwordx4 v[140:143], v[136:137], off
	v_add_u32_e32 v136, v235, v229
	v_mov_b32_e32 v137, v159
	v_lshl_add_u64 v[136:137], v[136:137], 2, s[88:89]
	global_load_dwordx4 v[136:139], v[136:137], off
	v_add_u32_e32 v202, 0x80, v194
	v_mov_b32_e32 v203, v159
	v_lshl_add_u64 v[202:203], v[202:203], 2, s[90:91]
	s_waitcnt vmcnt(0)
	v_sub_f32_e32 v241, v241, v220
	v_sub_f32_e32 v240, v240, v220
	v_sub_f32_e32 v243, v243, v220
	v_sub_f32_e32 v242, v242, v220
	v_pk_mul_f32 v[242:243], v[220:221], v[242:243] op_sel:[1,0]
	v_pk_mul_f32 v[240:241], v[220:221], v[240:241] op_sel:[1,0]
	v_pk_fma_f32 v[242:243], v[212:213], v[242:243], v[62:63]
	v_pk_fma_f32 v[240:241], v[214:215], v[240:241], v[60:61]
	v_pk_fma_f32 v[242:243], v[134:135], s[78:79], v[242:243] op_sel_hi:[1,0,1]
	v_pk_fma_f32 v[240:241], v[132:133], s[78:79], v[240:241] op_sel_hi:[1,0,1]
	global_store_dwordx4 v[202:203], v[240:243], off
	v_sub_f32_e32 v203, v245, v220
	v_sub_f32_e32 v202, v244, v220
	v_sub_f32_e32 v241, v247, v220
	v_sub_f32_e32 v240, v246, v220
	v_pk_mul_f32 v[202:203], v[220:221], v[202:203] op_sel:[1,0]
	v_pk_mul_f32 v[240:241], v[220:221], v[240:241] op_sel:[1,0]
	v_pk_fma_f32 v[202:203], v[208:209], v[202:203], v[56:57]
	v_pk_fma_f32 v[220:221], v[206:207], v[240:241], v[58:59]
	v_pk_fma_f32 v[240:241], v[128:129], s[78:79], v[202:203] op_sel_hi:[1,0,1]
	v_add_u32_e32 v202, 0x90, v194
	v_mov_b32_e32 v203, v159
	v_pk_fma_f32 v[242:243], v[130:131], s[78:79], v[220:221] op_sel_hi:[1,0,1]
	v_lshl_add_u64 v[202:203], v[202:203], 2, s[90:91]
	global_store_dwordx4 v[202:203], v[240:243], off
	v_sub_f32_e32 v203, v249, v218
	v_sub_f32_e32 v202, v248, v218
	v_sub_f32_e32 v221, v251, v218
	v_sub_f32_e32 v220, v250, v218
	v_pk_mul_f32 v[202:203], v[218:219], v[202:203] op_sel:[1,0]
	v_pk_mul_f32 v[220:221], v[218:219], v[220:221] op_sel:[1,0]
	v_pk_fma_f32 v[202:203], v[214:215], v[202:203], v[52:53]
	v_pk_fma_f32 v[220:221], v[212:213], v[220:221], v[54:55]
	v_pk_fma_f32 v[240:241], v[132:133], s[78:79], v[202:203] op_sel_hi:[1,0,1]
	v_add_u32_e32 v202, 0x8080, v194
	v_mov_b32_e32 v203, v159
	v_sub_f32_e32 v153, v153, v218
	v_sub_f32_e32 v152, v152, v218
	v_sub_f32_e32 v155, v155, v218
	v_sub_f32_e32 v154, v154, v218
	v_pk_fma_f32 v[242:243], v[134:135], s[78:79], v[220:221] op_sel_hi:[1,0,1]
	v_lshl_add_u64 v[202:203], v[202:203], 2, s[90:91]
	v_pk_mul_f32 v[154:155], v[218:219], v[154:155] op_sel:[1,0]
	v_pk_mul_f32 v[152:153], v[218:219], v[152:153] op_sel:[1,0]
	global_store_dwordx4 v[202:203], v[240:243], off
	v_pk_fma_f32 v[152:153], v[208:209], v[152:153], v[48:49]
	v_pk_fma_f32 v[154:155], v[206:207], v[154:155], v[50:51]
	v_add_u32_e32 v202, 0x8090, v194
	v_mov_b32_e32 v203, v159
	v_sub_f32_e32 v149, v149, v216
	v_sub_f32_e32 v148, v148, v216
	v_sub_f32_e32 v151, v151, v216
	v_sub_f32_e32 v150, v150, v216
	v_pk_fma_f32 v[154:155], v[130:131], s[78:79], v[154:155] op_sel_hi:[1,0,1]
	v_pk_fma_f32 v[152:153], v[128:129], s[78:79], v[152:153] op_sel_hi:[1,0,1]
	v_lshl_add_u64 v[202:203], v[202:203], 2, s[90:91]
	v_pk_mul_f32 v[150:151], v[216:217], v[150:151] op_sel:[1,0]
	v_pk_mul_f32 v[148:149], v[216:217], v[148:149] op_sel:[1,0]
	global_store_dwordx4 v[202:203], v[152:155], off
	v_pk_fma_f32 v[148:149], v[214:215], v[148:149], v[44:45]
	v_pk_fma_f32 v[150:151], v[212:213], v[150:151], v[46:47]
	v_add_u32_e32 v152, 0x10080, v194
	v_mov_b32_e32 v153, v159
	v_sub_f32_e32 v145, v145, v216
	v_sub_f32_e32 v144, v144, v216
	v_sub_f32_e32 v147, v147, v216
	v_sub_f32_e32 v146, v146, v216
	v_pk_fma_f32 v[150:151], v[134:135], s[78:79], v[150:151] op_sel_hi:[1,0,1]
	v_pk_fma_f32 v[148:149], v[132:133], s[78:79], v[148:149] op_sel_hi:[1,0,1]
	v_lshl_add_u64 v[152:153], v[152:153], 2, s[90:91]
	v_pk_mul_f32 v[146:147], v[216:217], v[146:147] op_sel:[1,0]
	v_pk_mul_f32 v[144:145], v[216:217], v[144:145] op_sel:[1,0]
	global_store_dwordx4 v[152:153], v[148:151], off
	v_pk_fma_f32 v[144:145], v[208:209], v[144:145], v[40:41]
	v_pk_fma_f32 v[146:147], v[206:207], v[146:147], v[42:43]
;     template <bool LN, int BJ, int LO, int HI> DI void batch(const f32x4 (&acc)[2][2][4][2], unsigned row0, unsigned col0, const f32x4 (&gv)[2], const f32x4 (&bv)[2]) const {
;         f32x4 r[HI - LO]; float mean[(HI - LO) / 2], rstd[(HI - LO) / 2];
; #pragma unroll
;         for (int i = LO; i < HI; ++i) { const int ai = i >> 3, m = (i >> 1) & 3, n = i & 1; const unsigned row = row0 + ai * HALF + m * 16;
;             if (n == 0) { mean[(i - LO) >> 1] = 0.f; rstd[(i - LO) >> 1] = 1.f;
;                 if (LN) { const float2 st = *(const float2*)(stats + row * 2u); mean[(i - LO) >> 1] = st.x; rstd[(i - LO) >> 1] = st.y; } }
;             r[i - LO] = *(const f32x4*)(src + (row * (unsigned)DM + col0 + BJ * HALF + n * 16)); }
; #pragma unroll
;         for (int i = LO; i < HI; ++i) { const int ai = i >> 3, m = (i >> 1) & 3, n = i & 1; const unsigned row = row0 + ai * HALF + m * 16;
;             *(f32x4*)(Y + (row * (unsigned)DM + col0 + BJ * HALF + n * 16)) = acc[ai][BJ][m][n] + ((r[i - LO] - mean[(i - LO) >> 1]) * rstd[(i - LO) >> 1]) * gv[n] + bv[n]; }
	v_add_u32_e32 v148, 0x10090, v194
	v_mov_b32_e32 v149, v159
	v_sub_f32_e32 v141, v141, v200
	v_sub_f32_e32 v140, v140, v200
	v_sub_f32_e32 v143, v143, v200
	v_sub_f32_e32 v142, v142, v200
	v_pk_fma_f32 v[146:147], v[130:131], s[78:79], v[146:147] op_sel_hi:[1,0,1]
	v_pk_fma_f32 v[144:145], v[128:129], s[78:79], v[144:145] op_sel_hi:[1,0,1]
	v_lshl_add_u64 v[148:149], v[148:149], 2, s[90:91]
	v_pk_mul_f32 v[142:143], v[200:201], v[142:143] op_sel:[1,0]
	v_pk_mul_f32 v[140:141], v[200:201], v[140:141] op_sel:[1,0]
	global_store_dwordx4 v[148:149], v[144:147], off
	v_pk_fma_f32 v[140:141], v[214:215], v[140:141], v[36:37]
	v_pk_fma_f32 v[142:143], v[212:213], v[142:143], v[38:39]
	v_add_u32_e32 v144, 0x18080, v194
	v_mov_b32_e32 v145, v159
	v_sub_f32_e32 v137, v137, v200
	v_sub_f32_e32 v136, v136, v200
	v_sub_f32_e32 v139, v139, v200
	v_sub_f32_e32 v138, v138, v200
	v_pk_fma_f32 v[142:143], v[134:135], s[78:79], v[142:143] op_sel_hi:[1,0,1]
	v_pk_fma_f32 v[140:141], v[132:133], s[78:79], v[140:141] op_sel_hi:[1,0,1]
	v_lshl_add_u64 v[144:145], v[144:145], 2, s[90:91]
	v_pk_mul_f32 v[138:139], v[200:201], v[138:139] op_sel:[1,0]
	v_pk_mul_f32 v[136:137], v[200:201], v[136:137] op_sel:[1,0]
	global_store_dwordx4 v[144:145], v[140:143], off
	v_pk_fma_f32 v[136:137], v[208:209], v[136:137], v[32:33]
	v_pk_fma_f32 v[138:139], v[206:207], v[138:139], v[34:35]
	v_add_u32_e32 v140, 0x18090, v194
	v_mov_b32_e32 v141, v159
	v_pk_fma_f32 v[138:139], v[130:131], s[78:79], v[138:139] op_sel_hi:[1,0,1]
	v_pk_fma_f32 v[136:137], v[128:129], s[78:79], v[136:137] op_sel_hi:[1,0,1]
	v_lshl_add_u64 v[140:141], v[140:141], 2, s[90:91]
	global_store_dwordx4 v[140:141], v[136:139], off
	s_nop 1
	v_add_u32_e32 v136, v233, v230
	v_mov_b32_e32 v137, v159
	v_lshl_add_u64 v[136:137], v[136:137], 2, s[88:89]
	global_load_dwordx2 v[220:221], v[196:197], off
	global_load_dwordx4 v[216:219], v[136:137], off
	v_add_u32_e32 v136, v233, v229
	v_mov_b32_e32 v137, v159
	v_lshl_add_u64 v[136:137], v[136:137], 2, s[88:89]
	global_load_dwordx4 v[240:243], v[136:137], off
	global_load_dwordx2 v[200:201], v[198:199], off
	v_add_u32_e32 v136, v234, v230
	v_mov_b32_e32 v137, v159
	v_lshl_add_u64 v[136:137], v[136:137], 2, s[88:89]
	global_load_dwordx4 v[244:247], v[136:137], off
	v_add_u32_e32 v136, v234, v229
	v_mov_b32_e32 v137, v159
	v_lshl_add_u64 v[136:137], v[136:137], 2, s[88:89]
	global_load_dwordx4 v[152:155], v[136:137], off
	global_load_dwordx2 v[198:199], v[204:205], off
	v_add_u32_e32 v136, v237, v230
	v_mov_b32_e32 v137, v159
	v_lshl_add_u64 v[136:137], v[136:137], 2, s[88:89]
	global_load_dwordx4 v[148:151], v[136:137], off
	v_add_u32_e32 v136, v237, v229
	v_mov_b32_e32 v137, v159
	v_lshl_add_u64 v[136:137], v[136:137], 2, s[88:89]
	global_load_dwordx4 v[144:147], v[136:137], off
	global_load_dwordx2 v[196:197], v[210:211], off
	v_add_u32_e32 v136, v238, v230
	v_mov_b32_e32 v137, v159
	v_lshl_add_u64 v[136:137], v[136:137], 2, s[88:89]
	global_load_dwordx4 v[140:143], v[136:137], off
	v_add_u32_e32 v136, v238, v229
	v_mov_b32_e32 v137, v159
	v_lshl_add_u64 v[136:137], v[136:137], 2, s[88:89]
	global_load_dwordx4 v[136:139], v[136:137], off
	v_add_u32_e32 v210, 0x40080, v194
	v_mov_b32_e32 v211, v159
	v_lshl_add_u64 v[210:211], v[210:211], 2, s[90:91]
	s_waitcnt vmcnt(0)
;     template <bool LN, int BJ, int LO, int HI> DI void batch(const f32x4 (&acc)[2][2][4][2], unsigned row0, unsigned col0, const f32x4 (&gv)[2], const f32x4 (&bv)[2]) const {
;         f32x4 r[HI - LO]; float mean[(HI - LO) / 2], rstd[(HI - LO) / 2];
; #pragma unroll
;         for (int i = LO; i < HI; ++i) { const int ai = i >> 3, m = (i >> 1) & 3, n = i & 1; const unsigned row = row0 + ai * HALF + m * 16;
;             if (n == 0) { mean[(i - LO) >> 1] = 0.f; rstd[(i - LO) >> 1] = 1.f;
;                 if (LN) { const float2 st = *(const float2*)(stats + row * 2u); mean[(i - LO) >> 1] = st.x; rstd[(i - LO) >> 1] = st.y; } }
;             r[i - LO] = *(const f32x4*)(src + (row * (unsigned)DM + col0 + BJ * HALF + n * 16)); }
; #pragma unroll
;         for (int i = LO; i < HI; ++i) { const int ai = i >> 3, m = (i >> 1) & 3, n = i & 1; const unsigned row = row0 + ai * HALF + m * 16;
;             *(f32x4*)(Y + (row * (unsigned)DM + col0 + BJ * HALF + n * 16)) = acc[ai][BJ][m][n] + ((r[i - LO] - mean[(i - LO) >> 1]) * rstd[(i - LO) >> 1]) * gv[n] + bv[n]; }
	v_sub_f32_e32 v203, v217, v220
	v_sub_f32_e32 v202, v216, v220
	v_sub_f32_e32 v205, v219, v220
	v_sub_f32_e32 v204, v218, v220
	v_pk_mul_f32 v[204:205], v[220:221], v[204:205] op_sel:[1,0]
	v_pk_mul_f32 v[202:203], v[220:221], v[202:203] op_sel:[1,0]
	v_pk_fma_f32 v[204:205], v[212:213], v[204:205], v[30:31]
	v_pk_fma_f32 v[202:203], v[214:215], v[202:203], v[28:29]
	v_pk_fma_f32 v[204:205], v[134:135], s[78:79], v[204:205] op_sel_hi:[1,0,1]
	v_pk_fma_f32 v[202:203], v[132:133], s[78:79], v[202:203] op_sel_hi:[1,0,1]
	global_store_dwordx4 v[210:211], v[202:205], off
	v_add_u32_e32 v210, 0x40090, v194
	v_mov_b32_e32 v211, v159
	v_sub_f32_e32 v203, v241, v220
	v_sub_f32_e32 v202, v240, v220
	v_sub_f32_e32 v205, v243, v220
	v_sub_f32_e32 v204, v242, v220
	v_pk_mul_f32 v[204:205], v[220:221], v[204:205] op_sel:[1,0]
	v_pk_mul_f32 v[202:203], v[220:221], v[202:203] op_sel:[1,0]
	v_pk_fma_f32 v[204:205], v[206:207], v[204:205], v[26:27]
	v_pk_fma_f32 v[202:203], v[208:209], v[202:203], v[24:25]
	v_pk_fma_f32 v[204:205], v[130:131], s[78:79], v[204:205] op_sel_hi:[1,0,1]
	v_pk_fma_f32 v[202:203], v[128:129], s[78:79], v[202:203] op_sel_hi:[1,0,1]
	v_lshl_add_u64 v[210:211], v[210:211], 2, s[90:91]
	global_store_dwordx4 v[210:211], v[202:205], off
	v_sub_f32_e32 v149, v149, v198
	v_sub_f32_e32 v148, v148, v198
	v_sub_f32_e32 v203, v245, v200
	v_sub_f32_e32 v202, v244, v200
	v_sub_f32_e32 v141, v141, v196
	v_sub_f32_e32 v140, v140, v196
	v_sub_f32_e32 v205, v247, v200
	v_sub_f32_e32 v204, v246, v200
	v_pk_mul_f32 v[202:203], v[200:201], v[202:203] op_sel:[1,0]
	v_sub_f32_e32 v151, v151, v198
	v_sub_f32_e32 v150, v150, v198
	v_pk_mul_f32 v[148:149], v[198:199], v[148:149] op_sel:[1,0]
	v_sub_f32_e32 v143, v143, v196
	v_sub_f32_e32 v142, v142, v196
	v_pk_mul_f32 v[140:141], v[196:197], v[140:141] op_sel:[1,0]
	v_pk_mul_f32 v[204:205], v[200:201], v[204:205] op_sel:[1,0]
	v_pk_fma_f32 v[202:203], v[214:215], v[202:203], v[20:21]
	v_sub_f32_e32 v153, v153, v200
	v_sub_f32_e32 v152, v152, v200
	v_sub_f32_e32 v155, v155, v200
	v_sub_f32_e32 v154, v154, v200
	v_pk_mul_f32 v[150:151], v[198:199], v[150:151] op_sel:[1,0]
	v_pk_fma_f32 v[148:149], v[214:215], v[148:149], v[12:13]
	v_pk_mul_f32 v[142:143], v[196:197], v[142:143] op_sel:[1,0]
	v_pk_fma_f32 v[140:141], v[214:215], v[140:141], v[4:5]
	v_pk_fma_f32 v[204:205], v[212:213], v[204:205], v[22:23]
	v_pk_fma_f32 v[202:203], v[132:133], s[78:79], v[202:203] op_sel_hi:[1,0,1]
	v_pk_mul_f32 v[154:155], v[200:201], v[154:155] op_sel:[1,0]
	v_pk_mul_f32 v[152:153], v[200:201], v[152:153] op_sel:[1,0]
	v_pk_fma_f32 v[150:151], v[212:213], v[150:151], v[14:15]
	v_pk_fma_f32 v[148:149], v[132:133], s[78:79], v[148:149] op_sel_hi:[1,0,1]
	v_pk_fma_f32 v[142:143], v[212:213], v[142:143], v[6:7]
	v_pk_fma_f32 v[132:133], v[132:133], s[78:79], v[140:141] op_sel_hi:[1,0,1]
	v_add_u32_e32 v140, 0x58080, v194
	v_mov_b32_e32 v141, v159
	v_pk_fma_f32 v[204:205], v[134:135], s[78:79], v[204:205] op_sel_hi:[1,0,1]
	v_pk_fma_f32 v[152:153], v[208:209], v[152:153], v[16:17]
	v_pk_fma_f32 v[154:155], v[206:207], v[154:155], v[18:19]
	v_add_u32_e32 v200, 0x48090, v194
	v_mov_b32_e32 v201, v159
	v_pk_fma_f32 v[150:151], v[134:135], s[78:79], v[150:151] op_sel_hi:[1,0,1]
	v_pk_fma_f32 v[134:135], v[134:135], s[78:79], v[142:143] op_sel_hi:[1,0,1]
	v_lshl_add_u64 v[140:141], v[140:141], 2, s[90:91]
	v_pk_fma_f32 v[154:155], v[130:131], s[78:79], v[154:155] op_sel_hi:[1,0,1]
	v_pk_fma_f32 v[152:153], v[128:129], s[78:79], v[152:153] op_sel_hi:[1,0,1]
	v_lshl_add_u64 v[200:201], v[200:201], 2, s[90:91]
	v_sub_f32_e32 v145, v145, v198
	v_sub_f32_e32 v144, v144, v198
	global_store_dwordx4 v[140:141], v[132:135], off
	global_store_dwordx4 v[200:201], v[152:155], off
	v_sub_f32_e32 v147, v147, v198
	v_sub_f32_e32 v133, v137, v196
	v_sub_f32_e32 v132, v136, v196
	v_add_u32_e32 v152, 0x50080, v194
	v_mov_b32_e32 v153, v159
	v_sub_f32_e32 v146, v146, v198
	v_pk_mul_f32 v[144:145], v[198:199], v[144:145] op_sel:[1,0]
	v_sub_f32_e32 v135, v139, v196
	v_sub_f32_e32 v134, v138, v196
	v_pk_mul_f32 v[132:133], v[196:197], v[132:133] op_sel:[1,0]
	v_lshl_add_u64 v[152:153], v[152:153], 2, s[90:91]
	v_pk_mul_f32 v[146:147], v[198:199], v[146:147] op_sel:[1,0]
	v_pk_fma_f32 v[144:145], v[208:209], v[144:145], v[8:9]
	v_pk_mul_f32 v[134:135], v[196:197], v[134:135] op_sel:[1,0]
	v_pk_fma_f32 v[132:133], v[208:209], v[132:133], v[0:1]
	v_add_u32_e32 v210, 0x48080, v194
	v_mov_b32_e32 v211, v159
	global_store_dwordx4 v[152:153], v[148:151], off
	v_pk_fma_f32 v[146:147], v[206:207], v[146:147], v[10:11]
	v_pk_fma_f32 v[144:145], v[128:129], s[78:79], v[144:145] op_sel_hi:[1,0,1]
	v_add_u32_e32 v148, 0x50090, v194
	v_mov_b32_e32 v149, v159
	v_pk_fma_f32 v[134:135], v[206:207], v[134:135], v[2:3]
	v_pk_fma_f32 v[128:129], v[128:129], s[78:79], v[132:133] op_sel_hi:[1,0,1]
	v_add_u32_e32 v132, 0x58090, v194
	v_mov_b32_e32 v133, v159
	v_lshl_add_u64 v[210:211], v[210:211], 2, s[90:91]
	v_pk_fma_f32 v[146:147], v[130:131], s[78:79], v[146:147] op_sel_hi:[1,0,1]
	v_lshl_add_u64 v[148:149], v[148:149], 2, s[90:91]
	v_pk_fma_f32 v[130:131], v[130:131], s[78:79], v[134:135] op_sel_hi:[1,0,1]
	v_lshl_add_u64 v[132:133], v[132:133], 2, s[90:91]
	global_store_dwordx4 v[210:211], v[202:205], off
	global_store_dwordx4 v[148:149], v[144:147], off
	global_store_dwordx4 v[132:133], v[128:131], off
	s_mov_b64 s[24:25], 0
	s_branch .LBB0_324
